# v44 = v43 + attention address/pk-sub trimming + work-queue ticket prefetch + cvt_pk peephole and dead-chain removal in prep/S phases (stack of individually neutral edits)
# baseline (speedup 1.0000x reference)
.LBB0_423:
	v_add_u32_e32 v4, s25, v135
	v_mul_hi_i32 v2, v4, s64
	v_lshrrev_b32_e32 v3, 31, v2
	v_ashrrev_i32_e32 v2, 3, v2
	v_add_u32_e32 v5, v2, v3
	v_mad_u64_u32 v[20:21], s[0:1], v5, s66, v[0:1]
	v_add_u32_e32 v6, s18, v5
	v_mov_b64_e32 v[2:3], s[52:53]
	v_add_u32_e32 v8, s27, v5
	v_mad_i64_i32 v[6:7], s[0:1], v6, s34, v[2:3]
	v_ashrrev_i32_e32 v21, 31, v20
	v_mad_u64_u32 v[18:19], s[0:1], v5, s65, v[4:5]
	v_lshl_add_u64 v[6:7], v[20:21], 1, v[6:7]
	v_cmp_lt_i32_e32 vcc, s12, v8
	v_lshl_add_u64 v[14:15], v[6:7], 0, s[22:23]
	v_add_co_u32_e64 v6, s[0:1], s67, v6
	v_cndmask_b32_e64 v11, 0, -1, vcc
	v_cndmask_b32_e32 v10, 0, v132, vcc
	v_cmp_gt_i32_e64 s[6:7], s24, v8
	v_addc_co_u32_e64 v7, s[0:1], 0, v7, s[0:1]
	v_lshl_add_u64 v[10:11], v[14:15], 0, v[10:11]
	global_load_dwordx4 v[6:9], v[6:7], off offset:1792
	v_cndmask_b32_e64 v64, 0, v133, s[6:7]
	global_load_dwordx4 v[10:13], v[10:11], off
	v_lshl_add_u64 v[14:15], v[14:15], 0, v[64:65]
	global_load_dwordx4 v[14:17], v[14:15], off
	v_lshlrev_b64 v[208:209], 2, v[20:21]
	v_lshl_add_u64 v[210:211], s[10:11], 0, v[208:209]
	v_lshl_add_u64 v[212:213], s[8:9], 0, v[208:209]
	global_load_dwordx4 v[216:219], v[210:211], off offset:3072
	global_load_dwordx4 v[220:223], v[212:213], off offset:3072
	global_load_dwordx4 v[224:227], v[210:211], off offset:3088
	global_load_dwordx4 v[228:231], v[212:213], off offset:3088
	v_cmp_gt_i32_e64 s[4:5], 32, v18
	v_cmp_gt_i32_e64 s[0:1], 16, v18
	v_lshl_add_u32 v5, v5, 4, v1
	v_add_u32_e32 v4, 0x100, v4
	s_addk_i32 s25, 0x200
	s_cmpk_eq_i32 s25, 0x600
	s_waitcnt vmcnt(0) lgkmcnt(0)
	v_lshlrev_b32_e32 v31, 16, v7
	v_and_b32_e32 v7, 0xffff0000, v7
	v_lshlrev_b32_e32 v26, 16, v12
	v_and_b32_e32 v27, 0xffff0000, v12
	v_lshlrev_b32_e32 v29, 16, v13
	v_and_b32_e32 v30, 0xffff0000, v13
	v_lshlrev_b64 v[12:13], 2, v[20:21]
	v_and_b32_e32 v19, 0xffff0000, v10
	v_lshlrev_b32_e32 v25, 16, v11
	v_and_b32_e32 v11, 0xffff0000, v11
	v_lshl_add_u64 v[20:21], s[10:11], 0, v[12:13]
	v_lshlrev_b32_e32 v10, 16, v10
	v_lshlrev_b32_e32 v32, 16, v14
	v_lshlrev_b32_e32 v33, 16, v15
	v_and_b32_e32 v36, 0xffff0000, v15
	v_and_b32_e32 v37, 0xffff0000, v14
	v_lshlrev_b32_e32 v38, 16, v16
	v_lshlrev_b32_e32 v39, 16, v17
	v_and_b32_e32 v40, 0xffff0000, v17
	v_and_b32_e32 v41, 0xffff0000, v16
	v_lshl_add_u64 v[22:23], s[8:9], 0, v[12:13]
	v_cndmask_b32_e32 v18, 0, v10, vcc
	v_cndmask_b32_e32 v24, 0, v19, vcc
	v_cndmask_b32_e32 v19, 0, v25, vcc
	v_cndmask_b32_e32 v25, 0, v11, vcc
	v_cndmask_b32_e32 v28, 0, v27, vcc
	v_cndmask_b32_e32 v27, 0, v29, vcc
	v_cndmask_b32_e32 v29, 0, v30, vcc
	v_lshlrev_b32_e32 v30, 16, v6
	v_cndmask_b32_e64 v33, 0, v33, s[6:7]
	v_cndmask_b32_e64 v32, 0, v32, s[6:7]
	v_pk_add_f32 v[18:19], v[18:19], v[30:31] neg_lo:[0,1] neg_hi:[0,1]
	v_and_b32_e32 v6, 0xffff0000, v6
	v_pk_add_f32 v[24:25], v[24:25], v[6:7] neg_lo:[0,1] neg_hi:[0,1]
	v_cndmask_b32_e32 v26, 0, v26, vcc
	s_waitcnt vmcnt(0) lgkmcnt(0)
	v_mov_b64_e32 v[10:11], v[216:217]
	v_mov_b64_e32 v[12:13], v[218:219]
	v_mov_b64_e32 v[14:15], v[220:221]
	v_mov_b64_e32 v[16:17], v[222:223]
	v_mov_b32_e32 v34, v10
	v_mov_b32_e32 v35, v12
	v_pk_fma_f32 v[18:19], v[34:35], v[18:19], v[30:31]
	v_pk_add_f32 v[30:31], v[32:33], v[30:31] neg_lo:[0,1] neg_hi:[0,1]
	v_mov_b32_e32 v32, v14
	v_mov_b32_e32 v33, v16
	v_pk_fma_f32 v[18:19], v[30:31], v[32:33], v[18:19]
	v_cndmask_b32_e64 v31, 0, v36, s[6:7]
	v_cndmask_b32_e64 v30, 0, v37, s[6:7]
	v_mov_b32_e32 v12, v11
	v_pk_fma_f32 v[12:13], v[12:13], v[24:25], v[6:7]
	v_pk_add_f32 v[6:7], v[30:31], v[6:7] neg_lo:[0,1] neg_hi:[0,1]
	v_mov_b32_e32 v16, v15
	v_pk_fma_f32 v[6:7], v[6:7], v[16:17], v[12:13]
	v_add_f32_e32 v10, v18, v18
	v_add_f32_e32 v11, v6, v6
	v_cndmask_b32_e64 v11, v11, v6, s[0:1]
	v_mul_f32_e32 v11, 0xbfb8aa3b, v11
	v_exp_f32_e32 v12, v11
	v_add_f32_e32 v11, v19, v19
	v_cndmask_b32_e64 v10, v10, v18, s[0:1]
	v_cndmask_b32_e64 v11, v11, v19, s[0:1]
	v_mul_f32_e32 v10, 0xbfb8aa3b, v10
	v_mul_f32_e32 v11, 0xbfb8aa3b, v11
	v_exp_f32_e32 v10, v10
	v_exp_f32_e32 v11, v11
	s_nop 0
	v_pk_add_f32 v[10:11], v[10:11], 1.0 op_sel_hi:[1,0]
	s_nop 0
	v_div_scale_f32 v13, s[78:79], v11, v11, 1.0
	v_rcp_f32_e32 v14, v13
	s_nop 0
	v_fma_f32 v15, -v13, v14, 1.0
	v_fmac_f32_e32 v14, v15, v14
	v_div_scale_f32 v15, vcc, 1.0, v11, 1.0
	v_mul_f32_e32 v16, v15, v14
	v_fma_f32 v17, -v13, v16, v15
	v_fmac_f32_e32 v16, v17, v14
	v_fma_f32 v13, -v13, v16, v15
	v_div_fmas_f32 v13, v13, v14, v16
	v_div_fixup_f32 v11, v13, v11, 1.0
	v_div_scale_f32 v13, s[78:79], v10, v10, 1.0
	v_rcp_f32_e32 v14, v13
	s_nop 0
	v_fma_f32 v15, -v13, v14, 1.0
	v_fmac_f32_e32 v14, v15, v14
	v_div_scale_f32 v15, vcc, 1.0, v10, 1.0
	v_mul_f32_e32 v16, v15, v14
	v_fma_f32 v17, -v13, v16, v15
	v_fmac_f32_e32 v16, v17, v14
	v_fma_f32 v13, -v13, v16, v15
	v_div_fmas_f32 v13, v13, v14, v16
	v_div_fixup_f32 v10, v13, v10, 1.0
	v_pk_fma_f32 v[14:15], v[10:11], 2.0, -1.0 op_sel_hi:[1,0,0]
	v_and_b32_e32 v17, 0xffff0000, v9
	v_cndmask_b32_e64 v13, v18, v14, s[4:5]
	v_cndmask_b32_e64 v25, v13, v10, s[0:1]
	v_add_f32_e32 v10, v7, v7
	v_cndmask_b32_e64 v10, v10, v7, s[0:1]
	v_mul_f32_e32 v10, 0xbfb8aa3b, v10
	v_exp_f32_e32 v13, v10
	v_cndmask_b32_e64 v14, v19, v15, s[4:5]
	v_cndmask_b32_e64 v24, v14, v11, s[0:1]
	v_cndmask_b32_e64 v19, 0, v39, s[6:7]
	v_pk_add_f32 v[10:11], v[12:13], 1.0 op_sel_hi:[1,0]
	v_cndmask_b32_e64 v18, 0, v38, s[6:7]
	v_div_scale_f32 v12, s[78:79], v11, v11, 1.0
	v_rcp_f32_e32 v13, v12
	s_nop 0
	v_fma_f32 v14, -v12, v13, 1.0
	v_fmac_f32_e32 v13, v14, v13
	v_div_scale_f32 v14, vcc, 1.0, v11, 1.0
	v_mul_f32_e32 v15, v14, v13
	v_fma_f32 v16, -v12, v15, v14
	v_fmac_f32_e32 v15, v16, v13
	v_fma_f32 v12, -v12, v15, v14
	v_div_fmas_f32 v12, v12, v13, v15
	v_div_fixup_f32 v11, v12, v11, 1.0
	v_div_scale_f32 v12, s[78:79], v10, v10, 1.0
	v_rcp_f32_e32 v13, v12
	s_nop 0
	v_fma_f32 v14, -v12, v13, 1.0
	v_fmac_f32_e32 v13, v14, v13
	v_div_scale_f32 v14, vcc, 1.0, v10, 1.0
	v_mul_f32_e32 v15, v14, v13
	v_fma_f32 v16, -v12, v15, v14
	v_fmac_f32_e32 v15, v16, v13
	v_fma_f32 v12, -v12, v15, v14
	v_div_fmas_f32 v12, v12, v13, v15
	v_div_fixup_f32 v10, v12, v10, 1.0
	v_pk_fma_f32 v[12:13], v[10:11], 2.0, -1.0 op_sel_hi:[1,0,0]
	v_lshlrev_b32_e32 v15, 16, v9
	v_cndmask_b32_e64 v7, v7, v13, s[4:5]
	v_cndmask_b32_e64 v6, v6, v12, s[4:5]
	v_cndmask_b32_e64 v30, v6, v10, s[0:1]
	v_cndmask_b32_e64 v31, v7, v11, s[0:1]
	v_lshlrev_b32_e32 v14, 16, v8
	v_and_b32_e32 v16, 0xffff0000, v8
	v_pk_add_f32 v[20:21], v[26:27], v[14:15] neg_lo:[0,1] neg_hi:[0,1]
	s_waitcnt vmcnt(0) lgkmcnt(0)
	v_mov_b64_e32 v[6:7], v[224:225]
	v_mov_b64_e32 v[8:9], v[226:227]
	v_mov_b64_e32 v[10:11], v[228:229]
	v_mov_b64_e32 v[12:13], v[230:231]
	v_mov_b32_e32 v22, v6
	v_mov_b32_e32 v23, v8
	v_pk_fma_f32 v[20:21], v[20:21], v[22:23], v[14:15]
	v_pk_add_f32 v[14:15], v[18:19], v[14:15] neg_lo:[0,1] neg_hi:[0,1]
	v_mov_b32_e32 v18, v10
	v_mov_b32_e32 v19, v12
	v_pk_fma_f32 v[14:15], v[14:15], v[18:19], v[20:21]
	v_cndmask_b32_e64 v19, 0, v40, s[6:7]
	v_cndmask_b32_e64 v18, 0, v41, s[6:7]
	v_pk_add_f32 v[20:21], v[28:29], v[16:17] neg_lo:[0,1] neg_hi:[0,1]
	v_mov_b32_e32 v8, v7
	v_pk_fma_f32 v[8:9], v[20:21], v[8:9], v[16:17]
	v_pk_add_f32 v[16:17], v[18:19], v[16:17] neg_lo:[0,1] neg_hi:[0,1]
	v_mov_b32_e32 v12, v11
	v_pk_fma_f32 v[8:9], v[16:17], v[12:13], v[8:9]
	v_add_f32_e32 v6, v14, v14
	v_add_f32_e32 v7, v8, v8
	v_cndmask_b32_e64 v7, v7, v8, s[0:1]
	v_mul_f32_e32 v7, 0xbfb8aa3b, v7
	v_exp_f32_e32 v10, v7
	v_add_f32_e32 v7, v15, v15
	v_cndmask_b32_e64 v6, v6, v14, s[0:1]
	v_cndmask_b32_e64 v7, v7, v15, s[0:1]
	v_mul_f32_e32 v6, 0xbfb8aa3b, v6
	v_mul_f32_e32 v7, 0xbfb8aa3b, v7
	v_exp_f32_e32 v6, v6
	v_exp_f32_e32 v7, v7
	s_nop 0
	v_pk_add_f32 v[6:7], v[6:7], 1.0 op_sel_hi:[1,0]
	s_nop 0
	v_div_scale_f32 v11, s[6:7], v7, v7, 1.0
	v_rcp_f32_e32 v12, v11
	s_nop 0
	v_fma_f32 v13, -v11, v12, 1.0
	v_fmac_f32_e32 v12, v13, v12
	v_div_scale_f32 v13, vcc, 1.0, v7, 1.0
	v_mul_f32_e32 v16, v13, v12
	v_fma_f32 v17, -v11, v16, v13
	v_fmac_f32_e32 v16, v17, v12
	v_fma_f32 v11, -v11, v16, v13
	v_div_fmas_f32 v11, v11, v12, v16
	v_div_fixup_f32 v7, v11, v7, 1.0
	v_div_scale_f32 v11, s[6:7], v6, v6, 1.0
	v_rcp_f32_e32 v12, v11
	s_nop 0
	v_fma_f32 v13, -v11, v12, 1.0
	v_fmac_f32_e32 v12, v13, v12
	v_div_scale_f32 v13, vcc, 1.0, v6, 1.0
	v_mul_f32_e32 v16, v13, v12
	v_fma_f32 v17, -v11, v16, v13
	v_fmac_f32_e32 v16, v17, v12
	v_fma_f32 v11, -v11, v16, v13
	v_div_fmas_f32 v11, v11, v12, v16
	v_div_fixup_f32 v6, v11, v6, 1.0
	v_pk_fma_f32 v[12:13], v[6:7], 2.0, -1.0 op_sel_hi:[1,0,0]
	s_nop 0
	v_cndmask_b32_e64 v11, v14, v12, s[4:5]
	v_cndmask_b32_e64 v12, v15, v13, s[4:5]
	v_cndmask_b32_e64 v13, v11, v6, s[0:1]
	v_add_f32_e32 v6, v9, v9
	v_cndmask_b32_e64 v6, v6, v9, s[0:1]
	v_mul_f32_e32 v6, 0xbfb8aa3b, v6
	v_exp_f32_e32 v11, v6
	v_cndmask_b32_e64 v12, v12, v7, s[0:1]
	v_pk_add_f32 v[6:7], v[10:11], 1.0 op_sel_hi:[1,0]
	s_nop 0
	v_div_scale_f32 v10, s[6:7], v7, v7, 1.0
	v_rcp_f32_e32 v11, v10
	s_nop 0
	v_fma_f32 v14, -v10, v11, 1.0
	v_fmac_f32_e32 v11, v14, v11
	v_div_scale_f32 v14, vcc, 1.0, v7, 1.0
	v_mul_f32_e32 v15, v14, v11
	v_fma_f32 v16, -v10, v15, v14
	v_fmac_f32_e32 v15, v16, v11
	v_fma_f32 v10, -v10, v15, v14
	v_div_fmas_f32 v10, v10, v11, v15
	v_div_fixup_f32 v7, v10, v7, 1.0
	v_div_scale_f32 v10, s[6:7], v6, v6, 1.0
	v_rcp_f32_e32 v11, v10
	s_nop 0
	v_fma_f32 v14, -v10, v11, 1.0
	v_fmac_f32_e32 v11, v14, v11
	v_div_scale_f32 v14, vcc, 1.0, v6, 1.0
	v_mul_f32_e32 v15, v14, v11
	v_fma_f32 v16, -v10, v15, v14
	v_fmac_f32_e32 v15, v16, v11
	v_fma_f32 v10, -v10, v15, v14
	v_div_fmas_f32 v10, v10, v11, v15
	v_div_fixup_f32 v6, v10, v6, 1.0
	v_pk_fma_f32 v[10:11], v[6:7], 2.0, -1.0 op_sel_hi:[1,0,0]
	v_bfe_u32 v14, v13, 16, 1
	v_cndmask_b32_e64 v9, v9, v11, s[4:5]
	v_cndmask_b32_e64 v8, v8, v10, s[4:5]
	v_cndmask_b32_e64 v6, v8, v6, s[0:1]
	v_cndmask_b32_e64 v7, v9, v7, s[0:1]
	v_cvt_pk_bf16_f32 v208, v12, v7
	v_bfe_u32 v9, v6, 16, 1
	v_add3_u32 v6, v6, v9, s58
	v_add3_u32 v13, v13, v14, s58
	v_lshrrev_b32_e32 v8, 16, v13
	v_mov_b32_e32 v9, v208
	v_and_or_b32 v8, v6, s54, v8
	v_cvt_pk_bf16_f32 v7, v24, v31
	v_cvt_pk_bf16_f32 v6, v25, v30
	ds_write_b128 v5, v[6:9]
	v_mul_hi_i32 v5, v4, s64
	v_lshrrev_b32_e32 v6, 31, v5
	v_ashrrev_i32_e32 v5, 3, v5
	v_add_u32_e32 v6, v5, v6
	v_mad_u64_u32 v[4:5], s[0:1], v6, s65, v[4:5]
	v_mul_lo_u32 v5, v6, s66
	s_movk_i32 s0, 0x800
	v_add3_u32 v20, v0, v5, s0
	v_add_u32_e32 v7, s18, v6
	v_mad_i64_i32 v[2:3], s[0:1], v7, s34, v[2:3]
	v_ashrrev_i32_e32 v21, 31, v20
	v_lshl_add_u64 v[2:3], v[20:21], 1, v[2:3]
	v_add_u32_e32 v5, s27, v6
	v_lshl_add_u64 v[16:17], v[2:3], 0, s[22:23]
	v_add_co_u32_e64 v2, s[0:1], s67, v2
	v_cmp_lt_i32_e32 vcc, s12, v5
	s_nop 0
	v_addc_co_u32_e64 v3, s[0:1], 0, v3, s[0:1]
	v_cmp_gt_i32_e64 s[6:7], s24, v5
	global_load_dwordx4 v[8:11], v[2:3], off offset:1792
	v_cndmask_b32_e64 v3, 0, -1, vcc
	v_cndmask_b32_e32 v2, 0, v132, vcc
	v_lshl_add_u64 v[2:3], v[16:17], 0, v[2:3]
	v_cndmask_b32_e64 v64, 0, v133, s[6:7]
	global_load_dwordx4 v[12:15], v[2:3], off
	v_lshl_add_u64 v[2:3], v[16:17], 0, v[64:65]
	global_load_dwordx4 v[16:19], v[2:3], off
	v_lshlrev_b64 v[208:209], 2, v[20:21]
	v_lshl_add_u64 v[210:211], s[10:11], 0, v[208:209]
	v_lshl_add_u64 v[212:213], s[8:9], 0, v[208:209]
	global_load_dwordx4 v[216:219], v[210:211], off offset:3072
	global_load_dwordx4 v[220:223], v[212:213], off offset:3072
	global_load_dwordx4 v[224:227], v[210:211], off offset:3088
	global_load_dwordx4 v[228:231], v[212:213], off offset:3088
	v_lshlrev_b64 v[2:3], 2, v[20:21]
	v_cmp_gt_i32_e64 s[4:5], 32, v4
	v_cmp_gt_i32_e64 s[0:1], 16, v4
	v_lshl_add_u32 v6, v6, 4, v1
	v_add_u32_e32 v1, 0x2000, v1
	v_add_u32_e32 v0, 0x1000, v0
	s_waitcnt vmcnt(0) lgkmcnt(0)
	v_lshlrev_b32_e32 v29, 16, v9
	v_lshlrev_b32_e32 v28, 16, v8
	v_and_b32_e32 v9, 0xffff0000, v9
	v_and_b32_e32 v8, 0xffff0000, v8
	v_and_b32_e32 v5, 0xffff0000, v12
	v_lshlrev_b32_e32 v7, 16, v13
	v_and_b32_e32 v13, 0xffff0000, v13
	v_lshlrev_b32_e32 v24, 16, v14
	v_and_b32_e32 v14, 0xffff0000, v14
	v_lshlrev_b32_e32 v25, 16, v15
	v_and_b32_e32 v15, 0xffff0000, v15
	v_lshlrev_b32_e32 v30, 16, v16
	v_lshlrev_b32_e32 v31, 16, v17
	v_and_b32_e32 v34, 0xffff0000, v17
	v_and_b32_e32 v35, 0xffff0000, v16
	v_lshlrev_b32_e32 v36, 16, v18
	v_lshlrev_b32_e32 v37, 16, v19
	v_and_b32_e32 v38, 0xffff0000, v19
	v_and_b32_e32 v39, 0xffff0000, v18
	v_lshl_add_u64 v[16:17], s[10:11], 0, v[2:3]
	v_lshl_add_u64 v[18:19], s[8:9], 0, v[2:3]
	v_lshlrev_b32_e32 v2, 16, v12
	v_cndmask_b32_e32 v20, 0, v2, vcc
	v_cndmask_b32_e32 v22, 0, v5, vcc
	v_cndmask_b32_e32 v23, 0, v13, vcc
	v_cndmask_b32_e32 v26, 0, v14, vcc
	v_cndmask_b32_e32 v27, 0, v15, vcc
	v_cndmask_b32_e32 v21, 0, v7, vcc
	v_cndmask_b32_e64 v31, 0, v31, s[6:7]
	v_cndmask_b32_e64 v30, 0, v30, s[6:7]
	v_pk_add_f32 v[20:21], v[20:21], v[28:29] neg_lo:[0,1] neg_hi:[0,1]
	v_pk_add_f32 v[22:23], v[22:23], v[8:9] neg_lo:[0,1] neg_hi:[0,1]
	v_cndmask_b32_e32 v24, 0, v24, vcc
	v_cndmask_b32_e32 v25, 0, v25, vcc
	s_waitcnt vmcnt(0) lgkmcnt(0)
	v_mov_b64_e32 v[2:3], v[216:217]
	v_mov_b64_e32 v[4:5], v[218:219]
	v_mov_b64_e32 v[12:13], v[220:221]
	v_mov_b64_e32 v[14:15], v[222:223]
	v_mov_b32_e32 v32, v2
	v_mov_b32_e32 v33, v4
	v_pk_fma_f32 v[20:21], v[32:33], v[20:21], v[28:29]
	v_pk_add_f32 v[28:29], v[30:31], v[28:29] neg_lo:[0,1] neg_hi:[0,1]
	v_mov_b32_e32 v30, v12
	v_mov_b32_e32 v31, v14
	v_pk_fma_f32 v[20:21], v[28:29], v[30:31], v[20:21]
	v_cndmask_b32_e64 v29, 0, v34, s[6:7]
	v_cndmask_b32_e64 v28, 0, v35, s[6:7]
	v_mov_b32_e32 v4, v3
	v_pk_fma_f32 v[4:5], v[4:5], v[22:23], v[8:9]
	v_pk_add_f32 v[8:9], v[28:29], v[8:9] neg_lo:[0,1] neg_hi:[0,1]
	v_mov_b32_e32 v14, v13
	v_pk_fma_f32 v[4:5], v[8:9], v[14:15], v[4:5]
	v_add_f32_e32 v2, v20, v20
	v_add_f32_e32 v3, v4, v4
	v_cndmask_b32_e64 v3, v3, v4, s[0:1]
	v_mul_f32_e32 v3, 0xbfb8aa3b, v3
	v_exp_f32_e32 v8, v3
	v_add_f32_e32 v3, v21, v21
	v_cndmask_b32_e64 v2, v2, v20, s[0:1]
	v_cndmask_b32_e64 v3, v3, v21, s[0:1]
	v_mul_f32_e32 v2, 0xbfb8aa3b, v2
	v_mul_f32_e32 v3, 0xbfb8aa3b, v3
	v_exp_f32_e32 v2, v2
	v_exp_f32_e32 v3, v3
	v_and_b32_e32 v15, 0xffff0000, v11
	v_pk_add_f32 v[2:3], v[2:3], 1.0 op_sel_hi:[1,0]
	s_nop 0
	v_div_scale_f32 v7, s[78:79], v3, v3, 1.0
	v_rcp_f32_e32 v9, v7
	s_nop 0
	v_fma_f32 v12, -v7, v9, 1.0
	v_fmac_f32_e32 v9, v12, v9
	v_div_scale_f32 v12, vcc, 1.0, v3, 1.0
	v_mul_f32_e32 v13, v12, v9
	v_fma_f32 v14, -v7, v13, v12
	v_fmac_f32_e32 v13, v14, v9
	v_fma_f32 v7, -v7, v13, v12
	v_div_fmas_f32 v7, v7, v9, v13
	v_div_fixup_f32 v3, v7, v3, 1.0
	v_div_scale_f32 v7, s[78:79], v2, v2, 1.0
	v_rcp_f32_e32 v9, v7
	s_nop 0
	v_fma_f32 v12, -v7, v9, 1.0
	v_fmac_f32_e32 v9, v12, v9
	v_div_scale_f32 v12, vcc, 1.0, v2, 1.0
	v_mul_f32_e32 v13, v12, v9
	v_fma_f32 v14, -v7, v13, v12
	v_fmac_f32_e32 v13, v14, v9
	v_fma_f32 v7, -v7, v13, v12
	v_div_fmas_f32 v7, v7, v9, v13
	v_div_fixup_f32 v2, v7, v2, 1.0
	v_pk_fma_f32 v[12:13], v[2:3], 2.0, -1.0 op_sel_hi:[1,0,0]
	s_nop 0
	v_cndmask_b32_e64 v7, v20, v12, s[4:5]
	v_cndmask_b32_e64 v7, v7, v2, s[0:1]
	v_add_f32_e32 v2, v5, v5
	v_cndmask_b32_e64 v2, v2, v5, s[0:1]
	v_cndmask_b32_e64 v9, v21, v13, s[4:5]
	v_mul_f32_e32 v2, 0xbfb8aa3b, v2
	v_cndmask_b32_e64 v22, v9, v3, s[0:1]
	v_exp_f32_e32 v9, v2
	s_nop 0
	v_pk_add_f32 v[2:3], v[8:9], 1.0 op_sel_hi:[1,0]
	s_nop 0
	v_div_scale_f32 v8, s[78:79], v3, v3, 1.0
	v_rcp_f32_e32 v9, v8
	s_nop 0
	v_fma_f32 v12, -v8, v9, 1.0
	v_fmac_f32_e32 v9, v12, v9
	v_div_scale_f32 v12, vcc, 1.0, v3, 1.0
	v_mul_f32_e32 v13, v12, v9
	v_fma_f32 v14, -v8, v13, v12
	v_fmac_f32_e32 v13, v14, v9
	v_fma_f32 v8, -v8, v13, v12
	v_div_fmas_f32 v8, v8, v9, v13
	v_div_fixup_f32 v3, v8, v3, 1.0
	v_div_scale_f32 v8, s[78:79], v2, v2, 1.0
	v_rcp_f32_e32 v9, v8
	s_nop 0
	v_fma_f32 v12, -v8, v9, 1.0
	v_fmac_f32_e32 v9, v12, v9
	v_div_scale_f32 v12, vcc, 1.0, v2, 1.0
	v_mul_f32_e32 v13, v12, v9
	v_fma_f32 v14, -v8, v13, v12
	v_fmac_f32_e32 v13, v14, v9
	v_fma_f32 v8, -v8, v13, v12
	v_div_fmas_f32 v8, v8, v9, v13
	v_div_fixup_f32 v2, v8, v2, 1.0
	v_pk_fma_f32 v[8:9], v[2:3], 2.0, -1.0 op_sel_hi:[1,0,0]
	v_lshlrev_b32_e32 v13, 16, v11
	v_cndmask_b32_e64 v5, v5, v9, s[4:5]
	v_cndmask_b32_e64 v4, v4, v8, s[4:5]
	v_cndmask_b32_e64 v23, v4, v2, s[0:1]
	v_cvt_pk_bf16_f32 v209, v7, v23
	v_cndmask_b32_e64 v28, v5, v3, s[0:1]
	v_lshlrev_b32_e32 v12, 16, v10
	v_and_b32_e32 v14, 0xffff0000, v10
	v_cndmask_b32_e64 v17, 0, v37, s[6:7]
	v_cndmask_b32_e64 v16, 0, v36, s[6:7]
	v_pk_add_f32 v[18:19], v[24:25], v[12:13] neg_lo:[0,1] neg_hi:[0,1]
	s_waitcnt vmcnt(0) lgkmcnt(0)
	v_mov_b64_e32 v[2:3], v[224:225]
	v_mov_b64_e32 v[4:5], v[226:227]
	v_mov_b64_e32 v[8:9], v[228:229]
	v_mov_b64_e32 v[10:11], v[230:231]
	v_mov_b32_e32 v20, v2
	v_mov_b32_e32 v21, v4
	v_pk_fma_f32 v[18:19], v[18:19], v[20:21], v[12:13]
	v_pk_add_f32 v[12:13], v[16:17], v[12:13] neg_lo:[0,1] neg_hi:[0,1]
	v_mov_b32_e32 v16, v8
	v_mov_b32_e32 v17, v10
	v_pk_fma_f32 v[12:13], v[12:13], v[16:17], v[18:19]
	v_cndmask_b32_e64 v17, 0, v38, s[6:7]
	v_cndmask_b32_e64 v16, 0, v39, s[6:7]
	v_pk_add_f32 v[18:19], v[26:27], v[14:15] neg_lo:[0,1] neg_hi:[0,1]
	v_mov_b32_e32 v4, v3
	v_pk_fma_f32 v[4:5], v[18:19], v[4:5], v[14:15]
	v_pk_add_f32 v[14:15], v[16:17], v[14:15] neg_lo:[0,1] neg_hi:[0,1]
	v_mov_b32_e32 v10, v9
	v_pk_fma_f32 v[4:5], v[14:15], v[10:11], v[4:5]
	v_add_f32_e32 v2, v12, v12
	v_add_f32_e32 v3, v4, v4
	v_cndmask_b32_e64 v3, v3, v4, s[0:1]
	v_mul_f32_e32 v3, 0xbfb8aa3b, v3
	v_exp_f32_e32 v8, v3
	v_add_f32_e32 v3, v13, v13
	v_cndmask_b32_e64 v2, v2, v12, s[0:1]
	v_cndmask_b32_e64 v3, v3, v13, s[0:1]
	v_mul_f32_e32 v2, 0xbfb8aa3b, v2
	v_mul_f32_e32 v3, 0xbfb8aa3b, v3
	v_exp_f32_e32 v2, v2
	v_exp_f32_e32 v3, v3
	s_nop 0
	v_pk_add_f32 v[2:3], v[2:3], 1.0 op_sel_hi:[1,0]
	s_nop 0
	v_div_scale_f32 v9, s[6:7], v3, v3, 1.0
	v_rcp_f32_e32 v10, v9
	s_nop 0
	v_fma_f32 v11, -v9, v10, 1.0
	v_fmac_f32_e32 v10, v11, v10
	v_div_scale_f32 v11, vcc, 1.0, v3, 1.0
	v_mul_f32_e32 v14, v11, v10
	v_fma_f32 v15, -v9, v14, v11
	v_fmac_f32_e32 v14, v15, v10
	v_fma_f32 v9, -v9, v14, v11
	v_div_fmas_f32 v9, v9, v10, v14
	v_div_fixup_f32 v3, v9, v3, 1.0
	v_div_scale_f32 v9, s[6:7], v2, v2, 1.0
	v_rcp_f32_e32 v10, v9
	s_nop 0
	v_fma_f32 v11, -v9, v10, 1.0
	v_fmac_f32_e32 v10, v11, v10
	v_div_scale_f32 v11, vcc, 1.0, v2, 1.0
	v_mul_f32_e32 v14, v11, v10
	v_fma_f32 v15, -v9, v14, v11
	v_fmac_f32_e32 v14, v15, v10
	v_fma_f32 v9, -v9, v14, v11
	v_div_fmas_f32 v9, v9, v10, v14
	v_div_fixup_f32 v2, v9, v2, 1.0
	v_pk_fma_f32 v[10:11], v[2:3], 2.0, -1.0 op_sel_hi:[1,0,0]
	s_nop 0
	v_cndmask_b32_e64 v9, v12, v10, s[4:5]
	v_cndmask_b32_e64 v10, v13, v11, s[4:5]
	v_cndmask_b32_e64 v11, v9, v2, s[0:1]
	v_add_f32_e32 v2, v5, v5
	v_cndmask_b32_e64 v2, v2, v5, s[0:1]
	v_mul_f32_e32 v2, 0xbfb8aa3b, v2
	v_exp_f32_e32 v9, v2
	v_cndmask_b32_e64 v10, v10, v3, s[0:1]
	v_pk_add_f32 v[2:3], v[8:9], 1.0 op_sel_hi:[1,0]
	s_nop 0
	v_div_scale_f32 v8, s[6:7], v3, v3, 1.0
	v_rcp_f32_e32 v9, v8
	s_nop 0
	v_fma_f32 v12, -v8, v9, 1.0
	v_fmac_f32_e32 v9, v12, v9
	v_div_scale_f32 v12, vcc, 1.0, v3, 1.0
	v_mul_f32_e32 v13, v12, v9
	v_fma_f32 v14, -v8, v13, v12
	v_fmac_f32_e32 v13, v14, v9
	v_fma_f32 v8, -v8, v13, v12
	v_div_fmas_f32 v8, v8, v9, v13
	v_div_fixup_f32 v3, v8, v3, 1.0
	v_div_scale_f32 v8, s[6:7], v2, v2, 1.0
	v_rcp_f32_e32 v9, v8
	s_nop 0
	v_fma_f32 v12, -v8, v9, 1.0
	v_fmac_f32_e32 v9, v12, v9
	v_div_scale_f32 v12, vcc, 1.0, v2, 1.0
	v_mul_f32_e32 v13, v12, v9
	v_fma_f32 v14, -v8, v13, v12
	v_fmac_f32_e32 v13, v14, v9
	v_fma_f32 v8, -v8, v13, v12
	v_div_fmas_f32 v8, v8, v9, v13
	v_div_fixup_f32 v2, v8, v2, 1.0
	v_pk_fma_f32 v[8:9], v[2:3], 2.0, -1.0 op_sel_hi:[1,0,0]
	v_bfe_u32 v12, v11, 16, 1
	v_cndmask_b32_e64 v5, v5, v9, s[4:5]
	v_cndmask_b32_e64 v4, v4, v8, s[4:5]
	v_cndmask_b32_e64 v2, v4, v2, s[0:1]
	v_cndmask_b32_e64 v3, v5, v3, s[0:1]
	v_cvt_pk_bf16_f32 v208, v10, v3
	v_bfe_u32 v5, v2, 16, 1
	v_add3_u32 v2, v2, v5, s58
	v_add3_u32 v11, v11, v12, s58
	v_lshrrev_b32_e32 v4, 16, v11
	v_mov_b32_e32 v5, v208
	v_and_or_b32 v4, v2, s54, v4
	v_cvt_pk_bf16_f32 v3, v22, v28
	v_mov_b32_e32 v2, v209
	ds_write_b128 v6, v[2:5] offset:4096
	s_cbranch_scc0 .LBB0_423
	v_ashrrev_i32_e32 v137, 3, v135
	v_and_b32_e32 v138, -4, v137
	v_add_u32_e32 v16, s27, v138
	v_add_u32_e32 v0, -1, v16
	v_or_b32_e32 v44, 1, v16
	v_and_b32_e32 v126, 31, v135
	v_max_i32_e32 v0, s12, v0
	v_max_i32_e32 v2, s12, v16
	v_max_i32_e32 v10, s12, v44
	v_lshlrev_b32_e32 v34, 4, v126
	v_mov_b32_e32 v35, v65
	s_mulk_i32 s26, 0x900
	v_min_i32_e32 v0, s24, v0
	v_min_i32_e32 v2, s24, v2
	v_min_i32_e32 v10, s24, v10
	v_lshl_add_u64 v[88:89], s[52:53], 0, v[34:35]
	s_mov_b64 s[0:1], 0x7158100
	v_add_u32_e32 v0, s26, v0
	v_add_u32_e32 v2, s26, v2
	v_add_u32_e32 v10, s26, v10
	v_lshl_add_u64 v[8:9], v[88:89], 0, s[0:1]
	v_mul_hi_i32_i24_e32 v29, 0x1240, v0
	v_mul_i32_i24_e32 v28, 0x1240, v0
	v_mul_hi_i32_i24_e32 v47, 0x1240, v2
	v_mul_i32_i24_e32 v46, 0x1240, v2
	v_mul_hi_i32_i24_e32 v49, 0x1240, v10
	v_mul_i32_i24_e32 v48, 0x1240, v10
	v_lshl_add_u64 v[0:1], v[8:9], 0, v[28:29]
	v_lshl_add_u64 v[4:5], v[8:9], 0, v[46:47]
	v_lshl_add_u64 v[10:11], v[8:9], 0, v[48:49]
	v_or_b32_e32 v45, 2, v16
	global_load_dwordx4 v[0:3], v[0:1], off
	s_nop 0
	global_load_dwordx4 v[4:7], v[4:5], off
	v_or_b32_e32 v66, 3, v16
	global_load_dwordx4 v[36:39], v[10:11], off
	v_max_i32_e32 v10, s12, v45
	v_min_i32_e32 v10, s24, v10
	v_add_u32_e32 v10, s26, v10
	v_mul_hi_i32_i24_e32 v51, 0x1240, v10
	v_mul_i32_i24_e32 v50, 0x1240, v10
	v_lshl_add_u64 v[10:11], v[8:9], 0, v[50:51]
	global_load_dwordx4 v[40:43], v[10:11], off
	v_max_i32_e32 v10, s12, v66
	v_min_i32_e32 v10, s24, v10
	v_add_u32_e32 v10, s26, v10
	v_mul_hi_i32_i24_e32 v53, 0x1240, v10
	v_mul_i32_i24_e32 v52, 0x1240, v10
	v_lshl_add_u64 v[10:11], v[8:9], 0, v[52:53]
	v_add_u32_e32 v67, 4, v16
	global_load_dwordx4 v[56:59], v[10:11], off
	v_max_i32_e32 v10, s12, v67
	v_min_i32_e32 v10, s24, v10
	v_add_u32_e32 v10, s26, v10
	v_mul_hi_i32_i24_e32 v55, 0x1240, v10
	v_mul_i32_i24_e32 v54, 0x1240, v10
	v_lshl_add_u64 v[8:9], v[8:9], 0, v[54:55]
	global_load_dwordx4 v[60:63], v[8:9], off
	v_mov_b32_e32 v8, s52
	v_lshlrev_b32_e32 v64, 5, v126
	v_mov_b32_e32 v9, s53
	v_add_co_u32_e32 v32, vcc, s55, v8
	v_lshl_add_u64 v[24:25], s[10:11], 0, v[64:65]
	s_nop 0
	v_addc_co_u32_e32 v33, vcc, 0, v9, vcc
	global_load_dwordx4 v[8:11], v[24:25], off
	v_lshl_add_u64 v[26:27], s[8:9], 0, v[64:65]
	global_load_dwordx2 v[30:31], v[32:33], off offset:464
	global_load_dwordx4 v[12:15], v[26:27], off
	v_cmp_lt_i32_e32 vcc, s12, v16
	v_cmp_ge_i32_e64 s[0:1], s13, v16
	v_cmp_le_i32_e64 s[4:5], s12, v16
	v_cmp_gt_i32_e64 s[6:7], s13, v16
	global_load_dwordx4 v[16:19], v[24:25], off offset:16
	global_load_dwordx4 v[20:23], v[26:27], off offset:16
	v_cmp_le_i32_e64 s[8:9], s12, v44
	v_cmp_gt_i32_e64 s[10:11], s13, v44
	s_and_b64 vcc, vcc, s[0:1]
	s_and_b64 s[4:5], s[4:5], s[6:7]
	s_and_b64 s[6:7], s[8:9], s[10:11]
	v_cmp_le_i32_e64 s[0:1], s12, v45
	v_cmp_gt_i32_e64 s[8:9], s13, v45
	s_and_b64 s[8:9], s[0:1], s[8:9]
	v_cmp_le_i32_e64 s[0:1], s12, v66
	v_cmp_gt_i32_e64 s[10:11], s13, v66
	s_and_b64 s[10:11], s[0:1], s[10:11]
	v_cmp_le_i32_e64 s[0:1], s12, v67
	v_cmp_gt_i32_e64 s[12:13], s13, v67
	s_and_b64 s[12:13], s[0:1], s[12:13]
	v_add_u32_e32 v90, s18, v138
	v_ashrrev_i32_e32 v91, 31, v90
	v_or_b32_e32 v92, 1, v90
	v_ashrrev_i32_e32 v93, 31, v92
	s_mov_b32 s24, 0
	v_lshlrev_b32_e32 v126, 3, v126
	s_waitcnt vmcnt(0) lgkmcnt(0)
	v_cndmask_b32_e32 v44, 0, v1, vcc
	v_cndmask_b32_e32 v68, 0, v0, vcc
	v_cndmask_b32_e64 v69, 0, v5, s[4:5]
	v_cndmask_b32_e64 v73, 0, v4, s[4:5]
	v_cndmask_b32_e64 v76, 0, v39, s[6:7]
	v_cndmask_b32_e64 v78, 0, v38, s[6:7]
	v_cndmask_b32_e64 v38, 0, v37, s[6:7]
	v_cndmask_b32_e64 v39, 0, v36, s[6:7]
	v_and_b32_e32 v37, 0xffff0000, v44
	v_and_b32_e32 v36, 0xffff0000, v68
	v_cndmask_b32_e32 v70, 0, v3, vcc
	v_cndmask_b32_e32 v71, 0, v2, vcc
	v_cndmask_b32_e64 v72, 0, v7, s[4:5]
	v_cndmask_b32_e64 v74, 0, v6, s[4:5]
	v_lshlrev_b32_e32 v45, 16, v69
	v_lshlrev_b32_e32 v75, 16, v76
	v_and_b32_e32 v77, 0xffff0000, v76
	v_and_b32_e32 v76, 0xffff0000, v78
	v_cndmask_b32_e64 v86, 0, v59, s[10:11]
	v_cndmask_b32_e64 v87, 0, v58, s[10:11]
	v_and_b32_e32 v59, 0xffff0000, v69
	v_and_b32_e32 v58, 0xffff0000, v73
	v_pk_add_f32 v[36:37], v[36:37], v[58:59] neg_lo:[0,1] neg_hi:[0,1]
	v_cndmask_b32_e64 v94, 0, v57, s[10:11]
	v_cndmask_b32_e64 v95, 0, v56, s[10:11]
	v_cndmask_b32_e64 v96, 0, v63, s[12:13]
	v_cndmask_b32_e64 v97, 0, v62, s[12:13]
	v_and_b32_e32 v63, 0xffff0000, v38
	v_and_b32_e32 v62, 0xffff0000, v39
	v_cndmask_b32_e64 v118, 0, v61, s[12:13]
	v_cndmask_b32_e64 v119, 0, v60, s[12:13]
	v_lshlrev_b32_e32 v61, 16, v38
	v_lshlrev_b32_e32 v60, 16, v39
	v_lshl_add_u64 v[56:57], v[88:89], 0, s[36:37]
	v_mov_b32_e32 v67, v10
	v_mov_b32_e32 v10, v9
	v_readfirstlane_b32 s1, v31
	v_readfirstlane_b32 s0, v30
	v_lshlrev_b32_e32 v31, 16, v44
	v_lshlrev_b32_e32 v30, 16, v68
	v_lshlrev_b32_e32 v44, 16, v73
	v_mov_b32_e32 v66, v8
	v_mov_b32_e32 v69, v14
	v_pk_fma_f32 v[8:9], v[10:11], v[36:37], v[58:59]
	v_pk_add_f32 v[36:37], v[62:63], v[58:59] neg_lo:[0,1] neg_hi:[0,1]
	v_mov_b32_e32 v14, v13
	v_pk_add_f32 v[30:31], v[30:31], v[44:45] neg_lo:[0,1] neg_hi:[0,1]
	v_mov_b32_e32 v68, v12
	v_pk_fma_f32 v[36:37], v[14:15], v[36:37], v[8:9]
	v_lshlrev_b32_e32 v9, 16, v70
	v_lshlrev_b32_e32 v8, 16, v71
	v_and_b32_e32 v13, 0xffff0000, v70
	v_and_b32_e32 v12, 0xffff0000, v71
	v_lshlrev_b32_e32 v71, 16, v72
	v_lshlrev_b32_e32 v70, 16, v74
	v_pk_fma_f32 v[30:31], v[66:67], v[30:31], v[44:45]
	v_pk_add_f32 v[38:39], v[60:61], v[44:45] neg_lo:[0,1] neg_hi:[0,1]
	v_and_b32_e32 v73, 0xffff0000, v72
	v_and_b32_e32 v72, 0xffff0000, v74
	v_lshlrev_b32_e32 v74, 16, v78
	v_pk_add_f32 v[8:9], v[8:9], v[70:71] neg_lo:[0,1] neg_hi:[0,1]
	v_mov_b32_e32 v78, v16
	v_mov_b32_e32 v79, v18
	v_pk_fma_f32 v[30:31], v[68:69], v[38:39], v[30:31]
	v_pk_fma_f32 v[8:9], v[78:79], v[8:9], v[70:71]
	v_pk_add_f32 v[38:39], v[74:75], v[70:71] neg_lo:[0,1] neg_hi:[0,1]
	v_mov_b32_e32 v80, v20
	v_mov_b32_e32 v81, v22
	v_pk_fma_f32 v[98:99], v[80:81], v[38:39], v[8:9]
	v_pk_add_f32 v[8:9], v[12:13], v[72:73] neg_lo:[0,1] neg_hi:[0,1]
	v_mov_b32_e32 v18, v17
	v_pk_fma_f32 v[8:9], v[18:19], v[8:9], v[72:73]
	v_pk_add_f32 v[12:13], v[76:77], v[72:73] neg_lo:[0,1] neg_hi:[0,1]
	v_mov_b32_e32 v22, v21
	v_pk_fma_f32 v[100:101], v[22:23], v[12:13], v[8:9]
	v_bfe_u32 v8, v30, 16, 1
	v_bfe_u32 v9, v31, 16, 1
	v_bfe_u32 v12, v98, 16, 1
	v_bfe_u32 v13, v99, 16, 1
	v_add3_u32 v13, v99, v13, s58
	v_add3_u32 v12, v98, v12, s58
	v_add3_u32 v9, v31, v9, s58
	v_add3_u32 v8, v30, v8, s58
	v_lshrrev_b32_e32 v8, 16, v8
	v_lshrrev_b32_e32 v9, 16, v9
	v_lshrrev_b32_e32 v12, 16, v12
	v_lshrrev_b32_e32 v13, 16, v13
	v_lshlrev_b64 v[38:39], 9, v[90:91]
	v_cndmask_b32_e64 v82, 0, v43, s[8:9]
	v_cndmask_b32_e64 v83, 0, v42, s[8:9]
	v_cndmask_b32_e64 v84, 0, v41, s[8:9]
	v_cndmask_b32_e64 v85, 0, v40, s[8:9]
	v_lshl_add_u64 v[0:1], s[0:1], 0, v[64:65]
	v_and_or_b32 v43, v101, s54, v13
	v_and_or_b32 v42, v100, s54, v12
	v_and_or_b32 v41, v37, s54, v9
	v_and_or_b32 v40, v36, s54, v8
	v_lshl_add_u64 v[8:9], v[56:57], 0, v[38:39]
	global_load_dwordx4 v[4:7], v[0:1], off
	s_nop 0
	global_load_dwordx4 v[0:3], v[0:1], off offset:16
	v_pk_add_f32 v[16:17], v[44:45], v[60:61] neg_lo:[0,1] neg_hi:[0,1]
	global_store_dwordx4 v[8:9], v[40:43], off
	v_lshlrev_b32_e32 v9, 16, v84
	v_lshlrev_b32_e32 v8, 16, v85
	v_pk_fma_f32 v[16:17], v[66:67], v[16:17], v[60:61]
	v_pk_add_f32 v[20:21], v[8:9], v[60:61] neg_lo:[0,1] neg_hi:[0,1]
	v_and_b32_e32 v13, 0xffff0000, v84
	v_and_b32_e32 v12, 0xffff0000, v85
	v_pk_fma_f32 v[102:103], v[68:69], v[20:21], v[16:17]
	v_pk_add_f32 v[16:17], v[58:59], v[62:63] neg_lo:[0,1] neg_hi:[0,1]
	v_pk_add_f32 v[20:21], v[12:13], v[62:63] neg_lo:[0,1] neg_hi:[0,1]
	v_pk_fma_f32 v[16:17], v[10:11], v[16:17], v[62:63]
	v_pk_add_f32 v[40:41], v[70:71], v[74:75] neg_lo:[0,1] neg_hi:[0,1]
	v_pk_fma_f32 v[104:105], v[14:15], v[20:21], v[16:17]
	v_lshlrev_b32_e32 v17, 16, v82
	v_lshlrev_b32_e32 v16, 16, v83
	v_pk_fma_f32 v[40:41], v[78:79], v[40:41], v[74:75]
	v_pk_add_f32 v[42:43], v[16:17], v[74:75] neg_lo:[0,1] neg_hi:[0,1]
	v_and_b32_e32 v21, 0xffff0000, v82
	v_and_b32_e32 v20, 0xffff0000, v83
	v_pk_fma_f32 v[106:107], v[80:81], v[42:43], v[40:41]
	v_pk_add_f32 v[40:41], v[72:73], v[76:77] neg_lo:[0,1] neg_hi:[0,1]
	v_pk_add_f32 v[42:43], v[20:21], v[76:77] neg_lo:[0,1] neg_hi:[0,1]
	v_pk_fma_f32 v[40:41], v[18:19], v[40:41], v[76:77]
	v_pk_add_f32 v[60:61], v[60:61], v[8:9] neg_lo:[0,1] neg_hi:[0,1]
	v_pk_fma_f32 v[108:109], v[22:23], v[42:43], v[40:41]
	v_bfe_u32 v40, v102, 16, 1
	v_bfe_u32 v41, v103, 16, 1
	v_bfe_u32 v42, v106, 16, 1
	v_bfe_u32 v43, v107, 16, 1
	v_add3_u32 v43, v107, v43, s58
	v_add3_u32 v42, v106, v42, s58
	v_add3_u32 v41, v103, v41, s58
	v_add3_u32 v40, v102, v40, s58
	v_lshrrev_b32_e32 v40, 16, v40
	v_lshrrev_b32_e32 v41, 16, v41
	v_lshrrev_b32_e32 v42, 16, v42
	v_lshrrev_b32_e32 v43, 16, v43
	v_and_or_b32 v45, v109, s54, v43
	v_and_or_b32 v44, v108, s54, v42
	v_and_or_b32 v43, v105, s54, v41
	v_and_or_b32 v42, v104, s54, v40
	v_lshlrev_b64 v[40:41], 9, v[92:93]
	v_lshl_add_u64 v[58:59], v[56:57], 0, v[40:41]
	global_store_dwordx4 v[58:59], v[42:45], off
	v_pk_fma_f32 v[60:61], v[66:67], v[60:61], v[8:9]
	v_and_b32_e32 v71, 0xffff0000, v94
	v_lshlrev_b32_e32 v45, 16, v94
	v_lshlrev_b32_e32 v44, 16, v95
	v_pk_add_f32 v[42:43], v[44:45], v[8:9] neg_lo:[0,1] neg_hi:[0,1]
	v_and_b32_e32 v70, 0xffff0000, v95
	v_pk_fma_f32 v[110:111], v[68:69], v[42:43], v[60:61]
	v_pk_add_f32 v[42:43], v[62:63], v[12:13] neg_lo:[0,1] neg_hi:[0,1]
	v_pk_add_f32 v[58:59], v[70:71], v[12:13] neg_lo:[0,1] neg_hi:[0,1]
	v_pk_fma_f32 v[42:43], v[10:11], v[42:43], v[12:13]
	v_lshlrev_b32_e32 v63, 16, v86
	v_lshlrev_b32_e32 v62, 16, v87
	v_pk_add_f32 v[60:61], v[74:75], v[16:17] neg_lo:[0,1] neg_hi:[0,1]
	v_pk_fma_f32 v[112:113], v[14:15], v[58:59], v[42:43]
	v_pk_add_f32 v[42:43], v[62:63], v[16:17] neg_lo:[0,1] neg_hi:[0,1]
	v_pk_fma_f32 v[60:61], v[78:79], v[60:61], v[16:17]
	v_and_b32_e32 v73, 0xffff0000, v86
	v_and_b32_e32 v72, 0xffff0000, v87
	v_pk_fma_f32 v[114:115], v[80:81], v[42:43], v[60:61]
	v_pk_add_f32 v[42:43], v[76:77], v[20:21] neg_lo:[0,1] neg_hi:[0,1]
	v_pk_add_f32 v[58:59], v[72:73], v[20:21] neg_lo:[0,1] neg_hi:[0,1]
	v_pk_fma_f32 v[42:43], v[18:19], v[42:43], v[20:21]
	v_or_b32_e32 v94, 2, v90
	v_pk_fma_f32 v[116:117], v[22:23], v[58:59], v[42:43]
	v_bfe_u32 v42, v110, 16, 1
	v_bfe_u32 v43, v111, 16, 1
	v_bfe_u32 v58, v114, 16, 1
	v_bfe_u32 v59, v115, 16, 1
	v_add3_u32 v59, v115, v59, s58
	v_add3_u32 v58, v114, v58, s58
	v_add3_u32 v43, v111, v43, s58
	v_add3_u32 v42, v110, v42, s58
	v_lshrrev_b32_e32 v42, 16, v42
	v_lshrrev_b32_e32 v43, 16, v43
	v_lshrrev_b32_e32 v58, 16, v58
	v_lshrrev_b32_e32 v59, 16, v59
	v_ashrrev_i32_e32 v95, 31, v94
	v_and_or_b32 v61, v117, s54, v59
	v_and_or_b32 v60, v116, s54, v58
	v_and_or_b32 v59, v113, s54, v43
	v_and_or_b32 v58, v112, s54, v42
	v_lshlrev_b64 v[42:43], 9, v[94:95]
	v_lshl_add_u64 v[74:75], v[56:57], 0, v[42:43]
	global_store_dwordx4 v[74:75], v[58:61], off
	v_pk_add_f32 v[8:9], v[8:9], v[44:45] neg_lo:[0,1] neg_hi:[0,1]
	v_pk_add_f32 v[12:13], v[12:13], v[70:71] neg_lo:[0,1] neg_hi:[0,1]
	v_lshlrev_b32_e32 v59, 16, v118
	v_lshlrev_b32_e32 v58, 16, v119
	v_and_b32_e32 v61, 0xffff0000, v118
	v_and_b32_e32 v60, 0xffff0000, v119
	v_pk_add_f32 v[58:59], v[58:59], v[44:45] neg_lo:[0,1] neg_hi:[0,1]
	v_pk_fma_f32 v[8:9], v[66:67], v[8:9], v[44:45]
	v_pk_add_f32 v[60:61], v[60:61], v[70:71] neg_lo:[0,1] neg_hi:[0,1]
	v_pk_fma_f32 v[118:119], v[68:69], v[58:59], v[8:9]
	v_pk_fma_f32 v[8:9], v[10:11], v[12:13], v[70:71]
	v_pk_add_f32 v[12:13], v[16:17], v[62:63] neg_lo:[0,1] neg_hi:[0,1]
	v_pk_fma_f32 v[120:121], v[14:15], v[60:61], v[8:9]
	v_lshlrev_b32_e32 v9, 16, v96
	v_lshlrev_b32_e32 v8, 16, v97
	v_and_b32_e32 v11, 0xffff0000, v96
	v_and_b32_e32 v10, 0xffff0000, v97
	v_pk_add_f32 v[8:9], v[8:9], v[62:63] neg_lo:[0,1] neg_hi:[0,1]
	v_pk_add_f32 v[14:15], v[20:21], v[72:73] neg_lo:[0,1] neg_hi:[0,1]
	v_pk_fma_f32 v[12:13], v[78:79], v[12:13], v[62:63]
	v_pk_add_f32 v[10:11], v[10:11], v[72:73] neg_lo:[0,1] neg_hi:[0,1]
	v_pk_fma_f32 v[122:123], v[80:81], v[8:9], v[12:13]
	v_pk_fma_f32 v[8:9], v[18:19], v[14:15], v[72:73]
	v_or_b32_e32 v96, 3, v90
	v_pk_fma_f32 v[124:125], v[22:23], v[10:11], v[8:9]
	v_bfe_u32 v8, v118, 16, 1
	v_bfe_u32 v9, v119, 16, 1
	v_bfe_u32 v10, v122, 16, 1
	v_bfe_u32 v11, v123, 16, 1
	v_add3_u32 v11, v123, v11, s58
	v_add3_u32 v10, v122, v10, s58
	v_add3_u32 v9, v119, v9, s58
	v_add3_u32 v8, v118, v8, s58
	v_ashrrev_i32_e32 v97, 31, v96
	v_lshrrev_b32_e32 v8, 16, v8
	v_lshrrev_b32_e32 v9, 16, v9
	v_lshrrev_b32_e32 v10, 16, v10
	v_lshrrev_b32_e32 v11, 16, v11
	v_lshlrev_b64 v[44:45], 9, v[96:97]
	v_and_or_b32 v11, v125, s54, v11
	v_and_or_b32 v10, v124, s54, v10
	v_and_or_b32 v9, v121, s54, v9
	v_and_or_b32 v8, v120, s54, v8
	v_lshl_add_u64 v[12:13], v[56:57], 0, v[44:45]
	global_store_dwordx4 v[12:13], v[8:11], off
	s_waitcnt vmcnt(0) lgkmcnt(0)
	v_mul_f32_e32 v159, v98, v0
	v_mul_f32_e32 v160, v100, v1
	v_lshl_add_u64 v[8:9], v[88:89], 0, s[38:39]
	v_lshl_add_u64 v[10:11], v[8:9], 0, v[28:29]
	global_load_dwordx4 v[56:59], v[10:11], off
	v_lshl_add_u64 v[10:11], v[8:9], 0, v[46:47]
	global_load_dwordx4 v[60:63], v[10:11], off
	v_lshl_add_u64 v[10:11], v[8:9], 0, v[48:49]
	global_load_dwordx4 v[66:69], v[10:11], off
	v_lshl_add_u64 v[10:11], v[8:9], 0, v[50:51]
	global_load_dwordx4 v[70:73], v[10:11], off
	v_lshl_add_u64 v[10:11], v[8:9], 0, v[52:53]
	global_load_dwordx4 v[74:77], v[10:11], off
	v_lshl_add_u64 v[8:9], v[8:9], 0, v[54:55]
	global_load_dwordx4 v[78:81], v[8:9], off
	s_nop 0
	global_load_dwordx4 v[8:11], v[24:25], off offset:2048
	global_load_dwordx4 v[12:15], v[26:27], off offset:2048
	global_load_dwordx4 v[16:19], v[24:25], off offset:2064
	global_load_dwordx4 v[20:23], v[26:27], off offset:2064
	v_mul_f32_e32 v161, v99, v2
	v_mul_f32_e32 v162, v101, v3
	v_mul_f32_e32 v163, v4, v102
	v_mul_f32_e32 v168, v5, v104
	v_mul_f32_e32 v169, v103, v6
	v_mul_f32_e32 v170, v105, v7
	v_mul_f32_e32 v171, v106, v0
	v_mul_f32_e32 v175, v114, v0
	v_mul_f32_e32 v187, v122, v0
	v_mul_f32_e32 v172, v108, v1
	v_mul_f32_e32 v176, v116, v1
	v_mul_f32_e32 v177, v115, v2
	v_mul_f32_e32 v188, v124, v1
	v_bitop3_b32 v1, v135, 31, v130 bitop3:0xe0
	v_mul_f32_e32 v173, v107, v2
	v_mul_f32_e32 v174, v109, v3
	v_mul_f32_e32 v110, v4, v110
	v_mul_f32_e32 v112, v5, v112
	v_mul_f32_e32 v111, v6, v111
	v_mul_f32_e32 v113, v113, v7
	v_mul_f32_e32 v178, v117, v3
	v_mul_f32_e32 v179, v4, v118
	v_mul_f32_e32 v184, v5, v120
	v_mul_f32_e32 v185, v6, v119
	v_mul_f32_e32 v186, v7, v121
	v_mul_f32_e32 v189, v123, v2
	v_mul_f32_e32 v190, v125, v3
	s_waitcnt vmcnt(0) lgkmcnt(0)
	v_cndmask_b32_e32 v84, 0, v57, vcc
	v_cndmask_b32_e32 v85, 0, v56, vcc
	v_cndmask_b32_e64 v136, 0, v61, s[4:5]
	v_cndmask_b32_e64 v139, 0, v60, s[4:5]
	v_cndmask_b32_e64 v142, 0, v67, s[6:7]
	v_cndmask_b32_e64 v143, 0, v66, s[6:7]
	v_and_b32_e32 v61, 0xffff0000, v84
	v_and_b32_e32 v60, 0xffff0000, v85
	v_and_b32_e32 v67, 0xffff0000, v136
	v_and_b32_e32 v66, 0xffff0000, v139
	v_cndmask_b32_e32 v82, 0, v59, vcc
	v_cndmask_b32_e32 v83, 0, v58, vcc
	v_cndmask_b32_e64 v86, 0, v63, s[4:5]
	v_cndmask_b32_e64 v87, 0, v62, s[4:5]
	v_cndmask_b32_e64 v144, 0, v73, s[8:9]
	v_cndmask_b32_e64 v146, 0, v71, s[8:9]
	v_cndmask_b32_e64 v147, 0, v70, s[8:9]
	v_lshlrev_b32_e32 v59, 16, v84
	v_lshlrev_b32_e32 v58, 16, v85
	v_lshlrev_b32_e32 v63, 16, v136
	v_lshlrev_b32_e32 v62, 16, v139
	v_and_b32_e32 v71, 0xffff0000, v142
	v_and_b32_e32 v70, 0xffff0000, v143
	v_mov_b32_e32 v73, v10
	v_pk_add_f32 v[60:61], v[60:61], v[66:67] neg_lo:[0,1] neg_hi:[0,1]
	v_mov_b32_e32 v10, v9
	v_cndmask_b32_e64 v140, 0, v69, s[6:7]
	v_cndmask_b32_e64 v141, 0, v68, s[6:7]
	v_cndmask_b32_e64 v145, 0, v72, s[8:9]
	v_cndmask_b32_e64 v148, 0, v77, s[10:11]
	v_lshlrev_b32_e32 v69, 16, v142
	v_lshlrev_b32_e32 v68, 16, v143
	v_pk_add_f32 v[58:59], v[58:59], v[62:63] neg_lo:[0,1] neg_hi:[0,1]
	v_mov_b32_e32 v72, v8
	v_mov_b32_e32 v77, v14
	v_pk_fma_f32 v[8:9], v[10:11], v[60:61], v[66:67]
	v_pk_add_f32 v[60:61], v[70:71], v[66:67] neg_lo:[0,1] neg_hi:[0,1]
	v_mov_b32_e32 v14, v13
	v_cndmask_b32_e64 v149, 0, v76, s[10:11]
	v_cndmask_b32_e64 v150, 0, v75, s[10:11]
	v_cndmask_b32_e64 v151, 0, v74, s[10:11]
	v_cndmask_b32_e64 v154, 0, v79, s[12:13]
	v_cndmask_b32_e64 v155, 0, v78, s[12:13]
	v_pk_fma_f32 v[58:59], v[72:73], v[58:59], v[62:63]
	v_pk_add_f32 v[74:75], v[68:69], v[62:63] neg_lo:[0,1] neg_hi:[0,1]
	v_mov_b32_e32 v76, v12
	v_pk_fma_f32 v[8:9], v[14:15], v[60:61], v[8:9]
	v_and_b32_e32 v61, 0xffff0000, v82
	v_and_b32_e32 v60, 0xffff0000, v83
	v_and_b32_e32 v79, 0xffff0000, v86
	v_and_b32_e32 v78, 0xffff0000, v87
	v_pk_fma_f32 v[58:59], v[76:77], v[74:75], v[58:59]
	s_nop 0
	v_cvt_pk_bf16_f32 v210, v59, v9
	v_cvt_pk_bf16_f32 v211, v58, v8
	v_lshlrev_b32_e32 v13, 16, v82
	v_lshlrev_b32_e32 v12, 16, v83
	v_lshlrev_b32_e32 v75, 16, v86
	v_lshlrev_b32_e32 v74, 16, v87
	v_and_b32_e32 v83, 0xffff0000, v140
	v_and_b32_e32 v82, 0xffff0000, v141
	v_mov_b32_e32 v85, v18
	v_pk_add_f32 v[60:61], v[60:61], v[78:79] neg_lo:[0,1] neg_hi:[0,1]
	v_mov_b32_e32 v18, v17
	v_cndmask_b32_e64 v152, 0, v81, s[12:13]
	v_cndmask_b32_e64 v153, 0, v80, s[12:13]
	v_lshlrev_b32_e32 v81, 16, v140
	v_lshlrev_b32_e32 v80, 16, v141
	v_pk_add_f32 v[12:13], v[12:13], v[74:75] neg_lo:[0,1] neg_hi:[0,1]
	v_mov_b32_e32 v84, v16
	v_mov_b32_e32 v141, v22
	v_pk_fma_f32 v[16:17], v[18:19], v[60:61], v[78:79]
	v_pk_add_f32 v[60:61], v[82:83], v[78:79] neg_lo:[0,1] neg_hi:[0,1]
	v_mov_b32_e32 v22, v21
	v_pk_fma_f32 v[12:13], v[84:85], v[12:13], v[74:75]
	v_pk_add_f32 v[86:87], v[80:81], v[74:75] neg_lo:[0,1] neg_hi:[0,1]
	v_mov_b32_e32 v140, v20
	v_pk_fma_f32 v[16:17], v[22:23], v[60:61], v[16:17]
	v_pk_fma_f32 v[12:13], v[140:141], v[86:87], v[12:13]
	s_nop 0
	v_cvt_pk_bf16_f32 v208, v13, v17
	v_cvt_pk_bf16_f32 v209, v12, v16
	v_lshl_add_u64 v[56:57], v[88:89], 0, s[40:41]
	v_mov_b32_e32 v61, v208
	v_mov_b32_e32 v60, v209
	v_mov_b32_e32 v59, v210
	v_mov_b32_e32 v58, v211
	v_lshl_add_u64 v[8:9], v[56:57], 0, v[38:39]
	global_store_dwordx4 v[8:9], v[58:61], off
	v_lshlrev_b32_e32 v9, 16, v146
	v_lshlrev_b32_e32 v8, 16, v147
	v_pk_add_f32 v[16:17], v[62:63], v[68:69] neg_lo:[0,1] neg_hi:[0,1]
	v_pk_add_f32 v[20:21], v[8:9], v[68:69] neg_lo:[0,1] neg_hi:[0,1]
	v_pk_fma_f32 v[16:17], v[72:73], v[16:17], v[68:69]
	v_and_b32_e32 v13, 0xffff0000, v146
	v_and_b32_e32 v12, 0xffff0000, v147
	v_pk_fma_f32 v[16:17], v[76:77], v[20:21], v[16:17]
	v_pk_add_f32 v[20:21], v[66:67], v[70:71] neg_lo:[0,1] neg_hi:[0,1]
	v_pk_add_f32 v[58:59], v[12:13], v[70:71] neg_lo:[0,1] neg_hi:[0,1]
	v_pk_fma_f32 v[20:21], v[10:11], v[20:21], v[70:71]
	v_lshlrev_b32_e32 v63, 16, v144
	v_pk_fma_f32 v[20:21], v[14:15], v[58:59], v[20:21]
	s_nop 0
	v_cvt_pk_bf16_f32 v210, v17, v21
	v_cvt_pk_bf16_f32 v211, v16, v20
	v_lshlrev_b32_e32 v62, 16, v145
	v_pk_add_f32 v[58:59], v[74:75], v[80:81] neg_lo:[0,1] neg_hi:[0,1]
	v_pk_add_f32 v[60:61], v[62:63], v[80:81] neg_lo:[0,1] neg_hi:[0,1]
	v_pk_fma_f32 v[58:59], v[84:85], v[58:59], v[80:81]
	v_and_b32_e32 v67, 0xffff0000, v144
	v_and_b32_e32 v66, 0xffff0000, v145
	v_pk_fma_f32 v[58:59], v[140:141], v[60:61], v[58:59]
	v_pk_add_f32 v[60:61], v[78:79], v[82:83] neg_lo:[0,1] neg_hi:[0,1]
	v_pk_add_f32 v[74:75], v[66:67], v[82:83] neg_lo:[0,1] neg_hi:[0,1]
	v_pk_fma_f32 v[60:61], v[18:19], v[60:61], v[82:83]
	s_nop 0
	v_pk_fma_f32 v[60:61], v[22:23], v[74:75], v[60:61]
	s_nop 0
	v_cvt_pk_bf16_f32 v208, v59, v61
	v_cvt_pk_bf16_f32 v209, v58, v60
	v_mov_b32_e32 v61, v208
	v_mov_b32_e32 v60, v209
	v_mov_b32_e32 v59, v210
	v_mov_b32_e32 v58, v211
	v_lshl_add_u64 v[16:17], v[56:57], 0, v[40:41]
	global_store_dwordx4 v[16:17], v[58:61], off
	v_lshlrev_b32_e32 v17, 16, v150
	v_lshlrev_b32_e32 v16, 16, v151
	v_pk_add_f32 v[68:69], v[68:69], v[8:9] neg_lo:[0,1] neg_hi:[0,1]
	v_pk_add_f32 v[58:59], v[16:17], v[8:9] neg_lo:[0,1] neg_hi:[0,1]
	v_pk_fma_f32 v[68:69], v[72:73], v[68:69], v[8:9]
	v_and_b32_e32 v21, 0xffff0000, v150
	v_and_b32_e32 v20, 0xffff0000, v151
	v_pk_fma_f32 v[58:59], v[76:77], v[58:59], v[68:69]
	v_pk_add_f32 v[68:69], v[70:71], v[12:13] neg_lo:[0,1] neg_hi:[0,1]
	v_pk_add_f32 v[60:61], v[20:21], v[12:13] neg_lo:[0,1] neg_hi:[0,1]
	v_pk_fma_f32 v[68:69], v[10:11], v[68:69], v[12:13]
	v_pk_add_f32 v[80:81], v[80:81], v[62:63] neg_lo:[0,1] neg_hi:[0,1]
	v_pk_fma_f32 v[60:61], v[14:15], v[60:61], v[68:69]
	s_nop 0
	v_cvt_pk_bf16_f32 v210, v59, v61
	v_cvt_pk_bf16_f32 v211, v58, v60
	v_lshlrev_b32_e32 v69, 16, v148
	v_lshlrev_b32_e32 v68, 16, v149
	v_pk_add_f32 v[74:75], v[68:69], v[62:63] neg_lo:[0,1] neg_hi:[0,1]
	v_pk_fma_f32 v[80:81], v[84:85], v[80:81], v[62:63]
	v_and_b32_e32 v71, 0xffff0000, v148
	v_and_b32_e32 v70, 0xffff0000, v149
	v_pk_fma_f32 v[74:75], v[140:141], v[74:75], v[80:81]
	v_pk_add_f32 v[80:81], v[82:83], v[66:67] neg_lo:[0,1] neg_hi:[0,1]
	v_pk_add_f32 v[78:79], v[70:71], v[66:67] neg_lo:[0,1] neg_hi:[0,1]
	v_pk_fma_f32 v[80:81], v[18:19], v[80:81], v[66:67]
	s_nop 0
	v_pk_fma_f32 v[78:79], v[22:23], v[78:79], v[80:81]
	s_nop 0
	v_cvt_pk_bf16_f32 v208, v75, v79
	v_cvt_pk_bf16_f32 v209, v74, v78
	v_mov_b32_e32 v61, v208
	v_mov_b32_e32 v60, v209
	v_mov_b32_e32 v59, v210
	v_mov_b32_e32 v58, v211
	v_lshl_add_u64 v[74:75], v[56:57], 0, v[42:43]
	global_store_dwordx4 v[74:75], v[58:61], off
	v_pk_add_f32 v[8:9], v[8:9], v[16:17] neg_lo:[0,1] neg_hi:[0,1]
	v_pk_add_f32 v[12:13], v[12:13], v[20:21] neg_lo:[0,1] neg_hi:[0,1]
	v_lshlrev_b32_e32 v59, 16, v154
	v_lshlrev_b32_e32 v58, 16, v155
	v_and_b32_e32 v61, 0xffff0000, v154
	v_and_b32_e32 v60, 0xffff0000, v155
	v_pk_add_f32 v[58:59], v[58:59], v[16:17] neg_lo:[0,1] neg_hi:[0,1]
	v_pk_add_f32 v[60:61], v[60:61], v[20:21] neg_lo:[0,1] neg_hi:[0,1]
	v_pk_fma_f32 v[8:9], v[72:73], v[8:9], v[16:17]
	v_pk_fma_f32 v[10:11], v[10:11], v[12:13], v[20:21]
	v_lshlrev_b32_e32 v13, 16, v152
	v_lshlrev_b32_e32 v12, 16, v153
	v_pk_add_f32 v[16:17], v[62:63], v[68:69] neg_lo:[0,1] neg_hi:[0,1]
	v_pk_fma_f32 v[10:11], v[14:15], v[60:61], v[10:11]
	v_and_b32_e32 v15, 0xffff0000, v152
	v_and_b32_e32 v14, 0xffff0000, v153
	v_pk_add_f32 v[12:13], v[12:13], v[68:69] neg_lo:[0,1] neg_hi:[0,1]
	v_pk_add_f32 v[20:21], v[66:67], v[70:71] neg_lo:[0,1] neg_hi:[0,1]
	v_pk_fma_f32 v[16:17], v[84:85], v[16:17], v[68:69]
	v_pk_add_f32 v[14:15], v[14:15], v[70:71] neg_lo:[0,1] neg_hi:[0,1]
	v_pk_fma_f32 v[12:13], v[140:141], v[12:13], v[16:17]
	v_pk_fma_f32 v[16:17], v[18:19], v[20:21], v[70:71]
	v_pk_fma_f32 v[8:9], v[76:77], v[58:59], v[8:9]
	s_nop 0
	v_cvt_pk_bf16_f32 v210, v9, v11
	v_cvt_pk_bf16_f32 v211, v8, v10
	v_pk_fma_f32 v[14:15], v[22:23], v[14:15], v[16:17]
	s_nop 0
	v_cvt_pk_bf16_f32 v208, v13, v15
	v_cvt_pk_bf16_f32 v209, v12, v14
	v_mov_b32_e32 v11, v208
	v_mov_b32_e32 v10, v209
	v_mov_b32_e32 v9, v210
	v_mov_b32_e32 v8, v211
	v_lshl_add_u64 v[12:13], v[56:57], 0, v[44:45]
	global_store_dwordx4 v[12:13], v[8:11], off
	v_lshl_add_u64 v[12:13], v[88:89], 0, s[42:43]
	v_lshl_add_u64 v[14:15], v[12:13], 0, v[46:47]
	v_lshl_add_u64 v[8:9], v[12:13], 0, v[28:29]
	global_load_dwordx4 v[8:11], v[8:9], off
	v_and_b32_e32 v136, 0xffffffc0, v135
	global_load_dwordx4 v[56:59], v[14:15], off
	v_lshl_add_u64 v[14:15], v[12:13], 0, v[48:49]
	global_load_dwordx4 v[46:49], v[14:15], off
	v_lshl_add_u64 v[14:15], v[12:13], 0, v[50:51]
	global_load_dwordx4 v[60:63], v[14:15], off
	v_lshl_add_u64 v[14:15], v[12:13], 0, v[52:53]
	v_lshl_add_u64 v[12:13], v[12:13], 0, v[54:55]
	global_load_dwordx4 v[50:53], v[14:15], off
	global_load_dwordx4 v[66:69], v[12:13], off
	s_nop 0
	global_load_dwordx2 v[12:13], v[32:33], off offset:448
	global_load_dwordx4 v[18:21], v[24:25], off offset:1024
	global_load_dwordx4 v[14:17], v[26:27], off offset:1024
	s_waitcnt vmcnt(0) lgkmcnt(0)
	v_cndmask_b32_e32 v82, 0, v9, vcc
	global_load_dwordx4 v[22:25], v[24:25], off offset:1040
	v_cndmask_b32_e32 v83, 0, v8, vcc
	global_load_dwordx4 v[26:29], v[26:27], off offset:1040
	v_cndmask_b32_e64 v54, 0, v57, s[4:5]
	v_cndmask_b32_e64 v56, 0, v56, s[4:5]
	v_cndmask_b32_e64 v55, 0, v47, s[6:7]
	v_cndmask_b32_e64 v57, 0, v46, s[6:7]
	v_cndmask_b32_e32 v139, 0, v11, vcc
	v_cndmask_b32_e32 v146, 0, v10, vcc
	v_cndmask_b32_e64 v151, 0, v63, s[8:9]
	v_cndmask_b32_e64 v152, 0, v62, s[8:9]
	v_cndmask_b32_e64 v157, 0, v67, s[12:13]
	v_cndmask_b32_e64 v158, 0, v66, s[12:13]
	v_lshlrev_b32_e32 v8, 16, v83
	v_lshlrev_b32_e32 v9, 16, v82
	v_lshlrev_b32_e32 v10, 16, v56
	v_lshlrev_b32_e32 v11, 16, v54
	v_lshlrev_b32_e32 v62, 16, v57
	v_lshlrev_b32_e32 v63, 16, v55
	v_readfirstlane_b32 s1, v13
	v_readfirstlane_b32 s0, v12
	v_and_b32_e32 v67, 0xffff0000, v55
	v_and_b32_e32 v66, 0xffff0000, v57
	v_and_b32_e32 v55, 0xffff0000, v54
	v_and_b32_e32 v54, 0xffff0000, v56
	v_and_b32_e32 v57, 0xffff0000, v82
	v_and_b32_e32 v56, 0xffff0000, v83
	v_cndmask_b32_e64 v147, 0, v59, s[4:5]
	v_cndmask_b32_e64 v148, 0, v58, s[4:5]
	v_cndmask_b32_e64 v58, 0, v61, s[8:9]
	v_cndmask_b32_e64 v59, 0, v60, s[8:9]
	v_lshl_add_u64 v[12:13], s[0:1], 0, v[64:65]
	v_pk_add_f32 v[8:9], v[8:9], v[10:11] neg_lo:[0,1] neg_hi:[0,1]
	v_pk_add_f32 v[56:57], v[56:57], v[54:55] neg_lo:[0,1] neg_hi:[0,1]
	v_mov_b32_e32 v82, v18
	v_mov_b32_e32 v83, v20
	v_mov_b32_e32 v20, v19
	v_cndmask_b32_e64 v155, 0, v69, s[12:13]
	v_cndmask_b32_e64 v156, 0, v68, s[12:13]
	v_lshlrev_b32_e32 v68, 16, v59
	v_lshlrev_b32_e32 v69, 16, v58
	v_and_b32_e32 v77, 0xffff0000, v58
	v_and_b32_e32 v76, 0xffff0000, v59
	v_pk_add_f32 v[58:59], v[10:11], v[62:63] neg_lo:[0,1] neg_hi:[0,1]
	v_pk_fma_f32 v[140:141], v[82:83], v[8:9], v[10:11]
	v_pk_fma_f32 v[18:19], v[20:21], v[56:57], v[54:55]
	v_pk_add_f32 v[56:57], v[62:63], v[10:11] neg_lo:[0,1] neg_hi:[0,1]
	global_load_dwordx4 v[8:11], v[12:13], off
	v_mov_b32_e32 v144, v14
	v_mov_b32_e32 v145, v16
	v_mov_b32_e32 v16, v15
	global_load_dwordx4 v[12:15], v[12:13], off offset:16
	v_cndmask_b32_e64 v60, 0, v51, s[10:11]
	v_cndmask_b32_e64 v61, 0, v50, s[10:11]
	v_pk_add_f32 v[142:143], v[66:67], v[54:55] neg_lo:[0,1] neg_hi:[0,1]
	v_lshlrev_b32_e32 v70, 16, v61
	v_lshlrev_b32_e32 v71, 16, v60
	v_and_b32_e32 v79, 0xffff0000, v60
	v_and_b32_e32 v78, 0xffff0000, v61
	v_pk_add_f32 v[60:61], v[54:55], v[66:67] neg_lo:[0,1] neg_hi:[0,1]
	v_pk_fma_f32 v[54:55], v[144:145], v[56:57], v[140:141]
	v_pk_fma_f32 v[56:57], v[16:17], v[142:143], v[18:19]
	v_pk_fma_f32 v[18:19], v[82:83], v[58:59], v[62:63]
	v_pk_add_f32 v[58:59], v[68:69], v[62:63] neg_lo:[0,1] neg_hi:[0,1]
	v_and_b32_e32 v141, 0xffff0000, v157
	v_pk_fma_f32 v[58:59], v[144:145], v[58:59], v[18:19]
	v_pk_fma_f32 v[18:19], v[20:21], v[60:61], v[66:67]
	v_pk_add_f32 v[60:61], v[76:77], v[66:67] neg_lo:[0,1] neg_hi:[0,1]
	v_and_b32_e32 v140, 0xffff0000, v158
	v_pk_fma_f32 v[60:61], v[16:17], v[60:61], v[18:19]
	v_pk_add_f32 v[18:19], v[62:63], v[68:69] neg_lo:[0,1] neg_hi:[0,1]
	v_pk_add_f32 v[62:63], v[70:71], v[68:69] neg_lo:[0,1] neg_hi:[0,1]
	v_pk_fma_f32 v[18:19], v[82:83], v[18:19], v[68:69]
	v_pk_add_f32 v[68:69], v[68:69], v[70:71] neg_lo:[0,1] neg_hi:[0,1]
	v_pk_fma_f32 v[62:63], v[144:145], v[62:63], v[18:19]
	v_pk_add_f32 v[18:19], v[66:67], v[76:77] neg_lo:[0,1] neg_hi:[0,1]
	v_pk_add_f32 v[66:67], v[78:79], v[76:77] neg_lo:[0,1] neg_hi:[0,1]
	v_pk_fma_f32 v[18:19], v[20:21], v[18:19], v[76:77]
	v_pk_fma_f32 v[68:69], v[82:83], v[68:69], v[70:71]
	v_pk_fma_f32 v[66:67], v[16:17], v[66:67], v[18:19]
	v_lshlrev_b32_e32 v19, 16, v157
	v_lshlrev_b32_e32 v18, 16, v158
	v_pk_add_f32 v[18:19], v[18:19], v[70:71] neg_lo:[0,1] neg_hi:[0,1]
	v_cndmask_b32_e64 v149, 0, v49, s[6:7]
	v_pk_fma_f32 v[68:69], v[144:145], v[18:19], v[68:69]
	v_pk_add_f32 v[18:19], v[76:77], v[78:79] neg_lo:[0,1] neg_hi:[0,1]
	v_cndmask_b32_e64 v150, 0, v48, s[6:7]
	v_lshlrev_b32_e32 v74, 16, v146
	v_lshlrev_b32_e32 v75, 16, v139
	v_lshlrev_b32_e32 v72, 16, v148
	v_lshlrev_b32_e32 v73, 16, v147
	v_pk_fma_f32 v[18:19], v[20:21], v[18:19], v[78:79]
	v_pk_add_f32 v[20:21], v[140:141], v[78:79] neg_lo:[0,1] neg_hi:[0,1]
	v_and_b32_e32 v77, 0xffff0000, v147
	v_and_b32_e32 v76, 0xffff0000, v148
	v_and_b32_e32 v141, 0xffff0000, v139
	v_and_b32_e32 v140, 0xffff0000, v146
	v_lshlrev_b32_e32 v80, 16, v150
	v_lshlrev_b32_e32 v81, 16, v149
	v_pk_fma_f32 v[70:71], v[16:17], v[20:21], v[18:19]
	v_and_b32_e32 v17, 0xffff0000, v149
	v_and_b32_e32 v16, 0xffff0000, v150
	v_pk_add_f32 v[74:75], v[74:75], v[72:73] neg_lo:[0,1] neg_hi:[0,1]
	v_pk_add_f32 v[140:141], v[140:141], v[76:77] neg_lo:[0,1] neg_hi:[0,1]
	s_waitcnt vmcnt(0) lgkmcnt(0)
	v_mov_b32_e32 v142, v22
	v_mov_b32_e32 v143, v24
	v_mov_b32_e32 v24, v23
	v_lshlrev_b32_e32 v86, 16, v152
	v_lshlrev_b32_e32 v87, 16, v151
	v_pk_add_f32 v[78:79], v[72:73], v[80:81] neg_lo:[0,1] neg_hi:[0,1]
	v_pk_add_f32 v[82:83], v[76:77], v[16:17] neg_lo:[0,1] neg_hi:[0,1]
	v_pk_fma_f32 v[74:75], v[142:143], v[74:75], v[72:73]
	v_pk_fma_f32 v[22:23], v[24:25], v[140:141], v[76:77]
	v_pk_add_f32 v[72:73], v[80:81], v[72:73] neg_lo:[0,1] neg_hi:[0,1]
	v_pk_add_f32 v[76:77], v[16:17], v[76:77] neg_lo:[0,1] neg_hi:[0,1]
	v_mov_b32_e32 v140, v26
	v_mov_b32_e32 v141, v28
	v_mov_b32_e32 v28, v27
	v_and_b32_e32 v19, 0xffff0000, v151
	v_and_b32_e32 v18, 0xffff0000, v152
	v_pk_fma_f32 v[72:73], v[140:141], v[72:73], v[74:75]
	v_pk_fma_f32 v[74:75], v[28:29], v[76:77], v[22:23]
	v_pk_fma_f32 v[22:23], v[142:143], v[78:79], v[80:81]
	v_pk_add_f32 v[26:27], v[86:87], v[80:81] neg_lo:[0,1] neg_hi:[0,1]
	v_cndmask_b32_e64 v153, 0, v53, s[10:11]
	v_cndmask_b32_e64 v154, 0, v52, s[10:11]
	v_pk_fma_f32 v[76:77], v[140:141], v[26:27], v[22:23]
	v_pk_fma_f32 v[22:23], v[24:25], v[82:83], v[16:17]
	v_pk_add_f32 v[26:27], v[18:19], v[16:17] neg_lo:[0,1] neg_hi:[0,1]
	v_lshlrev_b32_e32 v84, 16, v154
	v_lshlrev_b32_e32 v85, 16, v153
	v_pk_fma_f32 v[78:79], v[28:29], v[26:27], v[22:23]
	v_pk_add_f32 v[22:23], v[80:81], v[86:87] neg_lo:[0,1] neg_hi:[0,1]
	v_and_b32_e32 v21, 0xffff0000, v153
	v_and_b32_e32 v20, 0xffff0000, v154
	v_pk_fma_f32 v[22:23], v[142:143], v[22:23], v[86:87]
	v_pk_add_f32 v[26:27], v[84:85], v[86:87] neg_lo:[0,1] neg_hi:[0,1]
	v_pk_add_f32 v[16:17], v[16:17], v[18:19] neg_lo:[0,1] neg_hi:[0,1]
	v_pk_fma_f32 v[80:81], v[140:141], v[26:27], v[22:23]
	v_pk_fma_f32 v[16:17], v[24:25], v[16:17], v[18:19]
	v_pk_add_f32 v[22:23], v[20:21], v[18:19] neg_lo:[0,1] neg_hi:[0,1]
	v_and_b32_e32 v27, 0xffff0000, v155
	v_pk_fma_f32 v[82:83], v[28:29], v[22:23], v[16:17]
	v_pk_add_f32 v[16:17], v[86:87], v[84:85] neg_lo:[0,1] neg_hi:[0,1]
	v_lshlrev_b32_e32 v23, 16, v155
	v_pk_fma_f32 v[86:87], v[142:143], v[16:17], v[84:85]
	v_mov_b32_e32 v16, v8
	v_mov_b32_e32 v17, v10
	v_mov_b32_e32 v10, v9
	v_pk_mul_f32 v[142:143], v[16:17], v[54:55]
	v_pk_mul_f32 v[144:145], v[56:57], v[10:11]
	v_mov_b32_e32 v8, v143
	v_mov_b32_e32 v9, v145
	v_pk_mul_f32 v[146:147], v[8:9], v[8:9]
	v_mov_b32_e32 v8, v12
	v_mov_b32_e32 v9, v14
	v_mov_b32_e32 v14, v13
	v_mul_f32_e32 v139, v142, v142
	v_pk_mul_f32 v[148:149], v[72:73], v[8:9]
	v_pk_mul_f32 v[12:13], v[74:75], v[14:15]
	v_fmac_f32_e32 v139, v144, v144
	v_mov_b32_e32 v150, v148
	v_mov_b32_e32 v151, v12
	v_add_f32_e32 v139, v139, v146
	v_pk_mul_f32 v[150:151], v[150:151], v[150:151]
	v_add_f32_e32 v139, v139, v147
	v_mov_b32_e32 v152, v149
	v_mov_b32_e32 v153, v13
	v_add_f32_e32 v139, v139, v150
	v_pk_mul_f32 v[152:153], v[152:153], v[152:153]
	v_add_f32_e32 v139, v139, v151
	v_add_f32_e32 v139, v139, v152
	v_add_f32_e32 v139, v139, v153
	v_lshlrev_b32_e32 v22, 16, v156
	v_pk_add_f32 v[22:23], v[22:23], v[84:85] neg_lo:[0,1] neg_hi:[0,1]
	v_add_f32_dpp v139, v139, v139 quad_perm:[1,0,3,2] row_mask:0xf bank_mask:0xf bound_ctrl:1
	v_pk_fma_f32 v[84:85], v[140:141], v[22:23], v[86:87]
	v_and_b32_e32 v26, 0xffff0000, v156
	v_add_f32_dpp v139, v139, v139 quad_perm:[2,3,0,1] row_mask:0xf bank_mask:0xf bound_ctrl:1
	v_pk_add_f32 v[18:19], v[18:19], v[20:21] neg_lo:[0,1] neg_hi:[0,1]
	v_pk_mul_f32 v[140:141], v[78:79], v[14:15]
	v_add_f32_dpp v139, v139, v139 row_half_mirror row_mask:0xf bank_mask:0xf bound_ctrl:1
	v_mul_f32_e32 v146, 0x4f800000, v139
	v_cmp_gt_f32_e32 vcc, s69, v139
	v_pk_fma_f32 v[18:19], v[24:25], v[18:19], v[20:21]
	v_pk_add_f32 v[20:21], v[26:27], v[20:21] neg_lo:[0,1] neg_hi:[0,1]
	v_cndmask_b32_e32 v139, v139, v146, vcc
	v_sqrt_f32_e32 v146, v139
	v_lshl_add_u64 v[52:53], v[88:89], 0, s[44:45]
	v_lshl_add_u64 v[46:47], v[52:53], 0, v[38:39]
	v_lshl_add_u64 v[48:49], v[52:53], 0, v[40:41]
	v_add_u32_e32 v22, -1, v146
	v_fma_f32 v23, -v22, v146, v139
	v_cmp_ge_f32_e64 s[0:1], 0, v23
	v_add_u32_e32 v23, 1, v146
	v_fma_f32 v86, -v23, v146, v139
	v_cndmask_b32_e64 v22, v146, v22, s[0:1]
	v_cmp_lt_f32_e64 s[0:1], 0, v86
	v_pk_fma_f32 v[86:87], v[28:29], v[20:21], v[18:19]
	v_pk_mul_f32 v[28:29], v[76:77], v[8:9]
	v_cndmask_b32_e64 v22, v22, v23, s[0:1]
	v_mul_f32_e32 v23, 0x37800000, v22
	v_cndmask_b32_e32 v22, v22, v23, vcc
	v_cmp_class_f32_e32 vcc, v139, v128
	v_lshl_add_u64 v[50:51], v[52:53], 0, v[42:43]
	v_lshl_add_u64 v[52:53], v[52:53], 0, v[44:45]
	v_cndmask_b32_e32 v22, v22, v139, vcc
	v_max_f32_e32 v22, 0x2b8cbccc, v22
	v_div_scale_f32 v23, s[0:1], v22, v22, 1.0
	v_rcp_f32_e32 v139, v23
	v_mul_f32_e32 v156, v36, v5
	v_mul_f32_e32 v157, v31, v6
	v_mul_f32_e32 v158, v37, v7
	v_fma_f32 v18, -v23, v139, 1.0
	v_fmac_f32_e32 v139, v18, v139
	v_div_scale_f32 v18, vcc, 1.0, v22, 1.0
	v_mul_f32_e32 v19, v18, v139
	v_fma_f32 v20, -v23, v19, v18
	v_fmac_f32_e32 v19, v20, v139
	v_fma_f32 v18, -v23, v19, v18
	v_div_fmas_f32 v18, v18, v139, v19
	v_div_fixup_f32 v18, v18, v22, 1.0
	v_pk_mul_f32 v[20:21], v[142:143], v[18:19] op_sel_hi:[1,0]
	v_pk_mul_f32 v[22:23], v[148:149], v[18:19] op_sel_hi:[1,0]
	v_bfe_u32 v19, v20, 16, 1
	v_bfe_u32 v24, v21, 16, 1
	v_bfe_u32 v25, v22, 16, 1
	v_bfe_u32 v26, v23, 16, 1
	v_add3_u32 v23, v23, v26, s58
	v_add3_u32 v22, v22, v25, s58
	v_add3_u32 v21, v21, v24, s58
	v_add3_u32 v19, v20, v19, s58
	v_pk_mul_f32 v[24:25], v[58:59], v[16:17]
	v_pk_mul_f32 v[26:27], v[60:61], v[10:11]
	v_lshrrev_b32_e32 v139, 16, v19
	v_lshrrev_b32_e32 v19, 16, v21
	v_mov_b32_e32 v20, v27
	v_mov_b32_e32 v21, v25
	v_mul_f32_e32 v148, v24, v24
	v_pk_mul_f32 v[20:21], v[20:21], v[20:21]
	v_fmac_f32_e32 v148, v26, v26
	v_mov_b32_e32 v142, v140
	v_mov_b32_e32 v143, v28
	v_add_f32_e32 v21, v21, v148
	v_pk_mul_f32 v[142:143], v[142:143], v[142:143]
	v_add_f32_e32 v20, v20, v21
	v_lshrrev_b32_e32 v146, 16, v22
	v_lshrrev_b32_e32 v147, 16, v23
	v_pk_mul_f32 v[22:23], v[144:145], v[18:19] op_sel_hi:[1,0]
	v_mov_b32_e32 v144, v141
	v_mov_b32_e32 v145, v29
	v_add_f32_e32 v20, v143, v20
	v_pk_mul_f32 v[144:145], v[144:145], v[144:145]
	v_add_f32_e32 v20, v142, v20
	v_add_f32_e32 v20, v145, v20
	v_add_f32_e32 v20, v144, v20
	v_pk_mul_f32 v[12:13], v[12:13], v[18:19] op_sel_hi:[1,0]
	v_and_or_b32 v19, v23, s54, v19
	v_add_f32_dpp v20, v20, v20 quad_perm:[1,0,3,2] row_mask:0xf bank_mask:0xf bound_ctrl:1
	v_lshlrev_b64 v[36:37], 11, v[94:95]
	v_lshl_add_u64 v[36:37], s[52:53], 0, v[36:37]
	v_add_f32_dpp v20, v20, v20 quad_perm:[2,3,0,1] row_mask:0xf bank_mask:0xf bound_ctrl:1
	v_lshl_add_u64 v[180:181], v[36:37], 0, v[34:35]
	v_or_b32_e32 v36, 3, v137
	v_add_f32_dpp v20, v20, v20 row_half_mirror row_mask:0xf bank_mask:0xf bound_ctrl:1
	v_mul_f32_e32 v21, 0x4f800000, v20
	v_cmp_gt_f32_e32 vcc, s69, v20
	v_mul_lo_u32 v36, v36, s68
	v_add_u32_e32 v119, v64, v36
	v_cndmask_b32_e32 v142, v20, v21, vcc
	v_sqrt_f32_e32 v143, v142
	v_and_or_b32 v20, v12, s54, v146
	v_and_or_b32 v21, v13, s54, v147
	v_lshlrev_b64 v[36:37], 11, v[96:97]
	v_add_u32_e32 v12, -1, v143
	v_fma_f32 v13, -v12, v143, v142
	v_cmp_ge_f32_e64 s[0:1], 0, v13
	v_add_u32_e32 v13, 1, v143
	v_fma_f32 v18, -v13, v143, v142
	v_cndmask_b32_e64 v12, v143, v12, s[0:1]
	v_cmp_lt_f32_e64 s[0:1], 0, v18
	v_and_or_b32 v18, v22, s54, v139
	global_store_dwordx4 v[46:47], v[18:21], off
	v_cndmask_b32_e64 v12, v12, v13, s[0:1]
	v_mul_f32_e32 v13, 0x37800000, v12
	v_cndmask_b32_e32 v12, v12, v13, vcc
	v_cmp_class_f32_e32 vcc, v142, v128
	v_lshl_add_u64 v[36:37], s[52:53], 0, v[36:37]
	v_lshl_add_u64 v[182:183], v[36:37], 0, v[34:35]
	v_cndmask_b32_e32 v12, v12, v142, vcc
	v_max_f32_e32 v12, 0x2b8cbccc, v12
	v_div_scale_f32 v13, s[0:1], v12, v12, 1.0
	v_rcp_f32_e32 v142, v13
	v_mul_f32_e32 v121, v156, v56
	v_mul_f32_e32 v122, v157, v55
	v_mul_f32_e32 v123, v158, v57
	v_fma_f32 v18, -v13, v142, 1.0
	v_fmac_f32_e32 v142, v18, v142
	v_div_scale_f32 v18, vcc, 1.0, v12, 1.0
	v_mul_f32_e32 v19, v18, v142
	v_fma_f32 v20, -v13, v19, v18
	v_fmac_f32_e32 v19, v20, v142
	v_fma_f32 v13, -v13, v19, v18
	v_div_fmas_f32 v13, v13, v142, v19
	v_div_fixup_f32 v12, v13, v12, 1.0
	v_pk_mul_f32 v[18:19], v[24:25], v[12:13] op_sel_hi:[1,0]
	v_pk_mul_f32 v[20:21], v[28:29], v[12:13] op_sel_hi:[1,0]
	v_bfe_u32 v13, v18, 16, 1
	v_bfe_u32 v22, v19, 16, 1
	v_bfe_u32 v23, v20, 16, 1
	v_bfe_u32 v24, v21, 16, 1
	v_add3_u32 v21, v21, v24, s58
	v_add3_u32 v20, v20, v23, s58
	v_add3_u32 v19, v19, v22, s58
	v_add3_u32 v13, v18, v13, s58
	v_pk_mul_f32 v[22:23], v[16:17], v[62:63]
	v_pk_mul_f32 v[24:25], v[66:67], v[10:11]
	v_lshrrev_b32_e32 v139, 16, v13
	v_lshrrev_b32_e32 v146, 16, v19
	v_lshrrev_b32_e32 v147, 16, v20
	v_lshrrev_b32_e32 v148, 16, v21
	v_pk_mul_f32 v[18:19], v[26:27], v[12:13] op_sel_hi:[1,0]
	v_mov_b32_e32 v20, v25
	v_mov_b32_e32 v21, v23
	v_mul_f32_e32 v13, v22, v22
	v_pk_mul_f32 v[20:21], v[20:21], v[20:21]
	v_pk_mul_f32 v[26:27], v[80:81], v[8:9]
	v_pk_mul_f32 v[28:29], v[82:83], v[14:15]
	v_fmac_f32_e32 v13, v24, v24
	v_mov_b32_e32 v142, v28
	v_mov_b32_e32 v143, v26
	v_add_f32_e32 v13, v21, v13
	v_pk_mul_f32 v[142:143], v[142:143], v[142:143]
	v_add_f32_e32 v13, v20, v13
	v_mov_b32_e32 v144, v29
	v_mov_b32_e32 v145, v27
	v_add_f32_e32 v13, v143, v13
	v_pk_mul_f32 v[144:145], v[144:145], v[144:145]
	v_add_f32_e32 v13, v142, v13
	v_add_f32_e32 v13, v145, v13
	v_add_f32_e32 v13, v144, v13
	v_and_or_b32 v19, v19, s54, v146
	v_and_or_b32 v18, v18, s54, v139
	v_add_f32_dpp v13, v13, v13 quad_perm:[1,0,3,2] row_mask:0xf bank_mask:0xf bound_ctrl:1
	v_pk_mul_f32 v[16:17], v[16:17], v[68:69]
	v_pk_mul_f32 v[14:15], v[86:87], v[14:15]
	v_add_f32_dpp v13, v13, v13 quad_perm:[2,3,0,1] row_mask:0xf bank_mask:0xf bound_ctrl:1
	v_mul_f32_e32 v124, v163, v58
	v_mul_f32_e32 v125, v168, v60
	v_add_f32_dpp v13, v13, v13 row_half_mirror row_mask:0xf bank_mask:0xf bound_ctrl:1
	v_mul_f32_e32 v20, 0x4f800000, v13
	v_cmp_gt_f32_e32 vcc, s69, v13
	v_mul_f32_e32 v137, v169, v59
	v_mul_f32_e32 v156, v176, v82
	v_cndmask_b32_e32 v142, v13, v20, vcc
	v_sqrt_f32_e32 v143, v142
	v_pk_mul_f32 v[12:13], v[140:141], v[12:13] op_sel_hi:[1,0]
	v_mul_f32_e32 v157, v177, v81
	v_and_or_b32 v20, v12, s54, v147
	v_add_u32_e32 v12, -1, v143
	v_and_or_b32 v21, v13, s54, v148
	v_fma_f32 v13, -v12, v143, v142
	v_cmp_ge_f32_e64 s[0:1], 0, v13
	v_add_u32_e32 v13, 1, v143
	v_fma_f32 v140, -v13, v143, v142
	v_cndmask_b32_e64 v12, v143, v12, s[0:1]
	v_cmp_lt_f32_e64 s[0:1], 0, v140
	global_store_dwordx4 v[48:49], v[18:21], off
	v_mul_f32_e32 v158, v178, v83
	v_cndmask_b32_e64 v12, v12, v13, s[0:1]
	v_mul_f32_e32 v13, 0x37800000, v12
	v_cndmask_b32_e32 v12, v12, v13, vcc
	v_cmp_class_f32_e32 vcc, v142, v128
	s_nop 1
	v_cndmask_b32_e32 v12, v12, v142, vcc
	v_max_f32_e32 v12, 0x2b8cbccc, v12
	v_div_scale_f32 v13, s[0:1], v12, v12, 1.0
	v_rcp_f32_e32 v140, v13
	s_nop 0
	v_fma_f32 v18, -v13, v140, 1.0
	v_fmac_f32_e32 v140, v18, v140
	v_div_scale_f32 v18, vcc, 1.0, v12, 1.0
	v_mul_f32_e32 v19, v18, v140
	v_fma_f32 v20, -v13, v19, v18
	v_fmac_f32_e32 v19, v20, v140
	v_fma_f32 v13, -v13, v19, v18
	v_div_fmas_f32 v13, v13, v140, v19
	v_div_fixup_f32 v12, v13, v12, 1.0
	v_pk_mul_f32 v[20:21], v[26:27], v[12:13] op_sel_hi:[1,0]
	v_pk_mul_f32 v[18:19], v[22:23], v[12:13] op_sel_hi:[1,0]
	v_bfe_u32 v23, v20, 16, 1
	v_bfe_u32 v26, v21, 16, 1
	v_add3_u32 v21, v21, v26, s58
	v_add3_u32 v20, v20, v23, s58
	v_lshrrev_b32_e32 v27, 16, v20
	v_lshrrev_b32_e32 v139, 16, v21
	v_pk_mul_f32 v[20:21], v[10:11], v[70:71]
	v_bfe_u32 v22, v19, 16, 1
	v_mov_b32_e32 v10, v21
	v_mov_b32_e32 v11, v17
	v_mul_f32_e32 v140, v16, v16
	v_bfe_u32 v13, v18, 16, 1
	v_add3_u32 v19, v19, v22, s58
	v_pk_mul_f32 v[10:11], v[10:11], v[10:11]
	v_pk_mul_f32 v[22:23], v[84:85], v[8:9]
	v_fmac_f32_e32 v140, v20, v20
	v_add3_u32 v13, v18, v13, s58
	v_mov_b32_e32 v8, v14
	v_mov_b32_e32 v9, v22
	v_add_f32_e32 v11, v11, v140
	v_lshrrev_b32_e32 v13, 16, v13
	v_pk_mul_f32 v[8:9], v[8:9], v[8:9]
	v_add_f32_e32 v10, v10, v11
	v_lshrrev_b32_e32 v26, 16, v19
	v_pk_mul_f32 v[18:19], v[24:25], v[12:13] op_sel_hi:[1,0]
	v_mov_b32_e32 v24, v15
	v_mov_b32_e32 v25, v23
	v_add_f32_e32 v9, v9, v10
	v_pk_mul_f32 v[24:25], v[24:25], v[24:25]
	v_add_f32_e32 v8, v8, v9
	v_add_f32_e32 v8, v25, v8
	v_add_f32_e32 v8, v24, v8
	s_nop 1
	v_add_f32_dpp v8, v8, v8 quad_perm:[1,0,3,2] row_mask:0xf bank_mask:0xf bound_ctrl:1
	s_nop 1
	v_add_f32_dpp v8, v8, v8 quad_perm:[2,3,0,1] row_mask:0xf bank_mask:0xf bound_ctrl:1
	s_nop 1
	v_add_f32_dpp v8, v8, v8 row_half_mirror row_mask:0xf bank_mask:0xf bound_ctrl:1
	v_mul_f32_e32 v9, 0x4f800000, v8
	v_cmp_gt_f32_e32 vcc, s69, v8
	s_nop 1
	v_cndmask_b32_e32 v24, v8, v9, vcc
	v_sqrt_f32_e32 v25, v24
	v_pk_mul_f32 v[8:9], v[28:29], v[12:13] op_sel_hi:[1,0]
	s_nop 0
	v_and_or_b32 v10, v8, s54, v27
	v_add_u32_e32 v8, -1, v25
	v_and_or_b32 v11, v9, s54, v139
	v_fma_f32 v9, -v8, v25, v24
	v_cmp_ge_f32_e64 s[0:1], 0, v9
	v_add_u32_e32 v9, 1, v25
	v_fma_f32 v12, -v9, v25, v24
	v_cndmask_b32_e64 v8, v25, v8, s[0:1]
	v_cmp_lt_f32_e64 s[0:1], 0, v12
	v_mul_f32_e32 v139, v4, v30
	v_mul_f32_e32 v120, v139, v54
	v_cndmask_b32_e64 v8, v8, v9, s[0:1]
	v_mul_f32_e32 v9, 0x37800000, v8
	v_cndmask_b32_e32 v8, v8, v9, vcc
	v_cmp_class_f32_e32 vcc, v24, v128
	v_and_or_b32 v9, v19, s54, v26
	v_mul_f32_e32 v139, v110, v62
	v_cndmask_b32_e32 v8, v8, v24, vcc
	v_max_f32_e32 v12, 0x2b8cbccc, v8
	v_div_scale_f32 v24, s[0:1], v12, v12, 1.0
	v_rcp_f32_e32 v25, v24
	v_and_or_b32 v8, v18, s54, v13
	global_store_dwordx4 v[50:51], v[8:11], off
	s_nop 1
	v_fma_f32 v8, -v24, v25, 1.0
	v_fmac_f32_e32 v25, v8, v25
	v_div_scale_f32 v8, vcc, 1.0, v12, 1.0
	v_mul_f32_e32 v9, v8, v25
	v_fma_f32 v10, -v24, v9, v8
	v_fmac_f32_e32 v9, v10, v25
	v_fma_f32 v8, -v24, v9, v8
	v_div_fmas_f32 v8, v8, v25, v9
	v_div_fixup_f32 v8, v8, v12, 1.0
	v_pk_mul_f32 v[10:11], v[16:17], v[8:9] op_sel_hi:[1,0]
	v_pk_mul_f32 v[12:13], v[22:23], v[8:9] op_sel_hi:[1,0]
	v_bfe_u32 v9, v10, 16, 1
	v_bfe_u32 v16, v11, 16, 1
	v_bfe_u32 v17, v12, 16, 1
	v_bfe_u32 v18, v13, 16, 1
	v_add3_u32 v13, v13, v18, s58
	v_add3_u32 v12, v12, v17, s58
	v_add3_u32 v11, v11, v16, s58
	v_add3_u32 v9, v10, v9, s58
	v_lshrrev_b32_e32 v16, 16, v9
	v_lshrrev_b32_e32 v17, 16, v11
	v_lshrrev_b32_e32 v10, 16, v12
	v_lshrrev_b32_e32 v11, 16, v13
	v_pk_mul_f32 v[12:13], v[20:21], v[8:9] op_sel_hi:[1,0]
	v_pk_mul_f32 v[8:9], v[14:15], v[8:9] op_sel_hi:[1,0]
	v_lshlrev_b64 v[24:25], 11, v[90:91]
	v_and_or_b32 v11, v9, s54, v11
	v_and_or_b32 v10, v8, s54, v10
	v_and_or_b32 v9, v13, s54, v17
	v_and_or_b32 v8, v12, s54, v16
	global_store_dwordx4 v[52:53], v[8:11], off
	s_waitcnt lgkmcnt(0)
	s_barrier
	v_mov_b32_e32 v8, v65
	v_lshl_add_u64 v[24:25], s[52:53], 0, v[24:25]
	v_mbcnt_lo_u32_b32 v8, -1, v8
	v_mbcnt_hi_u32_b32 v10, -1, v8
	v_and_b32_e32 v20, 31, v10
	v_or_b32_e32 v8, v20, v136
	v_ashrrev_i32_e32 v9, 31, v8
	v_ashrrev_i32_e32 v10, 2, v10
	v_lshlrev_b64 v[8:9], 8, v[8:9]
	v_and_b32_e32 v12, -8, v10
	v_lshl_add_u64 v[8:9], s[52:53], 0, v[8:9]
	v_ashrrev_i32_e32 v13, 31, v12
	v_lshl_add_u64 v[14:15], v[12:13], 1, v[8:9]
	v_add_co_u32_e32 v8, vcc, s70, v14
	v_lshl_add_u64 v[166:167], v[14:15], 0, s[46:47]
	s_nop 0
	v_addc_co_u32_e32 v9, vcc, 0, v15, vcc
	v_add_co_u32_e32 v164, vcc, s71, v14
	global_load_dwordx4 v[8:11], v[8:9], off
	s_nop 0
	v_addc_co_u32_e32 v165, vcc, 0, v15, vcc
	global_load_dwordx4 v[16:19], v[164:165], off
	global_load_dwordx4 v[140:143], v[166:167], off offset:32
	global_load_dwordx4 v[144:147], v[164:165], off offset:32
	global_load_dwordx4 v[148:151], v[166:167], off offset:64
	global_load_dwordx4 v[98:101], v[166:167], off offset:96
	global_load_dwordx4 v[152:155], v[164:165], off offset:64
	global_load_dwordx4 v[102:105], v[164:165], off offset:96
	v_lshlrev_b32_e32 v0, 1, v12
	v_mad_u32_u24 v191, v20, s63, v0
	ds_read_b128 v[20:23], v191
	ds_read_b128 v[106:109], v191 offset:32
	v_lshrrev_b32_e32 v0, 3, v135
	v_and_b32_e32 v0, 4, v0
	v_mul_u32_u24_e32 v0, 0x410, v0
	v_lshl_add_u64 v[114:115], v[24:25], 0, v[34:35]
	v_lshlrev_b64 v[24:25], 11, v[92:93]
	v_lshl_add_u32 v192, v1, 2, v0
	v_mul_lo_u32 v0, v138, s68
	v_lshl_add_u64 v[24:25], s[52:53], 0, v[24:25]
	v_add_u32_e32 v118, v64, v0
	s_waitcnt vmcnt(0) lgkmcnt(0)
	v_mfma_f32_32x32x16_bf16 v[0:15], v[20:23], v[8:11], 0
	v_lshl_add_u64 v[116:117], v[24:25], 0, v[34:35]
	ds_read_b128 v[34:37], v191 offset:64
	v_mul_f32_e32 v138, v170, v61
	v_mfma_f32_32x32x16_bf16 v[16:31], v[20:23], v[16:19], 0
	v_mfma_f32_32x32x16_bf16 v[0:15], v[106:109], v[140:143], v[0:15]
	v_mul_f32_e32 v140, v112, v66
	v_mul_f32_e32 v141, v111, v63
	v_mul_f32_e32 v142, v113, v67
	v_mul_f32_e32 v143, v179, v68
	v_mfma_f32_32x32x16_bf16 v[16:31], v[106:109], v[144:147], v[16:31]
	ds_read_b128 v[106:109], v191 offset:96
	v_mul_f32_e32 v144, v184, v70
	v_mul_f32_e32 v145, v185, v69
	v_mul_f32_e32 v146, v186, v71
	v_mul_f32_e32 v147, v159, v72
	v_mul_f32_e32 v159, v187, v84
	s_waitcnt lgkmcnt(1)
	v_mfma_f32_32x32x16_bf16 v[0:15], v[34:37], v[148:151], v[0:15]
	v_mul_f32_e32 v148, v160, v74
	v_mul_f32_e32 v149, v161, v73
	v_mul_f32_e32 v150, v162, v75
	v_mul_f32_e32 v151, v171, v76
	v_mul_f32_e32 v160, v188, v86
	v_mul_f32_e32 v161, v189, v85
	v_mul_f32_e32 v162, v190, v87
	v_mfma_f32_32x32x16_bf16 v[16:31], v[34:37], v[152:155], v[16:31]
	v_mul_f32_e32 v152, v172, v78
	v_mul_f32_e32 v153, v173, v77
	v_mul_f32_e32 v154, v174, v79
	v_mul_f32_e32 v155, v175, v80
	s_waitcnt lgkmcnt(0)
	v_mfma_f32_32x32x16_bf16 v[0:15], v[106:109], v[98:101], v[0:15]
	v_mfma_f32_32x32x16_bf16 v[16:31], v[106:109], v[102:105], v[16:31]
	global_load_dwordx4 v[34:37], v[166:167], off offset:128
	global_load_dwordx4 v[98:101], v[164:165], off offset:128
	ds_read_b128 v[102:105], v191 offset:128
	ds_read_b128 v[110:113], v191 offset:160
	global_load_dwordx4 v[106:109], v[166:167], off offset:160
	s_waitcnt vmcnt(0) lgkmcnt(0)
	v_mfma_f32_32x32x16_bf16 v[0:15], v[102:105], v[34:37], v[0:15]
	global_load_dwordx4 v[34:37], v[164:165], off offset:160
	v_mfma_f32_32x32x16_bf16 v[16:31], v[102:105], v[98:101], v[16:31]
	global_load_dwordx4 v[98:101], v[166:167], off offset:192
	global_load_dwordx4 v[102:105], v[164:165], off offset:192
	v_mfma_f32_32x32x16_bf16 v[0:15], v[110:113], v[106:109], v[0:15]
	ds_read_b128 v[106:109], v191 offset:192
	s_waitcnt vmcnt(0) lgkmcnt(0)
	v_mfma_f32_32x32x16_bf16 v[16:31], v[110:113], v[34:37], v[16:31]
	global_load_dwordx4 v[34:37], v[166:167], off offset:224
	ds_read_b128 v[110:113], v191 offset:224
	v_mfma_f32_32x32x16_bf16 v[0:15], v[106:109], v[98:101], v[0:15]
	global_load_dwordx4 v[98:101], v[164:165], off offset:224
	v_mfma_f32_32x32x16_bf16 v[16:31], v[106:109], v[102:105], v[16:31]
	s_waitcnt vmcnt(0) lgkmcnt(0)
	v_mfma_f32_32x32x16_bf16 v[0:15], v[110:113], v[34:37], v[0:15]
	v_mfma_f32_32x32x16_bf16 v[16:31], v[110:113], v[98:101], v[16:31]
	v_add_u32_e32 v163, 0x6000, v192
	v_add_u32_e32 v164, 0x6400, v192
	v_add_u32_e32 v165, 0x6800, v192
	v_add_u32_e32 v166, 0x6c00, v192
	v_add_u32_e32 v167, 0x8000, v192
	v_add_u32_e32 v168, 0x8400, v192
	v_add_u32_e32 v169, 0x8800, v192
	v_add_u32_e32 v170, 0x8c00, v192
	v_add_u32_e32 v171, 0xa000, v192
	v_add_u32_e32 v172, 0xa400, v192
	v_add_u32_e32 v173, 0xa800, v192
	v_add_u32_e32 v174, 0xac00, v192
	v_add_u32_e32 v175, 0xc200, v192
	v_add_u32_e32 v176, 0xc600, v192
	v_add_u32_e32 v177, 0xca00, v192
	v_add_u32_e32 v178, 0xce00, v192
	ds_write2_b32 v163, v0, v16 offset0:128 offset1:160
	ds_write2_b32 v164, v1, v17 offset0:132 offset1:164
	ds_write2_b32 v165, v2, v18 offset0:136 offset1:168
	ds_write2_b32 v166, v3, v19 offset0:140 offset1:172
	ds_write2_b32 v167, v4, v20 offset0:160 offset1:192
	ds_write2_b32 v168, v5, v21 offset0:164 offset1:196
	ds_write2_b32 v169, v6, v22 offset0:168 offset1:200
	ds_write2_b32 v170, v7, v23 offset0:172 offset1:204
	ds_write2_b32 v171, v8, v24 offset0:192 offset1:224
	ds_write2_b32 v172, v9, v25 offset0:196 offset1:228
	ds_write2_b32 v173, v10, v26 offset0:200 offset1:232
	ds_write2_b32 v174, v11, v27 offset0:204 offset1:236
	ds_write2_b32 v175, v12, v28 offset0:96 offset1:128
	ds_write2_b32 v176, v13, v29 offset0:100 offset1:132
	ds_write2_b32 v177, v14, v30 offset0:104 offset1:136
	ds_write2_b32 v178, v15, v31 offset0:108 offset1:140
	s_waitcnt lgkmcnt(0)
	s_barrier
	ds_read_b128 v[0:3], v118 offset:25088
	ds_read_b128 v[4:7], v118 offset:25104
	s_add_u32 s77, s52, 0x1b0d7900
	s_addc_u32 s78, s53, 0
	s_add_u32 s79, s52, 0x1d4d7900
	s_waitcnt lgkmcnt(1)
	v_and_b32_sdwa v8, v2, v134 dst_sel:DWORD dst_unused:UNUSED_PAD src0_sel:WORD_1 src1_sel:DWORD
	v_and_b32_sdwa v9, v0, v134 dst_sel:DWORD dst_unused:UNUSED_PAD src0_sel:WORD_1 src1_sel:DWORD
	v_add3_u32 v2, v2, v8, s58
	v_and_b32_sdwa v8, v3, v134 dst_sel:DWORD dst_unused:UNUSED_PAD src0_sel:WORD_1 src1_sel:DWORD
	v_add3_u32 v0, v0, v9, s58
	v_and_b32_sdwa v9, v1, v134 dst_sel:DWORD dst_unused:UNUSED_PAD src0_sel:WORD_1 src1_sel:DWORD
	v_add3_u32 v3, v3, v8, s58
	v_add3_u32 v1, v1, v9, s58
	v_and_b32_e32 v3, 0xffff0000, v3
	v_and_b32_e32 v8, 0xffff0000, v1
	v_or_b32_sdwa v1, v3, v2 dst_sel:DWORD dst_unused:UNUSED_PAD src0_sel:DWORD src1_sel:WORD_1
	s_waitcnt lgkmcnt(0)
	v_and_b32_sdwa v2, v6, v134 dst_sel:DWORD dst_unused:UNUSED_PAD src0_sel:WORD_1 src1_sel:DWORD
	v_and_b32_sdwa v3, v4, v134 dst_sel:DWORD dst_unused:UNUSED_PAD src0_sel:WORD_1 src1_sel:DWORD
	v_add3_u32 v4, v4, v3, s58
	v_add3_u32 v2, v6, v2, s58
	v_and_b32_sdwa v3, v7, v134 dst_sel:DWORD dst_unused:UNUSED_PAD src0_sel:WORD_1 src1_sel:DWORD
	v_and_b32_sdwa v6, v5, v134 dst_sel:DWORD dst_unused:UNUSED_PAD src0_sel:WORD_1 src1_sel:DWORD
	v_add3_u32 v3, v7, v3, s58
	v_add3_u32 v5, v5, v6, s58
	v_and_b32_e32 v3, 0xffff0000, v3
	v_and_b32_e32 v5, 0xffff0000, v5
	v_or_b32_sdwa v3, v3, v2 dst_sel:DWORD dst_unused:UNUSED_PAD src0_sel:DWORD src1_sel:WORD_1
	v_or_b32_sdwa v2, v5, v4 dst_sel:DWORD dst_unused:UNUSED_PAD src0_sel:DWORD src1_sel:WORD_1
	v_add_co_u32_e32 v4, vcc, s72, v114
	v_or_b32_sdwa v0, v8, v0 dst_sel:DWORD dst_unused:UNUSED_PAD src0_sel:DWORD src1_sel:WORD_1
	s_nop 0
	v_addc_co_u32_e32 v5, vcc, 0, v115, vcc
	global_store_dwordx4 v[4:5], v[0:3], off offset:2816
	ds_read_b128 v[0:3], v118 offset:26128
	ds_read_b128 v[4:7], v118 offset:26144
	s_addc_u32 s80, s53, 0
	s_add_u32 s81, s52, 0x1738000
	s_addc_u32 s82, s53, 0
	s_waitcnt lgkmcnt(0)
	v_and_b32_sdwa v8, v2, v134 dst_sel:DWORD dst_unused:UNUSED_PAD src0_sel:WORD_1 src1_sel:DWORD
	v_and_b32_sdwa v9, v0, v134 dst_sel:DWORD dst_unused:UNUSED_PAD src0_sel:WORD_1 src1_sel:DWORD
	v_add3_u32 v2, v2, v8, s58
	v_and_b32_sdwa v8, v3, v134 dst_sel:DWORD dst_unused:UNUSED_PAD src0_sel:WORD_1 src1_sel:DWORD
	v_add3_u32 v0, v0, v9, s58
	v_and_b32_sdwa v9, v1, v134 dst_sel:DWORD dst_unused:UNUSED_PAD src0_sel:WORD_1 src1_sel:DWORD
	v_add3_u32 v3, v3, v8, s58
	v_add3_u32 v1, v1, v9, s58
	v_and_b32_e32 v3, 0xffff0000, v3
	v_and_b32_e32 v8, 0xffff0000, v1
	v_or_b32_sdwa v1, v3, v2 dst_sel:DWORD dst_unused:UNUSED_PAD src0_sel:DWORD src1_sel:WORD_1
	v_and_b32_sdwa v2, v6, v134 dst_sel:DWORD dst_unused:UNUSED_PAD src0_sel:WORD_1 src1_sel:DWORD
	v_and_b32_sdwa v3, v4, v134 dst_sel:DWORD dst_unused:UNUSED_PAD src0_sel:WORD_1 src1_sel:DWORD
	v_add3_u32 v4, v4, v3, s58
	v_add3_u32 v2, v6, v2, s58
	v_and_b32_sdwa v3, v7, v134 dst_sel:DWORD dst_unused:UNUSED_PAD src0_sel:WORD_1 src1_sel:DWORD
	v_and_b32_sdwa v6, v5, v134 dst_sel:DWORD dst_unused:UNUSED_PAD src0_sel:WORD_1 src1_sel:DWORD
	v_add3_u32 v3, v7, v3, s58
	v_add3_u32 v5, v5, v6, s58
	v_and_b32_e32 v3, 0xffff0000, v3
	v_and_b32_e32 v5, 0xffff0000, v5
	v_or_b32_sdwa v3, v3, v2 dst_sel:DWORD dst_unused:UNUSED_PAD src0_sel:DWORD src1_sel:WORD_1
	v_or_b32_sdwa v2, v5, v4 dst_sel:DWORD dst_unused:UNUSED_PAD src0_sel:DWORD src1_sel:WORD_1
	v_add_co_u32_e32 v4, vcc, s72, v116
	v_or_b32_sdwa v0, v8, v0 dst_sel:DWORD dst_unused:UNUSED_PAD src0_sel:DWORD src1_sel:WORD_1
	s_nop 0
	v_addc_co_u32_e32 v5, vcc, 0, v117, vcc
	global_store_dwordx4 v[4:5], v[0:3], off offset:2816
	ds_read_b128 v[0:3], v118 offset:27168
	ds_read_b128 v[4:7], v118 offset:27184
	v_lshl_add_u64 v[88:89], v[88:89], 0, s[48:49]
	s_mov_b64 s[8:9], -1
	s_waitcnt lgkmcnt(0)
	v_and_b32_sdwa v8, v2, v134 dst_sel:DWORD dst_unused:UNUSED_PAD src0_sel:WORD_1 src1_sel:DWORD
	v_and_b32_sdwa v9, v0, v134 dst_sel:DWORD dst_unused:UNUSED_PAD src0_sel:WORD_1 src1_sel:DWORD
	v_add3_u32 v2, v2, v8, s58
	v_and_b32_sdwa v8, v3, v134 dst_sel:DWORD dst_unused:UNUSED_PAD src0_sel:WORD_1 src1_sel:DWORD
	v_add3_u32 v0, v0, v9, s58
	v_and_b32_sdwa v9, v1, v134 dst_sel:DWORD dst_unused:UNUSED_PAD src0_sel:WORD_1 src1_sel:DWORD
	v_add3_u32 v3, v3, v8, s58
	v_add3_u32 v1, v1, v9, s58
	v_and_b32_e32 v3, 0xffff0000, v3
	v_and_b32_e32 v8, 0xffff0000, v1
	v_or_b32_sdwa v1, v3, v2 dst_sel:DWORD dst_unused:UNUSED_PAD src0_sel:DWORD src1_sel:WORD_1
	v_and_b32_sdwa v2, v6, v134 dst_sel:DWORD dst_unused:UNUSED_PAD src0_sel:WORD_1 src1_sel:DWORD
	v_and_b32_sdwa v3, v4, v134 dst_sel:DWORD dst_unused:UNUSED_PAD src0_sel:WORD_1 src1_sel:DWORD
	v_add3_u32 v4, v4, v3, s58
	v_add3_u32 v2, v6, v2, s58
	v_and_b32_sdwa v3, v7, v134 dst_sel:DWORD dst_unused:UNUSED_PAD src0_sel:WORD_1 src1_sel:DWORD
	v_and_b32_sdwa v6, v5, v134 dst_sel:DWORD dst_unused:UNUSED_PAD src0_sel:WORD_1 src1_sel:DWORD
	v_add3_u32 v3, v7, v3, s58
	v_add3_u32 v5, v5, v6, s58
	v_and_b32_e32 v3, 0xffff0000, v3
	v_and_b32_e32 v5, 0xffff0000, v5
	v_or_b32_sdwa v3, v3, v2 dst_sel:DWORD dst_unused:UNUSED_PAD src0_sel:DWORD src1_sel:WORD_1
	v_or_b32_sdwa v2, v5, v4 dst_sel:DWORD dst_unused:UNUSED_PAD src0_sel:DWORD src1_sel:WORD_1
	v_add_co_u32_e32 v4, vcc, s72, v180
	v_or_b32_sdwa v0, v8, v0 dst_sel:DWORD dst_unused:UNUSED_PAD src0_sel:DWORD src1_sel:WORD_1
	s_nop 0
	v_addc_co_u32_e32 v5, vcc, 0, v181, vcc
	global_store_dwordx4 v[4:5], v[0:3], off offset:2816
	ds_read_b128 v[0:3], v119 offset:25088
	ds_read_b128 v[4:7], v119 offset:25104
	s_waitcnt lgkmcnt(0)
	v_and_b32_sdwa v8, v2, v134 dst_sel:DWORD dst_unused:UNUSED_PAD src0_sel:WORD_1 src1_sel:DWORD
	v_and_b32_sdwa v9, v0, v134 dst_sel:DWORD dst_unused:UNUSED_PAD src0_sel:WORD_1 src1_sel:DWORD
	v_add3_u32 v2, v2, v8, s58
	v_and_b32_sdwa v8, v3, v134 dst_sel:DWORD dst_unused:UNUSED_PAD src0_sel:WORD_1 src1_sel:DWORD
	v_add3_u32 v0, v0, v9, s58
	v_and_b32_sdwa v9, v1, v134 dst_sel:DWORD dst_unused:UNUSED_PAD src0_sel:WORD_1 src1_sel:DWORD
	v_add3_u32 v3, v3, v8, s58
	v_add3_u32 v1, v1, v9, s58
	v_and_b32_e32 v3, 0xffff0000, v3
	v_and_b32_e32 v8, 0xffff0000, v1
	v_or_b32_sdwa v1, v3, v2 dst_sel:DWORD dst_unused:UNUSED_PAD src0_sel:DWORD src1_sel:WORD_1
	v_and_b32_sdwa v2, v6, v134 dst_sel:DWORD dst_unused:UNUSED_PAD src0_sel:WORD_1 src1_sel:DWORD
	v_and_b32_sdwa v3, v4, v134 dst_sel:DWORD dst_unused:UNUSED_PAD src0_sel:WORD_1 src1_sel:DWORD
	v_add3_u32 v4, v4, v3, s58
	v_add3_u32 v2, v6, v2, s58
	v_and_b32_sdwa v3, v7, v134 dst_sel:DWORD dst_unused:UNUSED_PAD src0_sel:WORD_1 src1_sel:DWORD
	v_and_b32_sdwa v6, v5, v134 dst_sel:DWORD dst_unused:UNUSED_PAD src0_sel:WORD_1 src1_sel:DWORD
	v_add3_u32 v3, v7, v3, s58
	v_add3_u32 v5, v5, v6, s58
	v_and_b32_e32 v3, 0xffff0000, v3
	v_and_b32_e32 v5, 0xffff0000, v5
	v_or_b32_sdwa v3, v3, v2 dst_sel:DWORD dst_unused:UNUSED_PAD src0_sel:DWORD src1_sel:WORD_1
	v_or_b32_sdwa v2, v5, v4 dst_sel:DWORD dst_unused:UNUSED_PAD src0_sel:DWORD src1_sel:WORD_1
	v_add_co_u32_e32 v4, vcc, s72, v182
	v_or_b32_sdwa v0, v8, v0 dst_sel:DWORD dst_unused:UNUSED_PAD src0_sel:DWORD src1_sel:WORD_1
	s_nop 0
	v_addc_co_u32_e32 v5, vcc, 0, v183, vcc
	global_store_dwordx4 v[4:5], v[0:3], off offset:2816
	s_waitcnt lgkmcnt(0)
	s_barrier
	global_load_dwordx2 v[0:1], v[32:33], off offset:456
	v_and_b32_e32 v8, 7, v135
	v_lshlrev_b64 v[2:3], 8, v[92:93]
	v_lshlrev_b64 v[4:5], 8, v[94:95]
	v_lshlrev_b64 v[6:7], 8, v[96:97]
	v_cmp_eq_u32_e64 s[4:5], 0, v8
	v_or_b32_e32 v2, v2, v126
	v_or_b32_e32 v4, v4, v126
	v_or_b32_e32 v6, v6, v126
	v_lshlrev_b64 v[92:93], 4, v[92:93]
	v_lshlrev_b64 v[94:95], 4, v[94:95]
	v_lshlrev_b64 v[96:97], 4, v[96:97]
	v_lshlrev_b64 v[104:105], 1, v[2:3]
	v_lshlrev_b64 v[106:107], 1, v[4:5]
	v_lshlrev_b64 v[108:109], 1, v[6:7]
	s_waitcnt vmcnt(0) lgkmcnt(0)
	v_readfirstlane_b32 s1, v1
	v_readfirstlane_b32 s0, v0
	s_nop 1
	v_lshl_add_u64 v[0:1], s[0:1], 0, v[64:65]
	global_load_dwordx4 v[30:33], v[0:1], off
	global_load_dwordx4 v[34:37], v[0:1], off offset:16
	s_add_u32 s0, s52, 0x2954198
	s_addc_u32 s1, s53, 0
	s_add_u32 s83, s52, 0x1748000
	v_lshlrev_b64 v[0:1], 8, v[90:91]
	s_addc_u32 s84, s53, 0
	v_bfe_u32 v64, v135, 1, 4
	v_or_b32_e32 v0, v0, v126
	s_add_u32 s6, s52, 0x29541a8
	v_lshl_add_u64 v[8:9], s[52:53], 0, v[64:65]
	v_lshlrev_b64 v[90:91], 4, v[90:91]
	s_addc_u32 s7, s53, 0
	v_lshl_add_u64 v[98:99], v[8:9], 0, s[50:51]
	v_lshlrev_b32_e32 v64, 2, v126
	s_waitcnt vmcnt(0) lgkmcnt(0)
	v_mov_b32_e32 v100, v30
	v_mov_b32_e32 v101, v32
	v_mov_b32_e32 v32, v31
	v_mov_b32_e32 v102, v34
	v_mov_b32_e32 v103, v36
	v_mov_b32_e32 v36, v35
	v_lshlrev_b64 v[34:35], 1, v[0:1]
	s_branch .LBB0_426

.LBB0_1406:
	v_add_u32_e32 v4, s82, v135
	v_mul_hi_i32 v2, v4, s66
	v_lshrrev_b32_e32 v3, 31, v2
	v_ashrrev_i32_e32 v2, 3, v2
	v_add_u32_e32 v5, v2, v3
	v_mad_u64_u32 v[20:21], s[0:1], v5, s68, v[0:1]
	v_add_u32_e32 v6, s26, v5
	v_mov_b64_e32 v[2:3], s[54:55]
	v_add_u32_e32 v8, s81, v5
	v_mad_i64_i32 v[6:7], s[0:1], v6, s34, v[2:3]
	v_ashrrev_i32_e32 v21, 31, v20
	v_mad_u64_u32 v[18:19], s[0:1], v5, s67, v[4:5]
	v_lshl_add_u64 v[6:7], v[20:21], 1, v[6:7]
	v_cmp_lt_i32_e32 vcc, s27, v8
	v_lshl_add_u64 v[14:15], v[6:7], 0, s[22:23]
	v_add_co_u32_e64 v6, s[0:1], s69, v6
	v_cndmask_b32_e64 v11, 0, -1, vcc
	v_cndmask_b32_e32 v10, 0, v132, vcc
	v_cmp_gt_i32_e64 s[6:7], s80, v8
	v_addc_co_u32_e64 v7, s[0:1], 0, v7, s[0:1]
	v_lshl_add_u64 v[10:11], v[14:15], 0, v[10:11]
	global_load_dwordx4 v[6:9], v[6:7], off offset:1792
	v_cndmask_b32_e64 v64, 0, v133, s[6:7]
	global_load_dwordx4 v[10:13], v[10:11], off
	v_lshl_add_u64 v[14:15], v[14:15], 0, v[64:65]
	global_load_dwordx4 v[14:17], v[14:15], off
	v_lshlrev_b64 v[208:209], 2, v[20:21]
	v_lshl_add_u64 v[210:211], s[12:13], 0, v[208:209]
	v_lshl_add_u64 v[212:213], s[24:25], 0, v[208:209]
	global_load_dwordx4 v[216:219], v[210:211], off offset:0
	global_load_dwordx4 v[220:223], v[212:213], off offset:0
	global_load_dwordx4 v[224:227], v[210:211], off offset:16
	global_load_dwordx4 v[228:231], v[212:213], off offset:16
	v_cmp_gt_i32_e64 s[4:5], 32, v18
	v_cmp_gt_i32_e64 s[0:1], 16, v18
	v_lshl_add_u32 v5, v5, 4, v1
	v_add_u32_e32 v4, 0x100, v4
	s_addk_i32 s82, 0x200
	s_cmpk_eq_i32 s82, 0x600
	s_waitcnt vmcnt(0) lgkmcnt(0)
	v_lshlrev_b32_e32 v31, 16, v7
	v_and_b32_e32 v7, 0xffff0000, v7
	v_lshlrev_b32_e32 v26, 16, v12
	v_and_b32_e32 v27, 0xffff0000, v12
	v_lshlrev_b32_e32 v29, 16, v13
	v_and_b32_e32 v30, 0xffff0000, v13
	v_lshlrev_b64 v[12:13], 2, v[20:21]
	v_and_b32_e32 v19, 0xffff0000, v10
	v_lshlrev_b32_e32 v25, 16, v11
	v_and_b32_e32 v11, 0xffff0000, v11
	v_lshl_add_u64 v[20:21], s[12:13], 0, v[12:13]
	v_lshlrev_b32_e32 v10, 16, v10
	v_lshlrev_b32_e32 v32, 16, v14
	v_lshlrev_b32_e32 v33, 16, v15
	v_and_b32_e32 v36, 0xffff0000, v15
	v_and_b32_e32 v37, 0xffff0000, v14
	v_lshlrev_b32_e32 v38, 16, v16
	v_lshlrev_b32_e32 v39, 16, v17
	v_and_b32_e32 v40, 0xffff0000, v17
	v_and_b32_e32 v41, 0xffff0000, v16
	v_lshl_add_u64 v[22:23], s[24:25], 0, v[12:13]
	v_cndmask_b32_e32 v18, 0, v10, vcc
	v_cndmask_b32_e32 v24, 0, v19, vcc
	v_cndmask_b32_e32 v19, 0, v25, vcc
	v_cndmask_b32_e32 v25, 0, v11, vcc
	v_cndmask_b32_e32 v28, 0, v27, vcc
	v_cndmask_b32_e32 v27, 0, v29, vcc
	v_cndmask_b32_e32 v29, 0, v30, vcc
	v_lshlrev_b32_e32 v30, 16, v6
	v_cndmask_b32_e64 v33, 0, v33, s[6:7]
	v_cndmask_b32_e64 v32, 0, v32, s[6:7]
	v_pk_add_f32 v[18:19], v[18:19], v[30:31] neg_lo:[0,1] neg_hi:[0,1]
	v_and_b32_e32 v6, 0xffff0000, v6
	v_pk_add_f32 v[24:25], v[24:25], v[6:7] neg_lo:[0,1] neg_hi:[0,1]
	v_cndmask_b32_e32 v26, 0, v26, vcc
	s_waitcnt vmcnt(0) lgkmcnt(0)
	v_mov_b64_e32 v[10:11], v[216:217]
	v_mov_b64_e32 v[12:13], v[218:219]
	v_mov_b64_e32 v[14:15], v[220:221]
	v_mov_b64_e32 v[16:17], v[222:223]
	v_mov_b32_e32 v34, v10
	v_mov_b32_e32 v35, v12
	v_pk_fma_f32 v[18:19], v[34:35], v[18:19], v[30:31]
	v_pk_add_f32 v[30:31], v[32:33], v[30:31] neg_lo:[0,1] neg_hi:[0,1]
	v_mov_b32_e32 v32, v14
	v_mov_b32_e32 v33, v16
	v_pk_fma_f32 v[18:19], v[30:31], v[32:33], v[18:19]
	v_cndmask_b32_e64 v31, 0, v36, s[6:7]
	v_cndmask_b32_e64 v30, 0, v37, s[6:7]
	v_mov_b32_e32 v12, v11
	v_pk_fma_f32 v[12:13], v[12:13], v[24:25], v[6:7]
	v_pk_add_f32 v[6:7], v[30:31], v[6:7] neg_lo:[0,1] neg_hi:[0,1]
	v_mov_b32_e32 v16, v15
	v_pk_fma_f32 v[6:7], v[6:7], v[16:17], v[12:13]
	v_add_f32_e32 v10, v18, v18
	v_add_f32_e32 v11, v6, v6
	v_cndmask_b32_e64 v11, v11, v6, s[0:1]
	v_mul_f32_e32 v11, 0xbfb8aa3b, v11
	v_exp_f32_e32 v12, v11
	v_add_f32_e32 v11, v19, v19
	v_cndmask_b32_e64 v10, v10, v18, s[0:1]
	v_cndmask_b32_e64 v11, v11, v19, s[0:1]
	v_mul_f32_e32 v10, 0xbfb8aa3b, v10
	v_mul_f32_e32 v11, 0xbfb8aa3b, v11
	v_exp_f32_e32 v10, v10
	v_exp_f32_e32 v11, v11
	s_nop 0
	v_pk_add_f32 v[10:11], v[10:11], 1.0 op_sel_hi:[1,0]
	s_nop 0
	v_div_scale_f32 v13, s[84:85], v11, v11, 1.0
	v_rcp_f32_e32 v14, v13
	s_nop 0
	v_fma_f32 v15, -v13, v14, 1.0
	v_fmac_f32_e32 v14, v15, v14
	v_div_scale_f32 v15, vcc, 1.0, v11, 1.0
	v_mul_f32_e32 v16, v15, v14
	v_fma_f32 v17, -v13, v16, v15
	v_fmac_f32_e32 v16, v17, v14
	v_fma_f32 v13, -v13, v16, v15
	v_div_fmas_f32 v13, v13, v14, v16
	v_div_fixup_f32 v11, v13, v11, 1.0
	v_div_scale_f32 v13, s[84:85], v10, v10, 1.0
	v_rcp_f32_e32 v14, v13
	s_nop 0
	v_fma_f32 v15, -v13, v14, 1.0
	v_fmac_f32_e32 v14, v15, v14
	v_div_scale_f32 v15, vcc, 1.0, v10, 1.0
	v_mul_f32_e32 v16, v15, v14
	v_fma_f32 v17, -v13, v16, v15
	v_fmac_f32_e32 v16, v17, v14
	v_fma_f32 v13, -v13, v16, v15
	v_div_fmas_f32 v13, v13, v14, v16
	v_div_fixup_f32 v10, v13, v10, 1.0
	v_pk_fma_f32 v[14:15], v[10:11], 2.0, -1.0 op_sel_hi:[1,0,0]
	v_and_b32_e32 v17, 0xffff0000, v9
	v_cndmask_b32_e64 v13, v18, v14, s[4:5]
	v_cndmask_b32_e64 v25, v13, v10, s[0:1]
	v_add_f32_e32 v10, v7, v7
	v_cndmask_b32_e64 v10, v10, v7, s[0:1]
	v_mul_f32_e32 v10, 0xbfb8aa3b, v10
	v_exp_f32_e32 v13, v10
	v_cndmask_b32_e64 v14, v19, v15, s[4:5]
	v_cndmask_b32_e64 v24, v14, v11, s[0:1]
	v_cndmask_b32_e64 v19, 0, v39, s[6:7]
	v_pk_add_f32 v[10:11], v[12:13], 1.0 op_sel_hi:[1,0]
	v_cndmask_b32_e64 v18, 0, v38, s[6:7]
	v_div_scale_f32 v12, s[84:85], v11, v11, 1.0
	v_rcp_f32_e32 v13, v12
	s_nop 0
	v_fma_f32 v14, -v12, v13, 1.0
	v_fmac_f32_e32 v13, v14, v13
	v_div_scale_f32 v14, vcc, 1.0, v11, 1.0
	v_mul_f32_e32 v15, v14, v13
	v_fma_f32 v16, -v12, v15, v14
	v_fmac_f32_e32 v15, v16, v13
	v_fma_f32 v12, -v12, v15, v14
	v_div_fmas_f32 v12, v12, v13, v15
	v_div_fixup_f32 v11, v12, v11, 1.0
	v_div_scale_f32 v12, s[84:85], v10, v10, 1.0
	v_rcp_f32_e32 v13, v12
	s_nop 0
	v_fma_f32 v14, -v12, v13, 1.0
	v_fmac_f32_e32 v13, v14, v13
	v_div_scale_f32 v14, vcc, 1.0, v10, 1.0
	v_mul_f32_e32 v15, v14, v13
	v_fma_f32 v16, -v12, v15, v14
	v_fmac_f32_e32 v15, v16, v13
	v_fma_f32 v12, -v12, v15, v14
	v_div_fmas_f32 v12, v12, v13, v15
	v_div_fixup_f32 v10, v12, v10, 1.0
	v_pk_fma_f32 v[12:13], v[10:11], 2.0, -1.0 op_sel_hi:[1,0,0]
	v_lshlrev_b32_e32 v15, 16, v9
	v_cndmask_b32_e64 v7, v7, v13, s[4:5]
	v_cndmask_b32_e64 v6, v6, v12, s[4:5]
	v_cndmask_b32_e64 v30, v6, v10, s[0:1]
	v_cndmask_b32_e64 v31, v7, v11, s[0:1]
	v_lshlrev_b32_e32 v14, 16, v8
	v_and_b32_e32 v16, 0xffff0000, v8
	v_pk_add_f32 v[20:21], v[26:27], v[14:15] neg_lo:[0,1] neg_hi:[0,1]
	s_waitcnt vmcnt(0) lgkmcnt(0)
	v_mov_b64_e32 v[6:7], v[224:225]
	v_mov_b64_e32 v[8:9], v[226:227]
	v_mov_b64_e32 v[10:11], v[228:229]
	v_mov_b64_e32 v[12:13], v[230:231]
	v_mov_b32_e32 v22, v6
	v_mov_b32_e32 v23, v8
	v_pk_fma_f32 v[20:21], v[20:21], v[22:23], v[14:15]
	v_pk_add_f32 v[14:15], v[18:19], v[14:15] neg_lo:[0,1] neg_hi:[0,1]
	v_mov_b32_e32 v18, v10
	v_mov_b32_e32 v19, v12
	v_pk_fma_f32 v[14:15], v[14:15], v[18:19], v[20:21]
	v_cndmask_b32_e64 v19, 0, v40, s[6:7]
	v_cndmask_b32_e64 v18, 0, v41, s[6:7]
	v_pk_add_f32 v[20:21], v[28:29], v[16:17] neg_lo:[0,1] neg_hi:[0,1]
	v_mov_b32_e32 v8, v7
	v_pk_fma_f32 v[8:9], v[20:21], v[8:9], v[16:17]
	v_pk_add_f32 v[16:17], v[18:19], v[16:17] neg_lo:[0,1] neg_hi:[0,1]
	v_mov_b32_e32 v12, v11
	v_pk_fma_f32 v[8:9], v[16:17], v[12:13], v[8:9]
	v_add_f32_e32 v6, v14, v14
	v_add_f32_e32 v7, v8, v8
	v_cndmask_b32_e64 v7, v7, v8, s[0:1]
	v_mul_f32_e32 v7, 0xbfb8aa3b, v7
	v_exp_f32_e32 v10, v7
	v_add_f32_e32 v7, v15, v15
	v_cndmask_b32_e64 v6, v6, v14, s[0:1]
	v_cndmask_b32_e64 v7, v7, v15, s[0:1]
	v_mul_f32_e32 v6, 0xbfb8aa3b, v6
	v_mul_f32_e32 v7, 0xbfb8aa3b, v7
	v_exp_f32_e32 v6, v6
	v_exp_f32_e32 v7, v7
	s_nop 0
	v_pk_add_f32 v[6:7], v[6:7], 1.0 op_sel_hi:[1,0]
	s_nop 0
	v_div_scale_f32 v11, s[6:7], v7, v7, 1.0
	v_rcp_f32_e32 v12, v11
	s_nop 0
	v_fma_f32 v13, -v11, v12, 1.0
	v_fmac_f32_e32 v12, v13, v12
	v_div_scale_f32 v13, vcc, 1.0, v7, 1.0
	v_mul_f32_e32 v16, v13, v12
	v_fma_f32 v17, -v11, v16, v13
	v_fmac_f32_e32 v16, v17, v12
	v_fma_f32 v11, -v11, v16, v13
	v_div_fmas_f32 v11, v11, v12, v16
	v_div_fixup_f32 v7, v11, v7, 1.0
	v_div_scale_f32 v11, s[6:7], v6, v6, 1.0
	v_rcp_f32_e32 v12, v11
	s_nop 0
	v_fma_f32 v13, -v11, v12, 1.0
	v_fmac_f32_e32 v12, v13, v12
	v_div_scale_f32 v13, vcc, 1.0, v6, 1.0
	v_mul_f32_e32 v16, v13, v12
	v_fma_f32 v17, -v11, v16, v13
	v_fmac_f32_e32 v16, v17, v12
	v_fma_f32 v11, -v11, v16, v13
	v_div_fmas_f32 v11, v11, v12, v16
	v_div_fixup_f32 v6, v11, v6, 1.0
	v_pk_fma_f32 v[12:13], v[6:7], 2.0, -1.0 op_sel_hi:[1,0,0]
	s_nop 0
	v_cndmask_b32_e64 v11, v14, v12, s[4:5]
	v_cndmask_b32_e64 v12, v15, v13, s[4:5]
	v_cndmask_b32_e64 v13, v11, v6, s[0:1]
	v_add_f32_e32 v6, v9, v9
	v_cndmask_b32_e64 v6, v6, v9, s[0:1]
	v_mul_f32_e32 v6, 0xbfb8aa3b, v6
	v_exp_f32_e32 v11, v6
	v_cndmask_b32_e64 v12, v12, v7, s[0:1]
	v_pk_add_f32 v[6:7], v[10:11], 1.0 op_sel_hi:[1,0]
	s_nop 0
	v_div_scale_f32 v10, s[6:7], v7, v7, 1.0
	v_rcp_f32_e32 v11, v10
	s_nop 0
	v_fma_f32 v14, -v10, v11, 1.0
	v_fmac_f32_e32 v11, v14, v11
	v_div_scale_f32 v14, vcc, 1.0, v7, 1.0
	v_mul_f32_e32 v15, v14, v11
	v_fma_f32 v16, -v10, v15, v14
	v_fmac_f32_e32 v15, v16, v11
	v_fma_f32 v10, -v10, v15, v14
	v_div_fmas_f32 v10, v10, v11, v15
	v_div_fixup_f32 v7, v10, v7, 1.0
	v_div_scale_f32 v10, s[6:7], v6, v6, 1.0
	v_rcp_f32_e32 v11, v10
	s_nop 0
	v_fma_f32 v14, -v10, v11, 1.0
	v_fmac_f32_e32 v11, v14, v11
	v_div_scale_f32 v14, vcc, 1.0, v6, 1.0
	v_mul_f32_e32 v15, v14, v11
	v_fma_f32 v16, -v10, v15, v14
	v_fmac_f32_e32 v15, v16, v11
	v_fma_f32 v10, -v10, v15, v14
	v_div_fmas_f32 v10, v10, v11, v15
	v_div_fixup_f32 v6, v10, v6, 1.0
	v_pk_fma_f32 v[10:11], v[6:7], 2.0, -1.0 op_sel_hi:[1,0,0]
	v_bfe_u32 v14, v13, 16, 1
	v_cndmask_b32_e64 v9, v9, v11, s[4:5]
	v_cndmask_b32_e64 v8, v8, v10, s[4:5]
	v_cndmask_b32_e64 v6, v8, v6, s[0:1]
	v_cndmask_b32_e64 v7, v9, v7, s[0:1]
	v_cvt_pk_bf16_f32 v208, v12, v7
	v_bfe_u32 v9, v6, 16, 1
	v_add3_u32 v6, v6, v9, s60
	v_add3_u32 v13, v13, v14, s60
	v_lshrrev_b32_e32 v8, 16, v13
	v_mov_b32_e32 v9, v208
	v_and_or_b32 v8, v6, s56, v8
	v_cvt_pk_bf16_f32 v7, v24, v31
	v_cvt_pk_bf16_f32 v6, v25, v30
	ds_write_b128 v5, v[6:9]
	v_mul_hi_i32 v5, v4, s66
	v_lshrrev_b32_e32 v6, 31, v5
	v_ashrrev_i32_e32 v5, 3, v5
	v_add_u32_e32 v6, v5, v6
	v_mad_u64_u32 v[4:5], s[0:1], v6, s67, v[4:5]
	v_mul_lo_u32 v5, v6, s68
	s_movk_i32 s0, 0x800
	v_add3_u32 v20, v0, v5, s0
	v_add_u32_e32 v7, s26, v6
	v_mad_i64_i32 v[2:3], s[0:1], v7, s34, v[2:3]
	v_ashrrev_i32_e32 v21, 31, v20
	v_lshl_add_u64 v[2:3], v[20:21], 1, v[2:3]
	v_add_u32_e32 v5, s81, v6
	v_lshl_add_u64 v[16:17], v[2:3], 0, s[22:23]
	v_add_co_u32_e64 v2, s[0:1], s69, v2
	v_cmp_lt_i32_e32 vcc, s27, v5
	s_nop 0
	v_addc_co_u32_e64 v3, s[0:1], 0, v3, s[0:1]
	v_cmp_gt_i32_e64 s[6:7], s80, v5
	global_load_dwordx4 v[8:11], v[2:3], off offset:1792
	v_cndmask_b32_e64 v3, 0, -1, vcc
	v_cndmask_b32_e32 v2, 0, v132, vcc
	v_lshl_add_u64 v[2:3], v[16:17], 0, v[2:3]
	v_cndmask_b32_e64 v64, 0, v133, s[6:7]
	global_load_dwordx4 v[12:15], v[2:3], off
	v_lshl_add_u64 v[2:3], v[16:17], 0, v[64:65]
	global_load_dwordx4 v[16:19], v[2:3], off
	v_lshlrev_b64 v[208:209], 2, v[20:21]
	v_lshl_add_u64 v[210:211], s[12:13], 0, v[208:209]
	v_lshl_add_u64 v[212:213], s[24:25], 0, v[208:209]
	global_load_dwordx4 v[216:219], v[210:211], off offset:0
	global_load_dwordx4 v[220:223], v[212:213], off offset:0
	global_load_dwordx4 v[224:227], v[210:211], off offset:16
	global_load_dwordx4 v[228:231], v[212:213], off offset:16
	v_lshlrev_b64 v[2:3], 2, v[20:21]
	v_cmp_gt_i32_e64 s[4:5], 32, v4
	v_cmp_gt_i32_e64 s[0:1], 16, v4
	v_lshl_add_u32 v6, v6, 4, v1
	v_add_u32_e32 v1, 0x2000, v1
	v_add_u32_e32 v0, 0x1000, v0
	s_waitcnt vmcnt(0) lgkmcnt(0)
	v_lshlrev_b32_e32 v29, 16, v9
	v_lshlrev_b32_e32 v28, 16, v8
	v_and_b32_e32 v9, 0xffff0000, v9
	v_and_b32_e32 v8, 0xffff0000, v8
	v_and_b32_e32 v5, 0xffff0000, v12
	v_lshlrev_b32_e32 v7, 16, v13
	v_and_b32_e32 v13, 0xffff0000, v13
	v_lshlrev_b32_e32 v24, 16, v14
	v_and_b32_e32 v14, 0xffff0000, v14
	v_lshlrev_b32_e32 v25, 16, v15
	v_and_b32_e32 v15, 0xffff0000, v15
	v_lshlrev_b32_e32 v30, 16, v16
	v_lshlrev_b32_e32 v31, 16, v17
	v_and_b32_e32 v34, 0xffff0000, v17
	v_and_b32_e32 v35, 0xffff0000, v16
	v_lshlrev_b32_e32 v36, 16, v18
	v_lshlrev_b32_e32 v37, 16, v19
	v_and_b32_e32 v38, 0xffff0000, v19
	v_and_b32_e32 v39, 0xffff0000, v18
	v_lshl_add_u64 v[16:17], s[12:13], 0, v[2:3]
	v_lshl_add_u64 v[18:19], s[24:25], 0, v[2:3]
	v_lshlrev_b32_e32 v2, 16, v12
	v_cndmask_b32_e32 v20, 0, v2, vcc
	v_cndmask_b32_e32 v22, 0, v5, vcc
	v_cndmask_b32_e32 v23, 0, v13, vcc
	v_cndmask_b32_e32 v26, 0, v14, vcc
	v_cndmask_b32_e32 v27, 0, v15, vcc
	v_cndmask_b32_e32 v21, 0, v7, vcc
	v_cndmask_b32_e64 v31, 0, v31, s[6:7]
	v_cndmask_b32_e64 v30, 0, v30, s[6:7]
	v_pk_add_f32 v[20:21], v[20:21], v[28:29] neg_lo:[0,1] neg_hi:[0,1]
	v_pk_add_f32 v[22:23], v[22:23], v[8:9] neg_lo:[0,1] neg_hi:[0,1]
	v_cndmask_b32_e32 v24, 0, v24, vcc
	v_cndmask_b32_e32 v25, 0, v25, vcc
	s_waitcnt vmcnt(0) lgkmcnt(0)
	v_mov_b64_e32 v[2:3], v[216:217]
	v_mov_b64_e32 v[4:5], v[218:219]
	v_mov_b64_e32 v[12:13], v[220:221]
	v_mov_b64_e32 v[14:15], v[222:223]
	v_mov_b32_e32 v32, v2
	v_mov_b32_e32 v33, v4
	v_pk_fma_f32 v[20:21], v[32:33], v[20:21], v[28:29]
	v_pk_add_f32 v[28:29], v[30:31], v[28:29] neg_lo:[0,1] neg_hi:[0,1]
	v_mov_b32_e32 v30, v12
	v_mov_b32_e32 v31, v14
	v_pk_fma_f32 v[20:21], v[28:29], v[30:31], v[20:21]
	v_cndmask_b32_e64 v29, 0, v34, s[6:7]
	v_cndmask_b32_e64 v28, 0, v35, s[6:7]
	v_mov_b32_e32 v4, v3
	v_pk_fma_f32 v[4:5], v[4:5], v[22:23], v[8:9]
	v_pk_add_f32 v[8:9], v[28:29], v[8:9] neg_lo:[0,1] neg_hi:[0,1]
	v_mov_b32_e32 v14, v13
	v_pk_fma_f32 v[4:5], v[8:9], v[14:15], v[4:5]
	v_add_f32_e32 v2, v20, v20
	v_add_f32_e32 v3, v4, v4
	v_cndmask_b32_e64 v3, v3, v4, s[0:1]
	v_mul_f32_e32 v3, 0xbfb8aa3b, v3
	v_exp_f32_e32 v8, v3
	v_add_f32_e32 v3, v21, v21
	v_cndmask_b32_e64 v2, v2, v20, s[0:1]
	v_cndmask_b32_e64 v3, v3, v21, s[0:1]
	v_mul_f32_e32 v2, 0xbfb8aa3b, v2
	v_mul_f32_e32 v3, 0xbfb8aa3b, v3
	v_exp_f32_e32 v2, v2
	v_exp_f32_e32 v3, v3
	v_and_b32_e32 v15, 0xffff0000, v11
	v_pk_add_f32 v[2:3], v[2:3], 1.0 op_sel_hi:[1,0]
	s_nop 0
	v_div_scale_f32 v7, s[84:85], v3, v3, 1.0
	v_rcp_f32_e32 v9, v7
	s_nop 0
	v_fma_f32 v12, -v7, v9, 1.0
	v_fmac_f32_e32 v9, v12, v9
	v_div_scale_f32 v12, vcc, 1.0, v3, 1.0
	v_mul_f32_e32 v13, v12, v9
	v_fma_f32 v14, -v7, v13, v12
	v_fmac_f32_e32 v13, v14, v9
	v_fma_f32 v7, -v7, v13, v12
	v_div_fmas_f32 v7, v7, v9, v13
	v_div_fixup_f32 v3, v7, v3, 1.0
	v_div_scale_f32 v7, s[84:85], v2, v2, 1.0
	v_rcp_f32_e32 v9, v7
	s_nop 0
	v_fma_f32 v12, -v7, v9, 1.0
	v_fmac_f32_e32 v9, v12, v9
	v_div_scale_f32 v12, vcc, 1.0, v2, 1.0
	v_mul_f32_e32 v13, v12, v9
	v_fma_f32 v14, -v7, v13, v12
	v_fmac_f32_e32 v13, v14, v9
	v_fma_f32 v7, -v7, v13, v12
	v_div_fmas_f32 v7, v7, v9, v13
	v_div_fixup_f32 v2, v7, v2, 1.0
	v_pk_fma_f32 v[12:13], v[2:3], 2.0, -1.0 op_sel_hi:[1,0,0]
	s_nop 0
	v_cndmask_b32_e64 v7, v20, v12, s[4:5]
	v_cndmask_b32_e64 v7, v7, v2, s[0:1]
	v_add_f32_e32 v2, v5, v5
	v_cndmask_b32_e64 v2, v2, v5, s[0:1]
	v_cndmask_b32_e64 v9, v21, v13, s[4:5]
	v_mul_f32_e32 v2, 0xbfb8aa3b, v2
	v_cndmask_b32_e64 v22, v9, v3, s[0:1]
	v_exp_f32_e32 v9, v2
	s_nop 0
	v_pk_add_f32 v[2:3], v[8:9], 1.0 op_sel_hi:[1,0]
	s_nop 0
	v_div_scale_f32 v8, s[84:85], v3, v3, 1.0
	v_rcp_f32_e32 v9, v8
	s_nop 0
	v_fma_f32 v12, -v8, v9, 1.0
	v_fmac_f32_e32 v9, v12, v9
	v_div_scale_f32 v12, vcc, 1.0, v3, 1.0
	v_mul_f32_e32 v13, v12, v9
	v_fma_f32 v14, -v8, v13, v12
	v_fmac_f32_e32 v13, v14, v9
	v_fma_f32 v8, -v8, v13, v12
	v_div_fmas_f32 v8, v8, v9, v13
	v_div_fixup_f32 v3, v8, v3, 1.0
	v_div_scale_f32 v8, s[84:85], v2, v2, 1.0
	v_rcp_f32_e32 v9, v8
	s_nop 0
	v_fma_f32 v12, -v8, v9, 1.0
	v_fmac_f32_e32 v9, v12, v9
	v_div_scale_f32 v12, vcc, 1.0, v2, 1.0
	v_mul_f32_e32 v13, v12, v9
	v_fma_f32 v14, -v8, v13, v12
	v_fmac_f32_e32 v13, v14, v9
	v_fma_f32 v8, -v8, v13, v12
	v_div_fmas_f32 v8, v8, v9, v13
	v_div_fixup_f32 v2, v8, v2, 1.0
	v_pk_fma_f32 v[8:9], v[2:3], 2.0, -1.0 op_sel_hi:[1,0,0]
	v_lshlrev_b32_e32 v13, 16, v11
	v_cndmask_b32_e64 v5, v5, v9, s[4:5]
	v_cndmask_b32_e64 v4, v4, v8, s[4:5]
	v_cndmask_b32_e64 v23, v4, v2, s[0:1]
	v_cvt_pk_bf16_f32 v209, v7, v23
	v_cndmask_b32_e64 v28, v5, v3, s[0:1]
	v_lshlrev_b32_e32 v12, 16, v10
	v_and_b32_e32 v14, 0xffff0000, v10
	v_cndmask_b32_e64 v17, 0, v37, s[6:7]
	v_cndmask_b32_e64 v16, 0, v36, s[6:7]
	v_pk_add_f32 v[18:19], v[24:25], v[12:13] neg_lo:[0,1] neg_hi:[0,1]
	s_waitcnt vmcnt(0) lgkmcnt(0)
	v_mov_b64_e32 v[2:3], v[224:225]
	v_mov_b64_e32 v[4:5], v[226:227]
	v_mov_b64_e32 v[8:9], v[228:229]
	v_mov_b64_e32 v[10:11], v[230:231]
	v_mov_b32_e32 v20, v2
	v_mov_b32_e32 v21, v4
	v_pk_fma_f32 v[18:19], v[18:19], v[20:21], v[12:13]
	v_pk_add_f32 v[12:13], v[16:17], v[12:13] neg_lo:[0,1] neg_hi:[0,1]
	v_mov_b32_e32 v16, v8
	v_mov_b32_e32 v17, v10
	v_pk_fma_f32 v[12:13], v[12:13], v[16:17], v[18:19]
	v_cndmask_b32_e64 v17, 0, v38, s[6:7]
	v_cndmask_b32_e64 v16, 0, v39, s[6:7]
	v_pk_add_f32 v[18:19], v[26:27], v[14:15] neg_lo:[0,1] neg_hi:[0,1]
	v_mov_b32_e32 v4, v3
	v_pk_fma_f32 v[4:5], v[18:19], v[4:5], v[14:15]
	v_pk_add_f32 v[14:15], v[16:17], v[14:15] neg_lo:[0,1] neg_hi:[0,1]
	v_mov_b32_e32 v10, v9
	v_pk_fma_f32 v[4:5], v[14:15], v[10:11], v[4:5]
	v_add_f32_e32 v2, v12, v12
	v_add_f32_e32 v3, v4, v4
	v_cndmask_b32_e64 v3, v3, v4, s[0:1]
	v_mul_f32_e32 v3, 0xbfb8aa3b, v3
	v_exp_f32_e32 v8, v3
	v_add_f32_e32 v3, v13, v13
	v_cndmask_b32_e64 v2, v2, v12, s[0:1]
	v_cndmask_b32_e64 v3, v3, v13, s[0:1]
	v_mul_f32_e32 v2, 0xbfb8aa3b, v2
	v_mul_f32_e32 v3, 0xbfb8aa3b, v3
	v_exp_f32_e32 v2, v2
	v_exp_f32_e32 v3, v3
	s_nop 0
	v_pk_add_f32 v[2:3], v[2:3], 1.0 op_sel_hi:[1,0]
	s_nop 0
	v_div_scale_f32 v9, s[6:7], v3, v3, 1.0
	v_rcp_f32_e32 v10, v9
	s_nop 0
	v_fma_f32 v11, -v9, v10, 1.0
	v_fmac_f32_e32 v10, v11, v10
	v_div_scale_f32 v11, vcc, 1.0, v3, 1.0
	v_mul_f32_e32 v14, v11, v10
	v_fma_f32 v15, -v9, v14, v11
	v_fmac_f32_e32 v14, v15, v10
	v_fma_f32 v9, -v9, v14, v11
	v_div_fmas_f32 v9, v9, v10, v14
	v_div_fixup_f32 v3, v9, v3, 1.0
	v_div_scale_f32 v9, s[6:7], v2, v2, 1.0
	v_rcp_f32_e32 v10, v9
	s_nop 0
	v_fma_f32 v11, -v9, v10, 1.0
	v_fmac_f32_e32 v10, v11, v10
	v_div_scale_f32 v11, vcc, 1.0, v2, 1.0
	v_mul_f32_e32 v14, v11, v10
	v_fma_f32 v15, -v9, v14, v11
	v_fmac_f32_e32 v14, v15, v10
	v_fma_f32 v9, -v9, v14, v11
	v_div_fmas_f32 v9, v9, v10, v14
	v_div_fixup_f32 v2, v9, v2, 1.0
	v_pk_fma_f32 v[10:11], v[2:3], 2.0, -1.0 op_sel_hi:[1,0,0]
	s_nop 0
	v_cndmask_b32_e64 v9, v12, v10, s[4:5]
	v_cndmask_b32_e64 v10, v13, v11, s[4:5]
	v_cndmask_b32_e64 v11, v9, v2, s[0:1]
	v_add_f32_e32 v2, v5, v5
	v_cndmask_b32_e64 v2, v2, v5, s[0:1]
	v_mul_f32_e32 v2, 0xbfb8aa3b, v2
	v_exp_f32_e32 v9, v2
	v_cndmask_b32_e64 v10, v10, v3, s[0:1]
	v_pk_add_f32 v[2:3], v[8:9], 1.0 op_sel_hi:[1,0]
	s_nop 0
	v_div_scale_f32 v8, s[6:7], v3, v3, 1.0
	v_rcp_f32_e32 v9, v8
	s_nop 0
	v_fma_f32 v12, -v8, v9, 1.0
	v_fmac_f32_e32 v9, v12, v9
	v_div_scale_f32 v12, vcc, 1.0, v3, 1.0
	v_mul_f32_e32 v13, v12, v9
	v_fma_f32 v14, -v8, v13, v12
	v_fmac_f32_e32 v13, v14, v9
	v_fma_f32 v8, -v8, v13, v12
	v_div_fmas_f32 v8, v8, v9, v13
	v_div_fixup_f32 v3, v8, v3, 1.0
	v_div_scale_f32 v8, s[6:7], v2, v2, 1.0
	v_rcp_f32_e32 v9, v8
	s_nop 0
	v_fma_f32 v12, -v8, v9, 1.0
	v_fmac_f32_e32 v9, v12, v9
	v_div_scale_f32 v12, vcc, 1.0, v2, 1.0
	v_mul_f32_e32 v13, v12, v9
	v_fma_f32 v14, -v8, v13, v12
	v_fmac_f32_e32 v13, v14, v9
	v_fma_f32 v8, -v8, v13, v12
	v_div_fmas_f32 v8, v8, v9, v13
	v_div_fixup_f32 v2, v8, v2, 1.0
	v_pk_fma_f32 v[8:9], v[2:3], 2.0, -1.0 op_sel_hi:[1,0,0]
	v_bfe_u32 v12, v11, 16, 1
	v_cndmask_b32_e64 v5, v5, v9, s[4:5]
	v_cndmask_b32_e64 v4, v4, v8, s[4:5]
	v_cndmask_b32_e64 v2, v4, v2, s[0:1]
	v_cndmask_b32_e64 v3, v5, v3, s[0:1]
	v_cvt_pk_bf16_f32 v208, v10, v3
	v_bfe_u32 v5, v2, 16, 1
	v_add3_u32 v2, v2, v5, s60
	v_add3_u32 v11, v11, v12, s60
	v_lshrrev_b32_e32 v4, 16, v11
	v_mov_b32_e32 v5, v208
	v_and_or_b32 v4, v2, s56, v4
	v_cvt_pk_bf16_f32 v3, v22, v28
	v_mov_b32_e32 v2, v209
	ds_write_b128 v6, v[2:5] offset:4096
	s_cbranch_scc0 .LBB0_1406
	v_ashrrev_i32_e32 v137, 3, v135
	v_and_b32_e32 v138, -4, v137
	v_add_u32_e32 v18, s81, v138
	v_add_u32_e32 v0, -1, v18
	v_or_b32_e32 v44, 1, v18
	v_and_b32_e32 v126, 31, v135
	v_max_i32_e32 v0, s27, v0
	v_max_i32_e32 v2, s27, v18
	v_max_i32_e32 v10, s27, v44
	v_lshlrev_b32_e32 v34, 4, v126
	v_mov_b32_e32 v35, v65
	s_mulk_i32 s18, 0x900
	v_min_i32_e32 v0, s80, v0
	v_min_i32_e32 v2, s80, v2
	v_min_i32_e32 v10, s80, v10
	v_lshl_add_u64 v[88:89], s[54:55], 0, v[34:35]
	s_mov_b64 s[0:1], 0x7158100
	v_add_u32_e32 v0, s18, v0
	v_add_u32_e32 v2, s18, v2
	v_add_u32_e32 v10, s18, v10
	v_lshl_add_u64 v[8:9], v[88:89], 0, s[0:1]
	v_mul_hi_i32_i24_e32 v25, 0x1240, v0
	v_mul_i32_i24_e32 v24, 0x1240, v0
	v_mul_hi_i32_i24_e32 v27, 0x1240, v2
	v_mul_i32_i24_e32 v26, 0x1240, v2
	v_mul_hi_i32_i24_e32 v49, 0x1240, v10
	v_mul_i32_i24_e32 v48, 0x1240, v10
	v_lshl_add_u64 v[0:1], v[8:9], 0, v[24:25]
	v_lshl_add_u64 v[4:5], v[8:9], 0, v[26:27]
	v_lshl_add_u64 v[10:11], v[8:9], 0, v[48:49]
	v_or_b32_e32 v45, 2, v18
	global_load_dwordx4 v[0:3], v[0:1], off
	s_nop 0
	global_load_dwordx4 v[4:7], v[4:5], off
	v_or_b32_e32 v70, 3, v18
	global_load_dwordx4 v[36:39], v[10:11], off
	v_max_i32_e32 v10, s27, v45
	v_min_i32_e32 v10, s80, v10
	v_add_u32_e32 v10, s18, v10
	v_mul_hi_i32_i24_e32 v55, 0x1240, v10
	v_mul_i32_i24_e32 v54, 0x1240, v10
	v_lshl_add_u64 v[10:11], v[8:9], 0, v[54:55]
	global_load_dwordx4 v[40:43], v[10:11], off
	v_max_i32_e32 v10, s27, v70
	v_min_i32_e32 v10, s80, v10
	v_add_u32_e32 v10, s18, v10
	v_mul_hi_i32_i24_e32 v57, 0x1240, v10
	v_mul_i32_i24_e32 v56, 0x1240, v10
	v_lshl_add_u64 v[10:11], v[8:9], 0, v[56:57]
	v_add_u32_e32 v71, 4, v18
	global_load_dwordx4 v[60:63], v[10:11], off
	v_max_i32_e32 v10, s27, v71
	v_min_i32_e32 v10, s80, v10
	v_add_u32_e32 v10, s18, v10
	v_mul_hi_i32_i24_e32 v59, 0x1240, v10
	v_mul_i32_i24_e32 v58, 0x1240, v10
	v_lshl_add_u64 v[8:9], v[8:9], 0, v[58:59]
	global_load_dwordx4 v[66:69], v[8:9], off
	v_mov_b32_e32 v8, s54
	v_mov_b32_e32 v9, s55
	v_add_co_u32_e32 v32, vcc, s57, v8
	v_lshlrev_b32_e32 v64, 5, v126
	s_nop 0
	v_addc_co_u32_e32 v33, vcc, 0, v9, vcc
	v_lshl_add_u64 v[28:29], s[8:9], 0, v[64:65]
	v_add_co_u32_e32 v50, vcc, s35, v28
	v_lshl_add_u64 v[46:47], s[10:11], 0, v[64:65]
	s_nop 0
	v_addc_co_u32_e32 v51, vcc, 0, v29, vcc
	v_add_co_u32_e32 v52, vcc, s35, v46
	global_load_dwordx4 v[8:11], v[50:51], off offset:512
	s_nop 0
	v_addc_co_u32_e32 v53, vcc, 0, v47, vcc
	global_load_dwordx2 v[30:31], v[32:33], off offset:464
	global_load_dwordx4 v[12:15], v[52:53], off offset:512
	v_lshl_add_u64 v[16:17], v[28:29], 0, s[20:21]
	v_lshl_add_u64 v[20:21], v[46:47], 0, s[20:21]
	v_cmp_lt_i32_e32 vcc, s27, v18
	v_cmp_ge_i32_e64 s[0:1], s79, v18
	v_cmp_le_i32_e64 s[4:5], s27, v18
	v_cmp_gt_i32_e64 s[6:7], s79, v18
	global_load_dwordx4 v[16:19], v[16:17], off offset:16
	s_and_b64 vcc, vcc, s[0:1]
	global_load_dwordx4 v[20:23], v[20:21], off offset:16
	s_and_b64 s[4:5], s[4:5], s[6:7]
	v_cmp_le_i32_e64 s[0:1], s27, v44
	v_cmp_gt_i32_e64 s[6:7], s79, v44
	s_and_b64 s[6:7], s[0:1], s[6:7]
	v_cmp_le_i32_e64 s[0:1], s27, v45
	v_cmp_gt_i32_e64 s[8:9], s79, v45
	s_and_b64 s[8:9], s[0:1], s[8:9]
	v_cmp_le_i32_e64 s[0:1], s27, v70
	v_cmp_gt_i32_e64 s[10:11], s79, v70
	s_and_b64 s[10:11], s[0:1], s[10:11]
	v_cmp_le_i32_e64 s[0:1], s27, v71
	v_cmp_gt_i32_e64 s[12:13], s79, v71
	s_and_b64 s[12:13], s[0:1], s[12:13]
	v_add_u32_e32 v90, s26, v138
	v_ashrrev_i32_e32 v91, 31, v90
	s_mov_b32 s24, 0
	v_lshlrev_b32_e32 v126, 3, v126
	s_waitcnt vmcnt(0) lgkmcnt(0)
	v_cndmask_b32_e32 v72, 0, v1, vcc
	v_cndmask_b32_e32 v73, 0, v0, vcc
	v_cndmask_b32_e64 v77, 0, v5, s[4:5]
	v_cndmask_b32_e64 v79, 0, v4, s[4:5]
	v_cndmask_b32_e64 v80, 0, v39, s[6:7]
	v_cndmask_b32_e64 v82, 0, v38, s[6:7]
	v_cndmask_b32_e64 v38, 0, v37, s[6:7]
	v_cndmask_b32_e64 v39, 0, v36, s[6:7]
	v_and_b32_e32 v37, 0xffff0000, v72
	v_and_b32_e32 v36, 0xffff0000, v73
	v_cndmask_b32_e32 v74, 0, v3, vcc
	v_cndmask_b32_e32 v75, 0, v2, vcc
	v_cndmask_b32_e64 v76, 0, v7, s[4:5]
	v_cndmask_b32_e64 v78, 0, v6, s[4:5]
	v_lshlrev_b32_e32 v45, 16, v77
	v_lshlrev_b32_e32 v44, 16, v79
	v_and_b32_e32 v81, 0xffff0000, v80
	v_cndmask_b32_e64 v86, 0, v43, s[8:9]
	v_cndmask_b32_e64 v94, 0, v63, s[10:11]
	v_cndmask_b32_e64 v95, 0, v62, s[10:11]
	v_and_b32_e32 v63, 0xffff0000, v77
	v_and_b32_e32 v62, 0xffff0000, v79
	v_pk_add_f32 v[36:37], v[36:37], v[62:63] neg_lo:[0,1] neg_hi:[0,1]
	v_and_b32_e32 v77, 0xffff0000, v76
	v_lshlrev_b32_e32 v79, 16, v80
	v_cndmask_b32_e64 v122, 0, v69, s[12:13]
	v_cndmask_b32_e64 v123, 0, v68, s[12:13]
	v_and_b32_e32 v69, 0xffff0000, v38
	v_and_b32_e32 v68, 0xffff0000, v39
	v_cndmask_b32_e64 v118, 0, v67, s[12:13]
	v_cndmask_b32_e64 v119, 0, v66, s[12:13]
	v_lshlrev_b32_e32 v67, 16, v38
	v_lshlrev_b32_e32 v66, 16, v39
	v_pk_add_f32 v[38:39], v[66:67], v[44:45] neg_lo:[0,1] neg_hi:[0,1]
	v_and_b32_e32 v80, 0xffff0000, v82
	v_cndmask_b32_e64 v96, 0, v61, s[10:11]
	v_cndmask_b32_e64 v97, 0, v60, s[10:11]
	v_cndmask_b32_e64 v87, 0, v42, s[8:9]
	v_cndmask_b32_e64 v92, 0, v41, s[8:9]
	v_cndmask_b32_e64 v93, 0, v40, s[8:9]
	v_mov_b32_e32 v71, v10
	v_mov_b32_e32 v10, v9
	v_mov_b32_e32 v70, v8
	v_readfirstlane_b32 s1, v31
	v_readfirstlane_b32 s0, v30
	v_lshlrev_b32_e32 v31, 16, v72
	v_lshlrev_b32_e32 v30, 16, v73
	v_mov_b32_e32 v73, v14
	v_pk_fma_f32 v[8:9], v[10:11], v[36:37], v[62:63]
	v_pk_add_f32 v[36:37], v[68:69], v[62:63] neg_lo:[0,1] neg_hi:[0,1]
	v_mov_b32_e32 v14, v13
	v_pk_add_f32 v[30:31], v[30:31], v[44:45] neg_lo:[0,1] neg_hi:[0,1]
	v_mov_b32_e32 v72, v12
	v_pk_fma_f32 v[36:37], v[14:15], v[36:37], v[8:9]
	v_lshlrev_b32_e32 v9, 16, v74
	v_lshlrev_b32_e32 v8, 16, v75
	v_and_b32_e32 v13, 0xffff0000, v74
	v_and_b32_e32 v12, 0xffff0000, v75
	v_lshlrev_b32_e32 v75, 16, v76
	v_lshlrev_b32_e32 v74, 16, v78
	v_pk_fma_f32 v[30:31], v[70:71], v[30:31], v[44:45]
	v_and_b32_e32 v76, 0xffff0000, v78
	v_lshlrev_b32_e32 v78, 16, v82
	v_pk_add_f32 v[8:9], v[8:9], v[74:75] neg_lo:[0,1] neg_hi:[0,1]
	v_mov_b32_e32 v82, v16
	v_mov_b32_e32 v83, v18
	v_pk_fma_f32 v[30:31], v[72:73], v[38:39], v[30:31]
	v_pk_fma_f32 v[8:9], v[82:83], v[8:9], v[74:75]
	v_pk_add_f32 v[38:39], v[78:79], v[74:75] neg_lo:[0,1] neg_hi:[0,1]
	v_mov_b32_e32 v84, v20
	v_mov_b32_e32 v85, v22
	v_pk_fma_f32 v[98:99], v[84:85], v[38:39], v[8:9]
	v_pk_add_f32 v[8:9], v[12:13], v[76:77] neg_lo:[0,1] neg_hi:[0,1]
	v_mov_b32_e32 v18, v17
	v_pk_fma_f32 v[8:9], v[18:19], v[8:9], v[76:77]
	v_pk_add_f32 v[12:13], v[80:81], v[76:77] neg_lo:[0,1] neg_hi:[0,1]
	v_mov_b32_e32 v22, v21
	v_pk_fma_f32 v[100:101], v[22:23], v[12:13], v[8:9]
	v_bfe_u32 v8, v30, 16, 1
	v_bfe_u32 v9, v31, 16, 1
	v_bfe_u32 v12, v98, 16, 1
	v_bfe_u32 v13, v99, 16, 1
	v_lshl_add_u64 v[0:1], s[0:1], 0, v[64:65]
	s_mov_b64 s[0:1], 0x156d7900
	v_add3_u32 v13, v99, v13, s60
	v_add3_u32 v12, v98, v12, s60
	v_add3_u32 v9, v31, v9, s60
	v_add3_u32 v8, v30, v8, s60
	v_lshl_add_u64 v[60:61], v[88:89], 0, s[0:1]
	v_lshrrev_b32_e32 v8, 16, v8
	v_lshrrev_b32_e32 v9, 16, v9
	v_lshrrev_b32_e32 v12, 16, v12
	v_lshrrev_b32_e32 v13, 16, v13
	v_lshlrev_b64 v[38:39], 9, v[90:91]
	v_and_or_b32 v43, v101, s56, v13
	v_and_or_b32 v42, v100, s56, v12
	v_and_or_b32 v41, v37, s56, v9
	v_and_or_b32 v40, v36, s56, v8
	v_lshl_add_u64 v[8:9], v[60:61], 0, v[38:39]
	global_load_dwordx4 v[4:7], v[0:1], off offset:1024
	s_nop 0
	global_load_dwordx4 v[0:3], v[0:1], off offset:1040
	v_pk_add_f32 v[16:17], v[44:45], v[66:67] neg_lo:[0,1] neg_hi:[0,1]
	global_store_dwordx4 v[8:9], v[40:43], off
	v_lshlrev_b32_e32 v9, 16, v92
	v_lshlrev_b32_e32 v8, 16, v93
	v_pk_fma_f32 v[16:17], v[70:71], v[16:17], v[66:67]
	v_pk_add_f32 v[20:21], v[8:9], v[66:67] neg_lo:[0,1] neg_hi:[0,1]
	v_and_b32_e32 v13, 0xffff0000, v92
	v_and_b32_e32 v12, 0xffff0000, v93
	v_pk_fma_f32 v[102:103], v[72:73], v[20:21], v[16:17]
	v_pk_add_f32 v[16:17], v[62:63], v[68:69] neg_lo:[0,1] neg_hi:[0,1]
	v_pk_add_f32 v[20:21], v[12:13], v[68:69] neg_lo:[0,1] neg_hi:[0,1]
	v_pk_fma_f32 v[16:17], v[10:11], v[16:17], v[68:69]
	v_pk_add_f32 v[40:41], v[74:75], v[78:79] neg_lo:[0,1] neg_hi:[0,1]
	v_pk_fma_f32 v[104:105], v[14:15], v[20:21], v[16:17]
	v_lshlrev_b32_e32 v17, 16, v86
	v_lshlrev_b32_e32 v16, 16, v87
	v_pk_fma_f32 v[40:41], v[82:83], v[40:41], v[78:79]
	v_pk_add_f32 v[42:43], v[16:17], v[78:79] neg_lo:[0,1] neg_hi:[0,1]
	v_and_b32_e32 v21, 0xffff0000, v86
	v_and_b32_e32 v20, 0xffff0000, v87
	v_pk_fma_f32 v[106:107], v[84:85], v[42:43], v[40:41]
	v_pk_add_f32 v[40:41], v[76:77], v[80:81] neg_lo:[0,1] neg_hi:[0,1]
	v_pk_add_f32 v[42:43], v[20:21], v[80:81] neg_lo:[0,1] neg_hi:[0,1]
	v_pk_fma_f32 v[40:41], v[18:19], v[40:41], v[80:81]
	v_or_b32_e32 v92, 1, v90
	v_pk_fma_f32 v[108:109], v[22:23], v[42:43], v[40:41]
	v_bfe_u32 v40, v102, 16, 1
	v_bfe_u32 v41, v103, 16, 1
	v_bfe_u32 v42, v106, 16, 1
	v_bfe_u32 v43, v107, 16, 1
	v_add3_u32 v43, v107, v43, s60
	v_add3_u32 v42, v106, v42, s60
	v_add3_u32 v41, v103, v41, s60
	v_add3_u32 v40, v102, v40, s60
	v_lshrrev_b32_e32 v40, 16, v40
	v_lshrrev_b32_e32 v41, 16, v41
	v_lshrrev_b32_e32 v42, 16, v42
	v_lshrrev_b32_e32 v43, 16, v43
	v_ashrrev_i32_e32 v93, 31, v92
	v_and_or_b32 v45, v109, s56, v43
	v_and_or_b32 v44, v108, s56, v42
	v_and_or_b32 v43, v105, s56, v41
	v_and_or_b32 v42, v104, s56, v40
	v_lshlrev_b64 v[40:41], 9, v[92:93]
	v_lshl_add_u64 v[62:63], v[60:61], 0, v[40:41]
	global_store_dwordx4 v[62:63], v[42:45], off
	v_pk_add_f32 v[66:67], v[66:67], v[8:9] neg_lo:[0,1] neg_hi:[0,1]
	v_and_b32_e32 v63, 0xffff0000, v96
	v_lshlrev_b32_e32 v45, 16, v96
	v_lshlrev_b32_e32 v44, 16, v97
	v_pk_add_f32 v[42:43], v[44:45], v[8:9] neg_lo:[0,1] neg_hi:[0,1]
	v_pk_fma_f32 v[66:67], v[70:71], v[66:67], v[8:9]
	v_and_b32_e32 v62, 0xffff0000, v97
	v_pk_fma_f32 v[110:111], v[72:73], v[42:43], v[66:67]
	v_pk_add_f32 v[42:43], v[68:69], v[12:13] neg_lo:[0,1] neg_hi:[0,1]
	v_pk_add_f32 v[74:75], v[62:63], v[12:13] neg_lo:[0,1] neg_hi:[0,1]
	v_pk_fma_f32 v[42:43], v[10:11], v[42:43], v[12:13]
	v_pk_add_f32 v[68:69], v[78:79], v[16:17] neg_lo:[0,1] neg_hi:[0,1]
	v_pk_fma_f32 v[112:113], v[14:15], v[74:75], v[42:43]
	v_lshlrev_b32_e32 v75, 16, v94
	v_lshlrev_b32_e32 v74, 16, v95
	v_pk_add_f32 v[42:43], v[74:75], v[16:17] neg_lo:[0,1] neg_hi:[0,1]
	v_pk_fma_f32 v[68:69], v[82:83], v[68:69], v[16:17]
	v_and_b32_e32 v77, 0xffff0000, v94
	v_and_b32_e32 v76, 0xffff0000, v95
	v_pk_fma_f32 v[114:115], v[84:85], v[42:43], v[68:69]
	v_pk_add_f32 v[42:43], v[80:81], v[20:21] neg_lo:[0,1] neg_hi:[0,1]
	v_pk_add_f32 v[66:67], v[76:77], v[20:21] neg_lo:[0,1] neg_hi:[0,1]
	v_pk_fma_f32 v[42:43], v[18:19], v[42:43], v[20:21]
	v_or_b32_e32 v94, 2, v90
	v_pk_fma_f32 v[116:117], v[22:23], v[66:67], v[42:43]
	v_bfe_u32 v42, v110, 16, 1
	v_bfe_u32 v43, v111, 16, 1
	v_bfe_u32 v66, v114, 16, 1
	v_bfe_u32 v67, v115, 16, 1
	v_add3_u32 v67, v115, v67, s60
	v_add3_u32 v66, v114, v66, s60
	v_add3_u32 v43, v111, v43, s60
	v_add3_u32 v42, v110, v42, s60
	v_lshrrev_b32_e32 v42, 16, v42
	v_lshrrev_b32_e32 v43, 16, v43
	v_lshrrev_b32_e32 v66, 16, v66
	v_lshrrev_b32_e32 v67, 16, v67
	v_ashrrev_i32_e32 v95, 31, v94
	v_and_or_b32 v69, v117, s56, v67
	v_and_or_b32 v68, v116, s56, v66
	v_and_or_b32 v67, v113, s56, v43
	v_and_or_b32 v66, v112, s56, v42
	v_lshlrev_b64 v[42:43], 9, v[94:95]
	v_lshl_add_u64 v[78:79], v[60:61], 0, v[42:43]
	global_store_dwordx4 v[78:79], v[66:69], off
	v_pk_add_f32 v[8:9], v[8:9], v[44:45] neg_lo:[0,1] neg_hi:[0,1]
	v_pk_add_f32 v[12:13], v[12:13], v[62:63] neg_lo:[0,1] neg_hi:[0,1]
	v_lshlrev_b32_e32 v67, 16, v118
	v_lshlrev_b32_e32 v66, 16, v119
	v_and_b32_e32 v69, 0xffff0000, v118
	v_and_b32_e32 v68, 0xffff0000, v119
	v_pk_add_f32 v[66:67], v[66:67], v[44:45] neg_lo:[0,1] neg_hi:[0,1]
	v_pk_fma_f32 v[8:9], v[70:71], v[8:9], v[44:45]
	v_pk_add_f32 v[68:69], v[68:69], v[62:63] neg_lo:[0,1] neg_hi:[0,1]
	v_pk_fma_f32 v[118:119], v[72:73], v[66:67], v[8:9]
	v_pk_fma_f32 v[8:9], v[10:11], v[12:13], v[62:63]
	v_pk_add_f32 v[12:13], v[16:17], v[74:75] neg_lo:[0,1] neg_hi:[0,1]
	v_pk_fma_f32 v[120:121], v[14:15], v[68:69], v[8:9]
	v_lshlrev_b32_e32 v9, 16, v122
	v_lshlrev_b32_e32 v8, 16, v123
	v_and_b32_e32 v11, 0xffff0000, v122
	v_and_b32_e32 v10, 0xffff0000, v123
	v_pk_add_f32 v[8:9], v[8:9], v[74:75] neg_lo:[0,1] neg_hi:[0,1]
	v_pk_add_f32 v[14:15], v[20:21], v[76:77] neg_lo:[0,1] neg_hi:[0,1]
	v_pk_fma_f32 v[12:13], v[82:83], v[12:13], v[74:75]
	v_pk_add_f32 v[10:11], v[10:11], v[76:77] neg_lo:[0,1] neg_hi:[0,1]
	v_pk_fma_f32 v[122:123], v[84:85], v[8:9], v[12:13]
	v_pk_fma_f32 v[8:9], v[18:19], v[14:15], v[76:77]
	v_or_b32_e32 v96, 3, v90
	v_pk_fma_f32 v[124:125], v[22:23], v[10:11], v[8:9]
	v_bfe_u32 v8, v118, 16, 1
	v_bfe_u32 v9, v119, 16, 1
	v_bfe_u32 v10, v122, 16, 1
	v_bfe_u32 v11, v123, 16, 1
	v_add3_u32 v11, v123, v11, s60
	v_add3_u32 v10, v122, v10, s60
	v_add3_u32 v9, v119, v9, s60
	v_add3_u32 v8, v118, v8, s60
	v_ashrrev_i32_e32 v97, 31, v96
	v_lshrrev_b32_e32 v8, 16, v8
	v_lshrrev_b32_e32 v9, 16, v9
	v_lshrrev_b32_e32 v10, 16, v10
	v_lshrrev_b32_e32 v11, 16, v11
	v_lshlrev_b64 v[44:45], 9, v[96:97]
	v_and_or_b32 v11, v125, s56, v11
	v_and_or_b32 v10, v124, s56, v10
	v_and_or_b32 v9, v121, s56, v9
	v_and_or_b32 v8, v120, s56, v8
	v_lshl_add_u64 v[12:13], v[60:61], 0, v[44:45]
	global_store_dwordx4 v[12:13], v[8:11], off
	v_lshl_add_u64 v[16:17], v[28:29], 0, s[36:37]
	v_lshl_add_u64 v[20:21], v[46:47], 0, s[36:37]
	v_lshl_add_u64 v[8:9], v[88:89], 0, s[38:39]
	v_lshl_add_u64 v[10:11], v[8:9], 0, v[24:25]
	global_load_dwordx4 v[60:63], v[10:11], off
	v_lshl_add_u64 v[10:11], v[8:9], 0, v[26:27]
	global_load_dwordx4 v[66:69], v[10:11], off
	v_lshl_add_u64 v[10:11], v[8:9], 0, v[48:49]
	global_load_dwordx4 v[70:73], v[10:11], off
	v_lshl_add_u64 v[10:11], v[8:9], 0, v[54:55]
	global_load_dwordx4 v[74:77], v[10:11], off
	v_lshl_add_u64 v[10:11], v[8:9], 0, v[56:57]
	global_load_dwordx4 v[78:81], v[10:11], off
	v_lshl_add_u64 v[8:9], v[8:9], 0, v[58:59]
	global_load_dwordx4 v[82:85], v[8:9], off
	s_nop 0
	global_load_dwordx4 v[8:11], v[50:51], off offset:2560
	global_load_dwordx4 v[12:15], v[52:53], off offset:2560
	s_waitcnt vmcnt(0) lgkmcnt(0)
	v_mul_f32_e32 v159, v98, v0
	global_load_dwordx4 v[16:19], v[16:17], off offset:16
	v_mul_f32_e32 v160, v100, v1
	global_load_dwordx4 v[20:23], v[20:21], off offset:16
	v_mul_f32_e32 v161, v99, v2
	v_mul_f32_e32 v162, v101, v3
	v_mul_f32_e32 v163, v4, v102
	v_mul_f32_e32 v168, v5, v104
	v_mul_f32_e32 v169, v103, v6
	v_mul_f32_e32 v170, v105, v7
	v_mul_f32_e32 v171, v106, v0
	v_mul_f32_e32 v114, v114, v0
	v_mul_f32_e32 v187, v122, v0
	v_mul_f32_e32 v172, v108, v1
	v_mul_f32_e32 v116, v116, v1
	v_mul_f32_e32 v188, v124, v1
	v_bitop3_b32 v1, v135, 31, v130 bitop3:0xe0
	v_mul_f32_e32 v173, v107, v2
	v_mul_f32_e32 v174, v109, v3
	v_mul_f32_e32 v175, v4, v110
	v_mul_f32_e32 v176, v5, v112
	v_mul_f32_e32 v177, v6, v111
	v_mul_f32_e32 v178, v113, v7
	v_mul_f32_e32 v115, v115, v2
	v_mul_f32_e32 v117, v117, v3
	v_mul_f32_e32 v179, v4, v118
	v_mul_f32_e32 v184, v5, v120
	v_mul_f32_e32 v185, v6, v119
	v_mul_f32_e32 v186, v7, v121
	v_mul_f32_e32 v189, v123, v2
	v_mul_f32_e32 v190, v125, v3
	v_or_b32_e32 v110, 3, v137
	v_mul_lo_u32 v110, v110, s70
	v_add_u32_e32 v119, v64, v110
	v_lshlrev_b64 v[110:111], 11, v[96:97]
	v_lshl_add_u64 v[110:111], s[54:55], 0, v[110:111]
	v_cndmask_b32_e32 v136, 0, v61, vcc
	v_cndmask_b32_e32 v139, 0, v60, vcc
	v_cndmask_b32_e64 v140, 0, v69, s[4:5]
	v_cndmask_b32_e64 v141, 0, v68, s[4:5]
	v_cndmask_b32_e64 v68, 0, v67, s[4:5]
	v_cndmask_b32_e64 v69, 0, v66, s[4:5]
	v_cndmask_b32_e64 v142, 0, v73, s[6:7]
	v_cndmask_b32_e64 v143, 0, v72, s[6:7]
	v_cndmask_b32_e64 v144, 0, v71, s[6:7]
	v_cndmask_b32_e64 v145, 0, v70, s[6:7]
	v_and_b32_e32 v67, 0xffff0000, v136
	v_and_b32_e32 v66, 0xffff0000, v139
	v_and_b32_e32 v73, 0xffff0000, v68
	v_and_b32_e32 v72, 0xffff0000, v69
	v_cndmask_b32_e64 v146, 0, v77, s[8:9]
	v_cndmask_b32_e64 v147, 0, v76, s[8:9]
	v_cndmask_b32_e64 v152, 0, v79, s[10:11]
	v_and_b32_e32 v77, 0xffff0000, v144
	v_and_b32_e32 v76, 0xffff0000, v145
	v_mov_b32_e32 v79, v10
	v_pk_add_f32 v[66:67], v[66:67], v[72:73] neg_lo:[0,1] neg_hi:[0,1]
	v_mov_b32_e32 v10, v9
	v_cndmask_b32_e32 v86, 0, v63, vcc
	v_cndmask_b32_e32 v87, 0, v62, vcc
	v_cndmask_b32_e64 v150, 0, v81, s[10:11]
	v_cndmask_b32_e64 v153, 0, v78, s[10:11]
	v_mov_b32_e32 v78, v8
	v_mov_b32_e32 v81, v14
	v_pk_fma_f32 v[8:9], v[10:11], v[66:67], v[72:73]
	v_pk_add_f32 v[66:67], v[76:77], v[72:73] neg_lo:[0,1] neg_hi:[0,1]
	v_mov_b32_e32 v14, v13
	v_cndmask_b32_e64 v154, 0, v85, s[12:13]
	v_cndmask_b32_e64 v155, 0, v84, s[12:13]
	v_lshlrev_b32_e32 v63, 16, v136
	v_lshlrev_b32_e32 v62, 16, v139
	v_lshlrev_b32_e32 v71, 16, v68
	v_lshlrev_b32_e32 v70, 16, v69
	v_pk_fma_f32 v[8:9], v[14:15], v[66:67], v[8:9]
	v_and_b32_e32 v67, 0xffff0000, v86
	v_and_b32_e32 v66, 0xffff0000, v87
	v_and_b32_e32 v85, 0xffff0000, v140
	v_and_b32_e32 v84, 0xffff0000, v141
	v_cndmask_b32_e64 v148, 0, v75, s[8:9]
	v_cndmask_b32_e64 v149, 0, v74, s[8:9]
	v_cndmask_b32_e64 v151, 0, v80, s[10:11]
	v_cndmask_b32_e64 v156, 0, v83, s[12:13]
	v_cndmask_b32_e64 v157, 0, v82, s[12:13]
	v_lshlrev_b32_e32 v75, 16, v144
	v_lshlrev_b32_e32 v74, 16, v145
	v_pk_add_f32 v[62:63], v[62:63], v[70:71] neg_lo:[0,1] neg_hi:[0,1]
	v_mov_b32_e32 v80, v12
	v_lshlrev_b32_e32 v13, 16, v86
	v_lshlrev_b32_e32 v12, 16, v87
	v_lshlrev_b32_e32 v83, 16, v140
	v_lshlrev_b32_e32 v82, 16, v141
	v_lshlrev_b32_e32 v86, 16, v143
	v_and_b32_e32 v141, 0xffff0000, v142
	v_and_b32_e32 v140, 0xffff0000, v143
	s_waitcnt vmcnt(0) lgkmcnt(0)
	v_mov_b32_e32 v143, v18
	v_pk_add_f32 v[66:67], v[66:67], v[84:85] neg_lo:[0,1] neg_hi:[0,1]
	v_mov_b32_e32 v18, v17
	v_pk_fma_f32 v[62:63], v[78:79], v[62:63], v[70:71]
	v_pk_add_f32 v[68:69], v[74:75], v[70:71] neg_lo:[0,1] neg_hi:[0,1]
	v_lshlrev_b32_e32 v87, 16, v142
	v_pk_add_f32 v[12:13], v[12:13], v[82:83] neg_lo:[0,1] neg_hi:[0,1]
	v_mov_b32_e32 v142, v16
	v_mov_b32_e32 v145, v22
	v_pk_fma_f32 v[16:17], v[18:19], v[66:67], v[84:85]
	v_pk_add_f32 v[66:67], v[140:141], v[84:85] neg_lo:[0,1] neg_hi:[0,1]
	v_mov_b32_e32 v22, v21
	v_pk_fma_f32 v[62:63], v[80:81], v[68:69], v[62:63]
	s_nop 0
	v_cvt_pk_bf16_f32 v210, v63, v9
	v_cvt_pk_bf16_f32 v211, v62, v8
	v_pk_fma_f32 v[12:13], v[142:143], v[12:13], v[82:83]
	v_pk_add_f32 v[68:69], v[86:87], v[82:83] neg_lo:[0,1] neg_hi:[0,1]
	v_mov_b32_e32 v144, v20
	v_pk_fma_f32 v[16:17], v[22:23], v[66:67], v[16:17]
	v_pk_fma_f32 v[12:13], v[144:145], v[68:69], v[12:13]
	s_nop 0
	v_cvt_pk_bf16_f32 v208, v13, v17
	v_cvt_pk_bf16_f32 v209, v12, v16
	v_lshl_add_u64 v[60:61], v[88:89], 0, s[40:41]
	v_mov_b32_e32 v69, v208
	v_mov_b32_e32 v68, v209
	v_mov_b32_e32 v67, v210
	v_mov_b32_e32 v66, v211
	v_lshl_add_u64 v[8:9], v[60:61], 0, v[38:39]
	global_store_dwordx4 v[8:9], v[66:69], off
	v_lshlrev_b32_e32 v9, 16, v148
	v_lshlrev_b32_e32 v8, 16, v149
	v_pk_add_f32 v[16:17], v[70:71], v[74:75] neg_lo:[0,1] neg_hi:[0,1]
	v_pk_add_f32 v[20:21], v[8:9], v[74:75] neg_lo:[0,1] neg_hi:[0,1]
	v_pk_fma_f32 v[16:17], v[78:79], v[16:17], v[74:75]
	v_and_b32_e32 v13, 0xffff0000, v148
	v_and_b32_e32 v12, 0xffff0000, v149
	v_pk_fma_f32 v[16:17], v[80:81], v[20:21], v[16:17]
	v_pk_add_f32 v[20:21], v[72:73], v[76:77] neg_lo:[0,1] neg_hi:[0,1]
	v_pk_add_f32 v[62:63], v[12:13], v[76:77] neg_lo:[0,1] neg_hi:[0,1]
	v_pk_fma_f32 v[20:21], v[10:11], v[20:21], v[76:77]
	v_pk_add_f32 v[66:67], v[82:83], v[86:87] neg_lo:[0,1] neg_hi:[0,1]
	v_pk_fma_f32 v[20:21], v[14:15], v[62:63], v[20:21]
	s_nop 0
	v_cvt_pk_bf16_f32 v210, v17, v21
	v_cvt_pk_bf16_f32 v211, v16, v20
	v_lshlrev_b32_e32 v63, 16, v146
	v_lshlrev_b32_e32 v62, 16, v147
	v_pk_fma_f32 v[66:67], v[142:143], v[66:67], v[86:87]
	v_pk_add_f32 v[68:69], v[62:63], v[86:87] neg_lo:[0,1] neg_hi:[0,1]
	v_and_b32_e32 v71, 0xffff0000, v146
	v_and_b32_e32 v70, 0xffff0000, v147
	v_pk_fma_f32 v[66:67], v[144:145], v[68:69], v[66:67]
	v_pk_add_f32 v[68:69], v[84:85], v[140:141] neg_lo:[0,1] neg_hi:[0,1]
	v_pk_add_f32 v[72:73], v[70:71], v[140:141] neg_lo:[0,1] neg_hi:[0,1]
	v_pk_fma_f32 v[68:69], v[18:19], v[68:69], v[140:141]
	s_nop 0
	v_pk_fma_f32 v[68:69], v[22:23], v[72:73], v[68:69]
	s_nop 0
	v_cvt_pk_bf16_f32 v208, v67, v69
	v_cvt_pk_bf16_f32 v209, v66, v68
	v_mov_b32_e32 v69, v208
	v_mov_b32_e32 v68, v209
	v_mov_b32_e32 v67, v210
	v_mov_b32_e32 v66, v211
	v_lshl_add_u64 v[16:17], v[60:61], 0, v[40:41]
	global_store_dwordx4 v[16:17], v[66:69], off
	v_lshlrev_b32_e32 v17, 16, v152
	v_lshlrev_b32_e32 v16, 16, v153
	v_pk_add_f32 v[72:73], v[74:75], v[8:9] neg_lo:[0,1] neg_hi:[0,1]
	v_pk_add_f32 v[66:67], v[16:17], v[8:9] neg_lo:[0,1] neg_hi:[0,1]
	v_pk_fma_f32 v[72:73], v[78:79], v[72:73], v[8:9]
	v_and_b32_e32 v21, 0xffff0000, v152
	v_and_b32_e32 v20, 0xffff0000, v153
	v_pk_fma_f32 v[66:67], v[80:81], v[66:67], v[72:73]
	v_pk_add_f32 v[72:73], v[76:77], v[12:13] neg_lo:[0,1] neg_hi:[0,1]
	v_pk_add_f32 v[68:69], v[20:21], v[12:13] neg_lo:[0,1] neg_hi:[0,1]
	v_pk_fma_f32 v[72:73], v[10:11], v[72:73], v[12:13]
	v_pk_add_f32 v[84:85], v[86:87], v[62:63] neg_lo:[0,1] neg_hi:[0,1]
	v_pk_fma_f32 v[68:69], v[14:15], v[68:69], v[72:73]
	s_nop 0
	v_cvt_pk_bf16_f32 v210, v67, v69
	v_cvt_pk_bf16_f32 v211, v66, v68
	v_lshlrev_b32_e32 v73, 16, v150
	v_lshlrev_b32_e32 v72, 16, v151
	v_pk_add_f32 v[76:77], v[72:73], v[62:63] neg_lo:[0,1] neg_hi:[0,1]
	v_pk_fma_f32 v[84:85], v[142:143], v[84:85], v[62:63]
	v_and_b32_e32 v75, 0xffff0000, v150
	v_and_b32_e32 v74, 0xffff0000, v151
	v_pk_fma_f32 v[76:77], v[144:145], v[76:77], v[84:85]
	v_pk_add_f32 v[84:85], v[140:141], v[70:71] neg_lo:[0,1] neg_hi:[0,1]
	v_pk_add_f32 v[82:83], v[74:75], v[70:71] neg_lo:[0,1] neg_hi:[0,1]
	v_pk_fma_f32 v[84:85], v[18:19], v[84:85], v[70:71]
	s_nop 0
	v_pk_fma_f32 v[82:83], v[22:23], v[82:83], v[84:85]
	s_nop 0
	v_cvt_pk_bf16_f32 v208, v77, v83
	v_cvt_pk_bf16_f32 v209, v76, v82
	v_mov_b32_e32 v69, v208
	v_mov_b32_e32 v68, v209
	v_mov_b32_e32 v67, v210
	v_mov_b32_e32 v66, v211
	v_lshl_add_u64 v[76:77], v[60:61], 0, v[42:43]
	global_store_dwordx4 v[76:77], v[66:69], off
	v_pk_add_f32 v[8:9], v[8:9], v[16:17] neg_lo:[0,1] neg_hi:[0,1]
	v_pk_add_f32 v[12:13], v[12:13], v[20:21] neg_lo:[0,1] neg_hi:[0,1]
	v_lshlrev_b32_e32 v67, 16, v156
	v_lshlrev_b32_e32 v66, 16, v157
	v_and_b32_e32 v69, 0xffff0000, v156
	v_and_b32_e32 v68, 0xffff0000, v157
	v_pk_add_f32 v[66:67], v[66:67], v[16:17] neg_lo:[0,1] neg_hi:[0,1]
	v_pk_add_f32 v[68:69], v[68:69], v[20:21] neg_lo:[0,1] neg_hi:[0,1]
	v_pk_fma_f32 v[8:9], v[78:79], v[8:9], v[16:17]
	v_pk_fma_f32 v[10:11], v[10:11], v[12:13], v[20:21]
	v_lshlrev_b32_e32 v13, 16, v154
	v_lshlrev_b32_e32 v12, 16, v155
	v_pk_add_f32 v[16:17], v[62:63], v[72:73] neg_lo:[0,1] neg_hi:[0,1]
	v_pk_fma_f32 v[10:11], v[14:15], v[68:69], v[10:11]
	v_and_b32_e32 v15, 0xffff0000, v154
	v_and_b32_e32 v14, 0xffff0000, v155
	v_pk_add_f32 v[12:13], v[12:13], v[72:73] neg_lo:[0,1] neg_hi:[0,1]
	v_pk_add_f32 v[20:21], v[70:71], v[74:75] neg_lo:[0,1] neg_hi:[0,1]
	v_pk_fma_f32 v[16:17], v[142:143], v[16:17], v[72:73]
	v_pk_add_f32 v[14:15], v[14:15], v[74:75] neg_lo:[0,1] neg_hi:[0,1]
	v_pk_fma_f32 v[12:13], v[144:145], v[12:13], v[16:17]
	v_pk_fma_f32 v[16:17], v[18:19], v[20:21], v[74:75]
	v_pk_fma_f32 v[8:9], v[80:81], v[66:67], v[8:9]
	s_nop 0
	v_cvt_pk_bf16_f32 v210, v9, v11
	v_cvt_pk_bf16_f32 v211, v8, v10
	v_pk_fma_f32 v[14:15], v[22:23], v[14:15], v[16:17]
	s_nop 0
	v_cvt_pk_bf16_f32 v208, v13, v15
	v_cvt_pk_bf16_f32 v209, v12, v14
	v_mov_b32_e32 v11, v208
	v_mov_b32_e32 v10, v209
	v_mov_b32_e32 v9, v210
	v_mov_b32_e32 v8, v211
	v_lshl_add_u64 v[12:13], v[60:61], 0, v[44:45]
	global_store_dwordx4 v[12:13], v[8:11], off
	v_lshl_add_u64 v[12:13], v[88:89], 0, s[44:45]
	v_lshl_add_u64 v[14:15], v[12:13], 0, v[26:27]
	v_lshl_add_u64 v[8:9], v[12:13], 0, v[24:25]
	global_load_dwordx4 v[8:11], v[8:9], off
	v_lshl_add_u64 v[26:27], v[28:29], 0, s[42:43]
	global_load_dwordx4 v[22:25], v[14:15], off
	v_lshl_add_u64 v[14:15], v[12:13], 0, v[48:49]
	global_load_dwordx4 v[60:63], v[14:15], off
	v_lshl_add_u64 v[14:15], v[12:13], 0, v[54:55]
	global_load_dwordx4 v[66:69], v[14:15], off
	v_lshl_add_u64 v[14:15], v[12:13], 0, v[56:57]
	global_load_dwordx4 v[54:57], v[14:15], off
	v_lshl_add_u64 v[12:13], v[12:13], 0, v[58:59]
	global_load_dwordx4 v[70:73], v[12:13], off
	s_nop 0
	global_load_dwordx2 v[12:13], v[32:33], off offset:448
	global_load_dwordx4 v[18:21], v[50:51], off offset:1536
	global_load_dwordx4 v[14:17], v[52:53], off offset:1536
	v_lshl_add_u64 v[28:29], v[46:47], 0, s[42:43]
	v_lshl_add_u64 v[52:53], v[88:89], 0, s[46:47]
	v_lshl_add_u64 v[46:47], v[52:53], 0, v[38:39]
	v_lshl_add_u64 v[48:49], v[52:53], 0, v[40:41]
	v_lshl_add_u64 v[50:51], v[52:53], 0, v[42:43]
	v_lshl_add_u64 v[52:53], v[52:53], 0, v[44:45]
	v_and_b32_e32 v136, 0xffffffc0, v135
	s_waitcnt vmcnt(0) lgkmcnt(0)
	v_cndmask_b32_e32 v82, 0, v9, vcc
	v_cndmask_b32_e32 v83, 0, v8, vcc
	v_cndmask_b32_e64 v147, 0, v25, s[4:5]
	v_cndmask_b32_e64 v148, 0, v24, s[4:5]
	v_cndmask_b32_e64 v58, 0, v23, s[4:5]
	v_cndmask_b32_e64 v59, 0, v22, s[4:5]
	global_load_dwordx4 v[22:25], v[26:27], off offset:16
	v_cndmask_b32_e32 v139, 0, v11, vcc
	global_load_dwordx4 v[26:29], v[28:29], off offset:16
	v_cndmask_b32_e64 v55, 0, v55, s[10:11]
	v_cndmask_b32_e64 v54, 0, v54, s[10:11]
	v_cndmask_b32_e32 v146, 0, v10, vcc
	v_cndmask_b32_e64 v61, 0, v61, s[6:7]
	v_cndmask_b32_e64 v60, 0, v60, s[6:7]
	v_cndmask_b32_e64 v153, 0, v57, s[10:11]
	v_cndmask_b32_e64 v154, 0, v56, s[10:11]
	v_cndmask_b32_e64 v157, 0, v71, s[12:13]
	v_cndmask_b32_e64 v158, 0, v70, s[12:13]
	v_lshlrev_b32_e32 v8, 16, v83
	v_lshlrev_b32_e32 v9, 16, v82
	v_lshlrev_b32_e32 v10, 16, v59
	v_lshlrev_b32_e32 v11, 16, v58
	v_lshlrev_b32_e32 v70, 16, v54
	v_lshlrev_b32_e32 v71, 16, v55
	v_readfirstlane_b32 s1, v13
	v_readfirstlane_b32 s0, v12
	v_and_b32_e32 v79, 0xffff0000, v55
	v_and_b32_e32 v78, 0xffff0000, v54
	v_and_b32_e32 v55, 0xffff0000, v58
	v_and_b32_e32 v54, 0xffff0000, v59
	v_and_b32_e32 v57, 0xffff0000, v82
	v_and_b32_e32 v56, 0xffff0000, v83
	v_cndmask_b32_e64 v149, 0, v63, s[6:7]
	v_cndmask_b32_e64 v150, 0, v62, s[6:7]
	v_lshlrev_b32_e32 v62, 16, v60
	v_lshlrev_b32_e32 v63, 16, v61
	v_lshl_add_u64 v[12:13], s[0:1], 0, v[64:65]
	v_pk_add_f32 v[8:9], v[8:9], v[10:11] neg_lo:[0,1] neg_hi:[0,1]
	v_pk_add_f32 v[56:57], v[56:57], v[54:55] neg_lo:[0,1] neg_hi:[0,1]
	v_mov_b32_e32 v82, v18
	v_mov_b32_e32 v83, v20
	v_mov_b32_e32 v20, v19
	v_pk_add_f32 v[58:59], v[10:11], v[62:63] neg_lo:[0,1] neg_hi:[0,1]
	v_pk_fma_f32 v[140:141], v[82:83], v[8:9], v[10:11]
	v_pk_fma_f32 v[18:19], v[20:21], v[56:57], v[54:55]
	v_pk_add_f32 v[56:57], v[62:63], v[10:11] neg_lo:[0,1] neg_hi:[0,1]
	global_load_dwordx4 v[8:11], v[12:13], off offset:1024
	v_mov_b32_e32 v144, v14
	v_mov_b32_e32 v145, v16
	v_mov_b32_e32 v16, v15
	global_load_dwordx4 v[12:15], v[12:13], off offset:1040
	v_cndmask_b32_e64 v67, 0, v67, s[8:9]
	v_cndmask_b32_e64 v66, 0, v66, s[8:9]
	v_cndmask_b32_e64 v151, 0, v69, s[8:9]
	v_cndmask_b32_e64 v152, 0, v68, s[8:9]
	v_lshlrev_b32_e32 v68, 16, v66
	v_lshlrev_b32_e32 v69, 16, v67
	v_and_b32_e32 v77, 0xffff0000, v67
	v_and_b32_e32 v76, 0xffff0000, v66
	v_and_b32_e32 v67, 0xffff0000, v61
	v_and_b32_e32 v66, 0xffff0000, v60
	v_pk_add_f32 v[142:143], v[66:67], v[54:55] neg_lo:[0,1] neg_hi:[0,1]
	v_pk_add_f32 v[60:61], v[54:55], v[66:67] neg_lo:[0,1] neg_hi:[0,1]
	v_pk_fma_f32 v[54:55], v[144:145], v[56:57], v[140:141]
	v_pk_fma_f32 v[56:57], v[16:17], v[142:143], v[18:19]
	v_pk_fma_f32 v[18:19], v[82:83], v[58:59], v[62:63]
	v_pk_add_f32 v[58:59], v[68:69], v[62:63] neg_lo:[0,1] neg_hi:[0,1]
	v_and_b32_e32 v141, 0xffff0000, v157
	v_pk_fma_f32 v[58:59], v[144:145], v[58:59], v[18:19]
	v_pk_fma_f32 v[18:19], v[20:21], v[60:61], v[66:67]
	v_pk_add_f32 v[60:61], v[76:77], v[66:67] neg_lo:[0,1] neg_hi:[0,1]
	v_and_b32_e32 v140, 0xffff0000, v158
	v_pk_fma_f32 v[60:61], v[16:17], v[60:61], v[18:19]
	v_pk_add_f32 v[18:19], v[62:63], v[68:69] neg_lo:[0,1] neg_hi:[0,1]
	v_pk_add_f32 v[62:63], v[70:71], v[68:69] neg_lo:[0,1] neg_hi:[0,1]
	v_pk_fma_f32 v[18:19], v[82:83], v[18:19], v[68:69]
	v_pk_add_f32 v[68:69], v[68:69], v[70:71] neg_lo:[0,1] neg_hi:[0,1]
	v_pk_fma_f32 v[62:63], v[144:145], v[62:63], v[18:19]
	v_pk_add_f32 v[18:19], v[66:67], v[76:77] neg_lo:[0,1] neg_hi:[0,1]
	v_pk_add_f32 v[66:67], v[78:79], v[76:77] neg_lo:[0,1] neg_hi:[0,1]
	v_pk_fma_f32 v[18:19], v[20:21], v[18:19], v[76:77]
	v_pk_fma_f32 v[68:69], v[82:83], v[68:69], v[70:71]
	v_pk_fma_f32 v[66:67], v[16:17], v[66:67], v[18:19]
	v_lshlrev_b32_e32 v19, 16, v157
	v_lshlrev_b32_e32 v18, 16, v158
	v_pk_add_f32 v[18:19], v[18:19], v[70:71] neg_lo:[0,1] neg_hi:[0,1]
	v_cndmask_b32_e64 v155, 0, v73, s[12:13]
	v_pk_fma_f32 v[68:69], v[144:145], v[18:19], v[68:69]
	v_pk_add_f32 v[18:19], v[76:77], v[78:79] neg_lo:[0,1] neg_hi:[0,1]
	v_cndmask_b32_e64 v156, 0, v72, s[12:13]
	v_lshlrev_b32_e32 v74, 16, v146
	v_lshlrev_b32_e32 v75, 16, v139
	v_lshlrev_b32_e32 v72, 16, v148
	v_lshlrev_b32_e32 v73, 16, v147
	v_pk_fma_f32 v[18:19], v[20:21], v[18:19], v[78:79]
	v_pk_add_f32 v[20:21], v[140:141], v[78:79] neg_lo:[0,1] neg_hi:[0,1]
	v_and_b32_e32 v77, 0xffff0000, v147
	v_and_b32_e32 v76, 0xffff0000, v148
	v_and_b32_e32 v141, 0xffff0000, v139
	v_and_b32_e32 v140, 0xffff0000, v146
	v_lshlrev_b32_e32 v80, 16, v150
	v_lshlrev_b32_e32 v81, 16, v149
	v_pk_fma_f32 v[70:71], v[16:17], v[20:21], v[18:19]
	v_and_b32_e32 v17, 0xffff0000, v149
	v_and_b32_e32 v16, 0xffff0000, v150
	v_pk_add_f32 v[74:75], v[74:75], v[72:73] neg_lo:[0,1] neg_hi:[0,1]
	v_pk_add_f32 v[140:141], v[140:141], v[76:77] neg_lo:[0,1] neg_hi:[0,1]
	s_waitcnt vmcnt(0) lgkmcnt(0)
	v_mov_b32_e32 v142, v22
	v_mov_b32_e32 v143, v24
	v_mov_b32_e32 v24, v23
	v_lshlrev_b32_e32 v86, 16, v152
	v_lshlrev_b32_e32 v87, 16, v151
	v_pk_add_f32 v[78:79], v[72:73], v[80:81] neg_lo:[0,1] neg_hi:[0,1]
	v_pk_add_f32 v[82:83], v[76:77], v[16:17] neg_lo:[0,1] neg_hi:[0,1]
	v_pk_fma_f32 v[74:75], v[142:143], v[74:75], v[72:73]
	v_pk_fma_f32 v[22:23], v[24:25], v[140:141], v[76:77]
	v_pk_add_f32 v[72:73], v[80:81], v[72:73] neg_lo:[0,1] neg_hi:[0,1]
	v_pk_add_f32 v[76:77], v[16:17], v[76:77] neg_lo:[0,1] neg_hi:[0,1]
	v_mov_b32_e32 v140, v26
	v_mov_b32_e32 v141, v28
	v_mov_b32_e32 v28, v27
	v_and_b32_e32 v19, 0xffff0000, v151
	v_and_b32_e32 v18, 0xffff0000, v152
	v_pk_fma_f32 v[72:73], v[140:141], v[72:73], v[74:75]
	v_pk_fma_f32 v[74:75], v[28:29], v[76:77], v[22:23]
	v_pk_fma_f32 v[22:23], v[142:143], v[78:79], v[80:81]
	v_pk_add_f32 v[26:27], v[86:87], v[80:81] neg_lo:[0,1] neg_hi:[0,1]
	v_lshlrev_b32_e32 v84, 16, v154
	v_pk_fma_f32 v[76:77], v[140:141], v[26:27], v[22:23]
	v_pk_fma_f32 v[22:23], v[24:25], v[82:83], v[16:17]
	v_pk_add_f32 v[26:27], v[18:19], v[16:17] neg_lo:[0,1] neg_hi:[0,1]
	v_lshlrev_b32_e32 v85, 16, v153
	v_pk_fma_f32 v[78:79], v[28:29], v[26:27], v[22:23]
	v_pk_add_f32 v[22:23], v[80:81], v[86:87] neg_lo:[0,1] neg_hi:[0,1]
	v_and_b32_e32 v21, 0xffff0000, v153
	v_and_b32_e32 v20, 0xffff0000, v154
	v_pk_fma_f32 v[22:23], v[142:143], v[22:23], v[86:87]
	v_pk_add_f32 v[26:27], v[84:85], v[86:87] neg_lo:[0,1] neg_hi:[0,1]
	v_pk_add_f32 v[16:17], v[16:17], v[18:19] neg_lo:[0,1] neg_hi:[0,1]
	v_pk_fma_f32 v[80:81], v[140:141], v[26:27], v[22:23]
	v_pk_fma_f32 v[16:17], v[24:25], v[16:17], v[18:19]
	v_pk_add_f32 v[22:23], v[20:21], v[18:19] neg_lo:[0,1] neg_hi:[0,1]
	v_and_b32_e32 v27, 0xffff0000, v155
	v_pk_fma_f32 v[82:83], v[28:29], v[22:23], v[16:17]
	v_pk_add_f32 v[16:17], v[86:87], v[84:85] neg_lo:[0,1] neg_hi:[0,1]
	v_lshlrev_b32_e32 v23, 16, v155
	v_pk_fma_f32 v[86:87], v[142:143], v[16:17], v[84:85]
	v_mov_b32_e32 v16, v8
	v_mov_b32_e32 v17, v10
	v_mov_b32_e32 v10, v9
	v_pk_mul_f32 v[142:143], v[16:17], v[54:55]
	v_pk_mul_f32 v[144:145], v[56:57], v[10:11]
	v_mov_b32_e32 v8, v143
	v_mov_b32_e32 v9, v145
	v_pk_mul_f32 v[146:147], v[8:9], v[8:9]
	v_mov_b32_e32 v8, v12
	v_mov_b32_e32 v9, v14
	v_mov_b32_e32 v14, v13
	v_mul_f32_e32 v139, v142, v142
	v_pk_mul_f32 v[148:149], v[72:73], v[8:9]
	v_pk_mul_f32 v[12:13], v[74:75], v[14:15]
	v_fmac_f32_e32 v139, v144, v144
	v_mov_b32_e32 v150, v148
	v_mov_b32_e32 v151, v12
	v_add_f32_e32 v139, v139, v146
	v_pk_mul_f32 v[150:151], v[150:151], v[150:151]
	v_add_f32_e32 v139, v139, v147
	v_mov_b32_e32 v152, v149
	v_mov_b32_e32 v153, v13
	v_add_f32_e32 v139, v139, v150
	v_pk_mul_f32 v[152:153], v[152:153], v[152:153]
	v_add_f32_e32 v139, v139, v151
	v_add_f32_e32 v139, v139, v152
	v_add_f32_e32 v139, v139, v153
	v_lshlrev_b32_e32 v22, 16, v156
	v_pk_add_f32 v[22:23], v[22:23], v[84:85] neg_lo:[0,1] neg_hi:[0,1]
	v_add_f32_dpp v139, v139, v139 quad_perm:[1,0,3,2] row_mask:0xf bank_mask:0xf bound_ctrl:1
	v_pk_fma_f32 v[84:85], v[140:141], v[22:23], v[86:87]
	v_and_b32_e32 v26, 0xffff0000, v156
	v_add_f32_dpp v139, v139, v139 quad_perm:[2,3,0,1] row_mask:0xf bank_mask:0xf bound_ctrl:1
	v_pk_add_f32 v[18:19], v[18:19], v[20:21] neg_lo:[0,1] neg_hi:[0,1]
	v_pk_mul_f32 v[140:141], v[78:79], v[14:15]
	v_add_f32_dpp v139, v139, v139 row_half_mirror row_mask:0xf bank_mask:0xf bound_ctrl:1
	v_mul_f32_e32 v146, 0x4f800000, v139
	v_cmp_gt_f32_e32 vcc, s71, v139
	v_pk_fma_f32 v[18:19], v[24:25], v[18:19], v[20:21]
	v_pk_add_f32 v[20:21], v[26:27], v[20:21] neg_lo:[0,1] neg_hi:[0,1]
	v_cndmask_b32_e32 v139, v139, v146, vcc
	v_sqrt_f32_e32 v146, v139
	v_mul_f32_e32 v156, v36, v5
	v_mul_f32_e32 v157, v31, v6
	v_mul_f32_e32 v158, v37, v7
	v_add_u32_e32 v22, -1, v146
	v_fma_f32 v23, -v22, v146, v139
	v_cmp_ge_f32_e64 s[0:1], 0, v23
	v_add_u32_e32 v23, 1, v146
	v_fma_f32 v86, -v23, v146, v139
	v_cndmask_b32_e64 v22, v146, v22, s[0:1]
	v_cmp_lt_f32_e64 s[0:1], 0, v86
	v_pk_fma_f32 v[86:87], v[28:29], v[20:21], v[18:19]
	v_pk_mul_f32 v[28:29], v[76:77], v[8:9]
	v_cndmask_b32_e64 v22, v22, v23, s[0:1]
	v_mul_f32_e32 v23, 0x37800000, v22
	v_cndmask_b32_e32 v22, v22, v23, vcc
	v_cmp_class_f32_e32 vcc, v139, v128
	v_lshlrev_b64 v[36:37], 11, v[94:95]
	v_lshl_add_u64 v[36:37], s[54:55], 0, v[36:37]
	v_cndmask_b32_e32 v22, v22, v139, vcc
	v_max_f32_e32 v22, 0x2b8cbccc, v22
	v_div_scale_f32 v23, s[0:1], v22, v22, 1.0
	v_rcp_f32_e32 v139, v23
	v_lshl_add_u64 v[36:37], v[36:37], 0, v[34:35]
	v_mul_f32_e32 v121, v156, v56
	v_mul_f32_e32 v122, v157, v55
	v_fma_f32 v18, -v23, v139, 1.0
	v_fmac_f32_e32 v139, v18, v139
	v_div_scale_f32 v18, vcc, 1.0, v22, 1.0
	v_mul_f32_e32 v19, v18, v139
	v_fma_f32 v20, -v23, v19, v18
	v_fmac_f32_e32 v19, v20, v139
	v_fma_f32 v18, -v23, v19, v18
	v_div_fmas_f32 v18, v18, v139, v19
	v_div_fixup_f32 v18, v18, v22, 1.0
	v_pk_mul_f32 v[20:21], v[142:143], v[18:19] op_sel_hi:[1,0]
	v_pk_mul_f32 v[22:23], v[148:149], v[18:19] op_sel_hi:[1,0]
	v_bfe_u32 v19, v20, 16, 1
	v_bfe_u32 v24, v21, 16, 1
	v_bfe_u32 v25, v22, 16, 1
	v_bfe_u32 v26, v23, 16, 1
	v_add3_u32 v23, v23, v26, s60
	v_add3_u32 v22, v22, v25, s60
	v_add3_u32 v21, v21, v24, s60
	v_add3_u32 v19, v20, v19, s60
	v_pk_mul_f32 v[24:25], v[58:59], v[16:17]
	v_pk_mul_f32 v[26:27], v[60:61], v[10:11]
	v_lshrrev_b32_e32 v139, 16, v19
	v_lshrrev_b32_e32 v19, 16, v21
	v_mov_b32_e32 v20, v27
	v_mov_b32_e32 v21, v25
	v_mul_f32_e32 v148, v24, v24
	v_pk_mul_f32 v[20:21], v[20:21], v[20:21]
	v_fmac_f32_e32 v148, v26, v26
	v_mov_b32_e32 v142, v140
	v_mov_b32_e32 v143, v28
	v_add_f32_e32 v21, v21, v148
	v_pk_mul_f32 v[142:143], v[142:143], v[142:143]
	v_add_f32_e32 v20, v20, v21
	v_lshrrev_b32_e32 v146, 16, v22
	v_lshrrev_b32_e32 v147, 16, v23
	v_pk_mul_f32 v[22:23], v[144:145], v[18:19] op_sel_hi:[1,0]
	v_mov_b32_e32 v144, v141
	v_mov_b32_e32 v145, v29
	v_add_f32_e32 v20, v143, v20
	v_pk_mul_f32 v[144:145], v[144:145], v[144:145]
	v_add_f32_e32 v20, v142, v20
	v_add_f32_e32 v20, v145, v20
	v_add_f32_e32 v20, v144, v20
	v_pk_mul_f32 v[12:13], v[12:13], v[18:19] op_sel_hi:[1,0]
	v_and_or_b32 v19, v23, s56, v19
	v_add_f32_dpp v20, v20, v20 quad_perm:[1,0,3,2] row_mask:0xf bank_mask:0xf bound_ctrl:1
	v_mul_f32_e32 v123, v158, v57
	v_mul_f32_e32 v124, v163, v58
	v_add_f32_dpp v20, v20, v20 quad_perm:[2,3,0,1] row_mask:0xf bank_mask:0xf bound_ctrl:1
	v_mul_f32_e32 v125, v168, v60
	v_mul_f32_e32 v137, v169, v59
	v_add_f32_dpp v20, v20, v20 row_half_mirror row_mask:0xf bank_mask:0xf bound_ctrl:1
	v_mul_f32_e32 v21, 0x4f800000, v20
	v_cmp_gt_f32_e32 vcc, s71, v20
	v_mul_f32_e32 v156, v116, v82
	v_mul_f32_e32 v157, v115, v81
	v_cndmask_b32_e32 v142, v20, v21, vcc
	v_sqrt_f32_e32 v143, v142
	v_and_or_b32 v20, v12, s56, v146
	v_and_or_b32 v21, v13, s56, v147
	v_mul_f32_e32 v158, v117, v83
	v_add_u32_e32 v12, -1, v143
	v_fma_f32 v13, -v12, v143, v142
	v_cmp_ge_f32_e64 s[0:1], 0, v13
	v_add_u32_e32 v13, 1, v143
	v_fma_f32 v18, -v13, v143, v142
	v_cndmask_b32_e64 v12, v143, v12, s[0:1]
	v_cmp_lt_f32_e64 s[0:1], 0, v18
	v_and_or_b32 v18, v22, s56, v139
	global_store_dwordx4 v[46:47], v[18:21], off
	v_cndmask_b32_e64 v12, v12, v13, s[0:1]
	v_mul_f32_e32 v13, 0x37800000, v12
	v_cndmask_b32_e32 v12, v12, v13, vcc
	v_cmp_class_f32_e32 vcc, v142, v128
	s_nop 1
	v_cndmask_b32_e32 v12, v12, v142, vcc
	v_max_f32_e32 v12, 0x2b8cbccc, v12
	v_div_scale_f32 v13, s[0:1], v12, v12, 1.0
	v_rcp_f32_e32 v142, v13
	s_nop 0
	v_fma_f32 v18, -v13, v142, 1.0
	v_fmac_f32_e32 v142, v18, v142
	v_div_scale_f32 v18, vcc, 1.0, v12, 1.0
	v_mul_f32_e32 v19, v18, v142
	v_fma_f32 v20, -v13, v19, v18
	v_fmac_f32_e32 v19, v20, v142
	v_fma_f32 v13, -v13, v19, v18
	v_div_fmas_f32 v13, v13, v142, v19
	v_div_fixup_f32 v12, v13, v12, 1.0
	v_pk_mul_f32 v[18:19], v[24:25], v[12:13] op_sel_hi:[1,0]
	v_pk_mul_f32 v[20:21], v[28:29], v[12:13] op_sel_hi:[1,0]
	v_bfe_u32 v13, v18, 16, 1
	v_bfe_u32 v22, v19, 16, 1
	v_bfe_u32 v23, v20, 16, 1
	v_bfe_u32 v24, v21, 16, 1
	v_add3_u32 v21, v21, v24, s60
	v_add3_u32 v20, v20, v23, s60
	v_add3_u32 v19, v19, v22, s60
	v_add3_u32 v13, v18, v13, s60
	v_pk_mul_f32 v[22:23], v[16:17], v[62:63]
	v_pk_mul_f32 v[24:25], v[66:67], v[10:11]
	v_lshrrev_b32_e32 v139, 16, v13
	v_lshrrev_b32_e32 v146, 16, v19
	v_lshrrev_b32_e32 v147, 16, v20
	v_lshrrev_b32_e32 v148, 16, v21
	v_pk_mul_f32 v[18:19], v[26:27], v[12:13] op_sel_hi:[1,0]
	v_mov_b32_e32 v20, v25
	v_mov_b32_e32 v21, v23
	v_mul_f32_e32 v13, v22, v22
	v_pk_mul_f32 v[20:21], v[20:21], v[20:21]
	v_pk_mul_f32 v[26:27], v[80:81], v[8:9]
	v_pk_mul_f32 v[28:29], v[82:83], v[14:15]
	v_fmac_f32_e32 v13, v24, v24
	v_mov_b32_e32 v142, v28
	v_mov_b32_e32 v143, v26
	v_add_f32_e32 v13, v21, v13
	v_pk_mul_f32 v[142:143], v[142:143], v[142:143]
	v_add_f32_e32 v13, v20, v13
	v_mov_b32_e32 v144, v29
	v_mov_b32_e32 v145, v27
	v_add_f32_e32 v13, v143, v13
	v_pk_mul_f32 v[144:145], v[144:145], v[144:145]
	v_add_f32_e32 v13, v142, v13
	v_add_f32_e32 v13, v145, v13
	v_add_f32_e32 v13, v144, v13
	v_and_or_b32 v19, v19, s56, v146
	v_and_or_b32 v18, v18, s56, v139
	v_add_f32_dpp v13, v13, v13 quad_perm:[1,0,3,2] row_mask:0xf bank_mask:0xf bound_ctrl:1
	v_pk_mul_f32 v[16:17], v[16:17], v[68:69]
	v_pk_mul_f32 v[14:15], v[86:87], v[14:15]
	v_add_f32_dpp v13, v13, v13 quad_perm:[2,3,0,1] row_mask:0xf bank_mask:0xf bound_ctrl:1
	s_nop 1
	v_add_f32_dpp v13, v13, v13 row_half_mirror row_mask:0xf bank_mask:0xf bound_ctrl:1
	v_mul_f32_e32 v20, 0x4f800000, v13
	v_cmp_gt_f32_e32 vcc, s71, v13
	s_nop 1
	v_cndmask_b32_e32 v142, v13, v20, vcc
	v_sqrt_f32_e32 v143, v142
	v_pk_mul_f32 v[12:13], v[140:141], v[12:13] op_sel_hi:[1,0]
	s_nop 0
	v_and_or_b32 v20, v12, s56, v147
	v_add_u32_e32 v12, -1, v143
	v_and_or_b32 v21, v13, s56, v148
	v_fma_f32 v13, -v12, v143, v142
	v_cmp_ge_f32_e64 s[0:1], 0, v13
	v_add_u32_e32 v13, 1, v143
	v_fma_f32 v140, -v13, v143, v142
	v_cndmask_b32_e64 v12, v143, v12, s[0:1]
	v_cmp_lt_f32_e64 s[0:1], 0, v140
	global_store_dwordx4 v[48:49], v[18:21], off
	s_nop 0
	v_cndmask_b32_e64 v12, v12, v13, s[0:1]
	v_mul_f32_e32 v13, 0x37800000, v12
	v_cndmask_b32_e32 v12, v12, v13, vcc
	v_cmp_class_f32_e32 vcc, v142, v128
	s_nop 1
	v_cndmask_b32_e32 v12, v12, v142, vcc
	v_max_f32_e32 v12, 0x2b8cbccc, v12
	v_div_scale_f32 v13, s[0:1], v12, v12, 1.0
	v_rcp_f32_e32 v140, v13
	s_nop 0
	v_fma_f32 v18, -v13, v140, 1.0
	v_fmac_f32_e32 v140, v18, v140
	v_div_scale_f32 v18, vcc, 1.0, v12, 1.0
	v_mul_f32_e32 v19, v18, v140
	v_fma_f32 v20, -v13, v19, v18
	v_fmac_f32_e32 v19, v20, v140
	v_fma_f32 v13, -v13, v19, v18
	v_div_fmas_f32 v13, v13, v140, v19
	v_div_fixup_f32 v12, v13, v12, 1.0
	v_pk_mul_f32 v[20:21], v[26:27], v[12:13] op_sel_hi:[1,0]
	v_pk_mul_f32 v[18:19], v[22:23], v[12:13] op_sel_hi:[1,0]
	v_bfe_u32 v23, v20, 16, 1
	v_bfe_u32 v26, v21, 16, 1
	v_add3_u32 v21, v21, v26, s60
	v_add3_u32 v20, v20, v23, s60
	v_lshrrev_b32_e32 v27, 16, v20
	v_lshrrev_b32_e32 v139, 16, v21
	v_pk_mul_f32 v[20:21], v[10:11], v[70:71]
	v_bfe_u32 v22, v19, 16, 1
	v_mov_b32_e32 v10, v21
	v_mov_b32_e32 v11, v17
	v_mul_f32_e32 v140, v16, v16
	v_bfe_u32 v13, v18, 16, 1
	v_add3_u32 v19, v19, v22, s60
	v_pk_mul_f32 v[10:11], v[10:11], v[10:11]
	v_pk_mul_f32 v[22:23], v[84:85], v[8:9]
	v_fmac_f32_e32 v140, v20, v20
	v_add3_u32 v13, v18, v13, s60
	v_mov_b32_e32 v8, v14
	v_mov_b32_e32 v9, v22
	v_add_f32_e32 v11, v11, v140
	v_lshrrev_b32_e32 v13, 16, v13
	v_pk_mul_f32 v[8:9], v[8:9], v[8:9]
	v_add_f32_e32 v10, v10, v11
	v_lshrrev_b32_e32 v26, 16, v19
	v_pk_mul_f32 v[18:19], v[24:25], v[12:13] op_sel_hi:[1,0]
	v_mov_b32_e32 v24, v15
	v_mov_b32_e32 v25, v23
	v_add_f32_e32 v9, v9, v10
	v_pk_mul_f32 v[24:25], v[24:25], v[24:25]
	v_add_f32_e32 v8, v8, v9
	v_add_f32_e32 v8, v25, v8
	v_add_f32_e32 v8, v24, v8
	s_nop 1
	v_add_f32_dpp v8, v8, v8 quad_perm:[1,0,3,2] row_mask:0xf bank_mask:0xf bound_ctrl:1
	s_nop 1
	v_add_f32_dpp v8, v8, v8 quad_perm:[2,3,0,1] row_mask:0xf bank_mask:0xf bound_ctrl:1
	s_nop 1
	v_add_f32_dpp v8, v8, v8 row_half_mirror row_mask:0xf bank_mask:0xf bound_ctrl:1
	v_mul_f32_e32 v9, 0x4f800000, v8
	v_cmp_gt_f32_e32 vcc, s71, v8
	s_nop 1
	v_cndmask_b32_e32 v24, v8, v9, vcc
	v_sqrt_f32_e32 v25, v24
	v_pk_mul_f32 v[8:9], v[28:29], v[12:13] op_sel_hi:[1,0]
	s_nop 0
	v_and_or_b32 v10, v8, s56, v27
	v_add_u32_e32 v8, -1, v25
	v_and_or_b32 v11, v9, s56, v139
	v_fma_f32 v9, -v8, v25, v24
	v_cmp_ge_f32_e64 s[0:1], 0, v9
	v_add_u32_e32 v9, 1, v25
	v_fma_f32 v12, -v9, v25, v24
	v_cndmask_b32_e64 v8, v25, v8, s[0:1]
	v_cmp_lt_f32_e64 s[0:1], 0, v12
	v_mul_f32_e32 v139, v4, v30
	v_mul_f32_e32 v120, v139, v54
	v_cndmask_b32_e64 v8, v8, v9, s[0:1]
	v_mul_f32_e32 v9, 0x37800000, v8
	v_cndmask_b32_e32 v8, v8, v9, vcc
	v_cmp_class_f32_e32 vcc, v24, v128
	v_and_or_b32 v9, v19, s56, v26
	v_mul_f32_e32 v139, v175, v62
	v_cndmask_b32_e32 v8, v8, v24, vcc
	v_max_f32_e32 v12, 0x2b8cbccc, v8
	v_div_scale_f32 v24, s[0:1], v12, v12, 1.0
	v_rcp_f32_e32 v25, v24
	v_and_or_b32 v8, v18, s56, v13
	global_store_dwordx4 v[50:51], v[8:11], off
	s_nop 1
	v_fma_f32 v8, -v24, v25, 1.0
	v_fmac_f32_e32 v25, v8, v25
	v_div_scale_f32 v8, vcc, 1.0, v12, 1.0
	v_mul_f32_e32 v9, v8, v25
	v_fma_f32 v10, -v24, v9, v8
	v_fmac_f32_e32 v9, v10, v25
	v_fma_f32 v8, -v24, v9, v8
	v_div_fmas_f32 v8, v8, v25, v9
	v_div_fixup_f32 v8, v8, v12, 1.0
	v_pk_mul_f32 v[10:11], v[16:17], v[8:9] op_sel_hi:[1,0]
	v_pk_mul_f32 v[12:13], v[22:23], v[8:9] op_sel_hi:[1,0]
	v_bfe_u32 v9, v10, 16, 1
	v_bfe_u32 v16, v11, 16, 1
	v_bfe_u32 v17, v12, 16, 1
	v_bfe_u32 v18, v13, 16, 1
	v_add3_u32 v13, v13, v18, s60
	v_add3_u32 v12, v12, v17, s60
	v_add3_u32 v11, v11, v16, s60
	v_add3_u32 v9, v10, v9, s60
	v_lshrrev_b32_e32 v16, 16, v9
	v_lshrrev_b32_e32 v17, 16, v11
	v_lshrrev_b32_e32 v10, 16, v12
	v_lshrrev_b32_e32 v11, 16, v13
	v_pk_mul_f32 v[12:13], v[20:21], v[8:9] op_sel_hi:[1,0]
	v_pk_mul_f32 v[8:9], v[14:15], v[8:9] op_sel_hi:[1,0]
	v_lshlrev_b64 v[24:25], 11, v[90:91]
	v_and_or_b32 v11, v9, s56, v11
	v_and_or_b32 v10, v8, s56, v10
	v_and_or_b32 v9, v13, s56, v17
	v_and_or_b32 v8, v12, s56, v16
	global_store_dwordx4 v[52:53], v[8:11], off
	s_waitcnt lgkmcnt(0)
	s_barrier
	v_mov_b32_e32 v8, v65
	v_lshl_add_u64 v[24:25], s[54:55], 0, v[24:25]
	v_mbcnt_lo_u32_b32 v8, -1, v8
	v_mbcnt_hi_u32_b32 v10, -1, v8
	v_and_b32_e32 v20, 31, v10
	v_or_b32_e32 v8, v20, v136
	v_ashrrev_i32_e32 v9, 31, v8
	v_ashrrev_i32_e32 v10, 2, v10
	v_lshlrev_b64 v[8:9], 8, v[8:9]
	v_and_b32_e32 v12, -8, v10
	v_lshl_add_u64 v[8:9], s[54:55], 0, v[8:9]
	v_ashrrev_i32_e32 v13, 31, v12
	v_lshl_add_u64 v[14:15], v[12:13], 1, v[8:9]
	v_add_co_u32_e32 v8, vcc, s72, v14
	v_lshl_add_u64 v[166:167], v[14:15], 0, s[48:49]
	s_nop 0
	v_addc_co_u32_e32 v9, vcc, 0, v15, vcc
	v_add_co_u32_e32 v164, vcc, s73, v14
	global_load_dwordx4 v[8:11], v[8:9], off
	s_nop 0
	v_addc_co_u32_e32 v165, vcc, 0, v15, vcc
	global_load_dwordx4 v[16:19], v[164:165], off
	global_load_dwordx4 v[140:143], v[166:167], off offset:32
	global_load_dwordx4 v[144:147], v[164:165], off offset:32
	global_load_dwordx4 v[148:151], v[166:167], off offset:64
	global_load_dwordx4 v[98:101], v[166:167], off offset:96
	global_load_dwordx4 v[152:155], v[164:165], off offset:64
	global_load_dwordx4 v[102:105], v[164:165], off offset:96
	v_lshlrev_b32_e32 v0, 1, v12
	v_mad_u32_u24 v191, v20, s65, v0
	ds_read_b128 v[20:23], v191
	ds_read_b128 v[106:109], v191 offset:32
	v_lshrrev_b32_e32 v0, 3, v135
	v_and_b32_e32 v0, 4, v0
	v_mul_u32_u24_e32 v0, 0x410, v0
	v_lshl_add_u64 v[180:181], v[24:25], 0, v[34:35]
	v_lshlrev_b64 v[24:25], 11, v[92:93]
	v_lshl_add_u32 v192, v1, 2, v0
	v_mul_lo_u32 v0, v138, s70
	v_lshl_add_u64 v[24:25], s[54:55], 0, v[24:25]
	v_add_u32_e32 v118, v64, v0
	s_waitcnt vmcnt(0) lgkmcnt(0)
	v_mfma_f32_32x32x16_bf16 v[0:15], v[20:23], v[8:11], 0
	v_lshl_add_u64 v[182:183], v[24:25], 0, v[34:35]
	v_lshl_add_u64 v[34:35], v[110:111], 0, v[34:35]
	ds_read_b128 v[110:113], v191 offset:64
	v_mul_f32_e32 v138, v170, v61
	v_mfma_f32_32x32x16_bf16 v[16:31], v[20:23], v[16:19], 0
	v_mfma_f32_32x32x16_bf16 v[0:15], v[106:109], v[140:143], v[0:15]
	v_mul_f32_e32 v140, v176, v66
	v_mul_f32_e32 v141, v177, v63
	v_mul_f32_e32 v142, v178, v67
	v_mul_f32_e32 v143, v179, v68
	v_mfma_f32_32x32x16_bf16 v[16:31], v[106:109], v[144:147], v[16:31]
	ds_read_b128 v[106:109], v191 offset:96
	v_mul_f32_e32 v144, v184, v70
	v_mul_f32_e32 v145, v185, v69
	v_mul_f32_e32 v146, v186, v71
	v_mul_f32_e32 v147, v159, v72
	v_mul_f32_e32 v159, v187, v84
	s_waitcnt lgkmcnt(1)
	v_mfma_f32_32x32x16_bf16 v[0:15], v[110:113], v[148:151], v[0:15]
	v_mul_f32_e32 v148, v160, v74
	v_mul_f32_e32 v149, v161, v73
	v_mul_f32_e32 v150, v162, v75
	v_mul_f32_e32 v151, v171, v76
	v_mul_f32_e32 v160, v188, v86
	v_mul_f32_e32 v161, v189, v85
	v_mul_f32_e32 v162, v190, v87
	v_mfma_f32_32x32x16_bf16 v[16:31], v[110:113], v[152:155], v[16:31]
	v_mul_f32_e32 v152, v172, v78
	v_mul_f32_e32 v153, v173, v77
	v_mul_f32_e32 v154, v174, v79
	v_mul_f32_e32 v155, v114, v80
	s_waitcnt lgkmcnt(0)
	v_mfma_f32_32x32x16_bf16 v[0:15], v[106:109], v[98:101], v[0:15]
	v_mfma_f32_32x32x16_bf16 v[16:31], v[106:109], v[102:105], v[16:31]
	global_load_dwordx4 v[98:101], v[166:167], off offset:128
	global_load_dwordx4 v[102:105], v[164:165], off offset:128
	ds_read_b128 v[106:109], v191 offset:128
	ds_read_b128 v[114:117], v191 offset:160
	global_load_dwordx4 v[110:113], v[166:167], off offset:160
	s_waitcnt vmcnt(0) lgkmcnt(0)
	v_mfma_f32_32x32x16_bf16 v[0:15], v[106:109], v[98:101], v[0:15]
	global_load_dwordx4 v[98:101], v[164:165], off offset:160
	v_mfma_f32_32x32x16_bf16 v[16:31], v[106:109], v[102:105], v[16:31]
	global_load_dwordx4 v[102:105], v[166:167], off offset:192
	global_load_dwordx4 v[106:109], v[164:165], off offset:192
	v_mfma_f32_32x32x16_bf16 v[0:15], v[114:117], v[110:113], v[0:15]
	ds_read_b128 v[110:113], v191 offset:192
	s_waitcnt vmcnt(0) lgkmcnt(0)
	v_mfma_f32_32x32x16_bf16 v[16:31], v[114:117], v[98:101], v[16:31]
	global_load_dwordx4 v[98:101], v[166:167], off offset:224
	ds_read_b128 v[114:117], v191 offset:224
	v_mfma_f32_32x32x16_bf16 v[0:15], v[110:113], v[102:105], v[0:15]
	global_load_dwordx4 v[102:105], v[164:165], off offset:224
	v_mfma_f32_32x32x16_bf16 v[16:31], v[110:113], v[106:109], v[16:31]
	s_waitcnt vmcnt(0) lgkmcnt(0)
	v_mfma_f32_32x32x16_bf16 v[0:15], v[114:117], v[98:101], v[0:15]
	v_mfma_f32_32x32x16_bf16 v[16:31], v[114:117], v[102:105], v[16:31]
	v_add_u32_e32 v163, 0x6000, v192
	v_add_u32_e32 v164, 0x6400, v192
	v_add_u32_e32 v165, 0x6800, v192
	v_add_u32_e32 v166, 0x6c00, v192
	v_add_u32_e32 v167, 0x8000, v192
	v_add_u32_e32 v168, 0x8400, v192
	v_add_u32_e32 v169, 0x8800, v192
	v_add_u32_e32 v170, 0x8c00, v192
	v_add_u32_e32 v171, 0xa000, v192
	v_add_u32_e32 v172, 0xa400, v192
	v_add_u32_e32 v173, 0xa800, v192
	v_add_u32_e32 v174, 0xac00, v192
	v_add_u32_e32 v175, 0xc200, v192
	v_add_u32_e32 v176, 0xc600, v192
	v_add_u32_e32 v177, 0xca00, v192
	v_add_u32_e32 v178, 0xce00, v192
	ds_write2_b32 v163, v0, v16 offset0:128 offset1:160
	ds_write2_b32 v164, v1, v17 offset0:132 offset1:164
	ds_write2_b32 v165, v2, v18 offset0:136 offset1:168
	ds_write2_b32 v166, v3, v19 offset0:140 offset1:172
	ds_write2_b32 v167, v4, v20 offset0:160 offset1:192
	ds_write2_b32 v168, v5, v21 offset0:164 offset1:196
	ds_write2_b32 v169, v6, v22 offset0:168 offset1:200
	ds_write2_b32 v170, v7, v23 offset0:172 offset1:204
	ds_write2_b32 v171, v8, v24 offset0:192 offset1:224
	ds_write2_b32 v172, v9, v25 offset0:196 offset1:228
	ds_write2_b32 v173, v10, v26 offset0:200 offset1:232
	ds_write2_b32 v174, v11, v27 offset0:204 offset1:236
	ds_write2_b32 v175, v12, v28 offset0:96 offset1:128
	ds_write2_b32 v176, v13, v29 offset0:100 offset1:132
	ds_write2_b32 v177, v14, v30 offset0:104 offset1:136
	ds_write2_b32 v178, v15, v31 offset0:108 offset1:140
	s_waitcnt lgkmcnt(0)
	s_barrier
	ds_read_b128 v[0:3], v118 offset:25088
	ds_read_b128 v[4:7], v118 offset:25104
	s_add_u32 s79, s54, 0x1b0d7900
	s_addc_u32 s80, s55, 0
	s_add_u32 s81, s54, 0x1d4d7900
	s_waitcnt lgkmcnt(1)
	v_and_b32_sdwa v8, v2, v134 dst_sel:DWORD dst_unused:UNUSED_PAD src0_sel:WORD_1 src1_sel:DWORD
	v_and_b32_sdwa v9, v0, v134 dst_sel:DWORD dst_unused:UNUSED_PAD src0_sel:WORD_1 src1_sel:DWORD
	v_add3_u32 v2, v2, v8, s60
	v_and_b32_sdwa v8, v3, v134 dst_sel:DWORD dst_unused:UNUSED_PAD src0_sel:WORD_1 src1_sel:DWORD
	v_add3_u32 v0, v0, v9, s60
	v_and_b32_sdwa v9, v1, v134 dst_sel:DWORD dst_unused:UNUSED_PAD src0_sel:WORD_1 src1_sel:DWORD
	v_add3_u32 v3, v3, v8, s60
	v_add3_u32 v1, v1, v9, s60
	v_and_b32_e32 v3, 0xffff0000, v3
	v_and_b32_e32 v8, 0xffff0000, v1
	v_or_b32_sdwa v1, v3, v2 dst_sel:DWORD dst_unused:UNUSED_PAD src0_sel:DWORD src1_sel:WORD_1
	s_waitcnt lgkmcnt(0)
	v_and_b32_sdwa v2, v6, v134 dst_sel:DWORD dst_unused:UNUSED_PAD src0_sel:WORD_1 src1_sel:DWORD
	v_and_b32_sdwa v3, v4, v134 dst_sel:DWORD dst_unused:UNUSED_PAD src0_sel:WORD_1 src1_sel:DWORD
	v_add3_u32 v4, v4, v3, s60
	v_add3_u32 v2, v6, v2, s60
	v_and_b32_sdwa v3, v7, v134 dst_sel:DWORD dst_unused:UNUSED_PAD src0_sel:WORD_1 src1_sel:DWORD
	v_and_b32_sdwa v6, v5, v134 dst_sel:DWORD dst_unused:UNUSED_PAD src0_sel:WORD_1 src1_sel:DWORD
	v_add3_u32 v3, v7, v3, s60
	v_add3_u32 v5, v5, v6, s60
	v_and_b32_e32 v3, 0xffff0000, v3
	v_and_b32_e32 v5, 0xffff0000, v5
	v_or_b32_sdwa v3, v3, v2 dst_sel:DWORD dst_unused:UNUSED_PAD src0_sel:DWORD src1_sel:WORD_1
	v_or_b32_sdwa v2, v5, v4 dst_sel:DWORD dst_unused:UNUSED_PAD src0_sel:DWORD src1_sel:WORD_1
	v_add_co_u32_e32 v4, vcc, s75, v180
	v_or_b32_sdwa v0, v8, v0 dst_sel:DWORD dst_unused:UNUSED_PAD src0_sel:DWORD src1_sel:WORD_1
	s_nop 0
	v_addc_co_u32_e32 v5, vcc, 0, v181, vcc
	global_store_dwordx4 v[4:5], v[0:3], off offset:2816
	ds_read_b128 v[0:3], v118 offset:26128
	ds_read_b128 v[4:7], v118 offset:26144
	s_addc_u32 s82, s55, 0
	s_add_u32 s83, s54, 0x1738000
	s_addc_u32 s84, s55, 0
	s_waitcnt lgkmcnt(0)
	v_and_b32_sdwa v8, v2, v134 dst_sel:DWORD dst_unused:UNUSED_PAD src0_sel:WORD_1 src1_sel:DWORD
	v_and_b32_sdwa v9, v0, v134 dst_sel:DWORD dst_unused:UNUSED_PAD src0_sel:WORD_1 src1_sel:DWORD
	v_add3_u32 v2, v2, v8, s60
	v_and_b32_sdwa v8, v3, v134 dst_sel:DWORD dst_unused:UNUSED_PAD src0_sel:WORD_1 src1_sel:DWORD
	v_add3_u32 v0, v0, v9, s60
	v_and_b32_sdwa v9, v1, v134 dst_sel:DWORD dst_unused:UNUSED_PAD src0_sel:WORD_1 src1_sel:DWORD
	v_add3_u32 v3, v3, v8, s60
	v_add3_u32 v1, v1, v9, s60
	v_and_b32_e32 v3, 0xffff0000, v3
	v_and_b32_e32 v8, 0xffff0000, v1
	v_or_b32_sdwa v1, v3, v2 dst_sel:DWORD dst_unused:UNUSED_PAD src0_sel:DWORD src1_sel:WORD_1
	v_and_b32_sdwa v2, v6, v134 dst_sel:DWORD dst_unused:UNUSED_PAD src0_sel:WORD_1 src1_sel:DWORD
	v_and_b32_sdwa v3, v4, v134 dst_sel:DWORD dst_unused:UNUSED_PAD src0_sel:WORD_1 src1_sel:DWORD
	v_add3_u32 v4, v4, v3, s60
	v_add3_u32 v2, v6, v2, s60
	v_and_b32_sdwa v3, v7, v134 dst_sel:DWORD dst_unused:UNUSED_PAD src0_sel:WORD_1 src1_sel:DWORD
	v_and_b32_sdwa v6, v5, v134 dst_sel:DWORD dst_unused:UNUSED_PAD src0_sel:WORD_1 src1_sel:DWORD
	v_add3_u32 v3, v7, v3, s60
	v_add3_u32 v5, v5, v6, s60
	v_and_b32_e32 v3, 0xffff0000, v3
	v_and_b32_e32 v5, 0xffff0000, v5
	v_or_b32_sdwa v3, v3, v2 dst_sel:DWORD dst_unused:UNUSED_PAD src0_sel:DWORD src1_sel:WORD_1
	v_or_b32_sdwa v2, v5, v4 dst_sel:DWORD dst_unused:UNUSED_PAD src0_sel:DWORD src1_sel:WORD_1
	v_add_co_u32_e32 v4, vcc, s75, v182
	v_or_b32_sdwa v0, v8, v0 dst_sel:DWORD dst_unused:UNUSED_PAD src0_sel:DWORD src1_sel:WORD_1
	s_nop 0
	v_addc_co_u32_e32 v5, vcc, 0, v183, vcc
	global_store_dwordx4 v[4:5], v[0:3], off offset:2816
	ds_read_b128 v[0:3], v118 offset:27168
	ds_read_b128 v[4:7], v118 offset:27184
	v_lshl_add_u64 v[88:89], v[88:89], 0, s[50:51]
	s_mov_b64 s[8:9], -1
	s_waitcnt lgkmcnt(0)
	v_and_b32_sdwa v8, v2, v134 dst_sel:DWORD dst_unused:UNUSED_PAD src0_sel:WORD_1 src1_sel:DWORD
	v_and_b32_sdwa v9, v0, v134 dst_sel:DWORD dst_unused:UNUSED_PAD src0_sel:WORD_1 src1_sel:DWORD
	v_add3_u32 v2, v2, v8, s60
	v_and_b32_sdwa v8, v3, v134 dst_sel:DWORD dst_unused:UNUSED_PAD src0_sel:WORD_1 src1_sel:DWORD
	v_add3_u32 v0, v0, v9, s60
	v_and_b32_sdwa v9, v1, v134 dst_sel:DWORD dst_unused:UNUSED_PAD src0_sel:WORD_1 src1_sel:DWORD
	v_add3_u32 v3, v3, v8, s60
	v_add3_u32 v1, v1, v9, s60
	v_and_b32_e32 v3, 0xffff0000, v3
	v_and_b32_e32 v8, 0xffff0000, v1
	v_or_b32_sdwa v1, v3, v2 dst_sel:DWORD dst_unused:UNUSED_PAD src0_sel:DWORD src1_sel:WORD_1
	v_and_b32_sdwa v2, v6, v134 dst_sel:DWORD dst_unused:UNUSED_PAD src0_sel:WORD_1 src1_sel:DWORD
	v_and_b32_sdwa v3, v4, v134 dst_sel:DWORD dst_unused:UNUSED_PAD src0_sel:WORD_1 src1_sel:DWORD
	v_add3_u32 v4, v4, v3, s60
	v_add3_u32 v2, v6, v2, s60
	v_and_b32_sdwa v3, v7, v134 dst_sel:DWORD dst_unused:UNUSED_PAD src0_sel:WORD_1 src1_sel:DWORD
	v_and_b32_sdwa v6, v5, v134 dst_sel:DWORD dst_unused:UNUSED_PAD src0_sel:WORD_1 src1_sel:DWORD
	v_add3_u32 v3, v7, v3, s60
	v_add3_u32 v5, v5, v6, s60
	v_and_b32_e32 v3, 0xffff0000, v3
	v_and_b32_e32 v5, 0xffff0000, v5
	v_or_b32_sdwa v3, v3, v2 dst_sel:DWORD dst_unused:UNUSED_PAD src0_sel:DWORD src1_sel:WORD_1
	v_or_b32_sdwa v2, v5, v4 dst_sel:DWORD dst_unused:UNUSED_PAD src0_sel:DWORD src1_sel:WORD_1
	v_add_co_u32_e32 v4, vcc, s75, v36
	v_or_b32_sdwa v0, v8, v0 dst_sel:DWORD dst_unused:UNUSED_PAD src0_sel:DWORD src1_sel:WORD_1
	s_nop 0
	v_addc_co_u32_e32 v5, vcc, 0, v37, vcc
	global_store_dwordx4 v[4:5], v[0:3], off offset:2816
	ds_read_b128 v[0:3], v119 offset:25088
	ds_read_b128 v[4:7], v119 offset:25104
	s_waitcnt lgkmcnt(0)
	v_and_b32_sdwa v8, v2, v134 dst_sel:DWORD dst_unused:UNUSED_PAD src0_sel:WORD_1 src1_sel:DWORD
	v_and_b32_sdwa v9, v0, v134 dst_sel:DWORD dst_unused:UNUSED_PAD src0_sel:WORD_1 src1_sel:DWORD
	v_add3_u32 v2, v2, v8, s60
	v_and_b32_sdwa v8, v3, v134 dst_sel:DWORD dst_unused:UNUSED_PAD src0_sel:WORD_1 src1_sel:DWORD
	v_add3_u32 v0, v0, v9, s60
	v_and_b32_sdwa v9, v1, v134 dst_sel:DWORD dst_unused:UNUSED_PAD src0_sel:WORD_1 src1_sel:DWORD
	v_add3_u32 v3, v3, v8, s60
	v_add3_u32 v1, v1, v9, s60
	v_and_b32_e32 v3, 0xffff0000, v3
	v_and_b32_e32 v8, 0xffff0000, v1
	v_or_b32_sdwa v1, v3, v2 dst_sel:DWORD dst_unused:UNUSED_PAD src0_sel:DWORD src1_sel:WORD_1
	v_and_b32_sdwa v2, v6, v134 dst_sel:DWORD dst_unused:UNUSED_PAD src0_sel:WORD_1 src1_sel:DWORD
	v_and_b32_sdwa v3, v4, v134 dst_sel:DWORD dst_unused:UNUSED_PAD src0_sel:WORD_1 src1_sel:DWORD
	v_add3_u32 v4, v4, v3, s60
	v_add3_u32 v2, v6, v2, s60
	v_and_b32_sdwa v3, v7, v134 dst_sel:DWORD dst_unused:UNUSED_PAD src0_sel:WORD_1 src1_sel:DWORD
	v_and_b32_sdwa v6, v5, v134 dst_sel:DWORD dst_unused:UNUSED_PAD src0_sel:WORD_1 src1_sel:DWORD
	v_add3_u32 v3, v7, v3, s60
	v_add3_u32 v5, v5, v6, s60
	v_and_b32_e32 v3, 0xffff0000, v3
	v_and_b32_e32 v5, 0xffff0000, v5
	v_or_b32_sdwa v3, v3, v2 dst_sel:DWORD dst_unused:UNUSED_PAD src0_sel:DWORD src1_sel:WORD_1
	v_or_b32_sdwa v2, v5, v4 dst_sel:DWORD dst_unused:UNUSED_PAD src0_sel:DWORD src1_sel:WORD_1
	v_add_co_u32_e32 v4, vcc, s75, v34
	v_or_b32_sdwa v0, v8, v0 dst_sel:DWORD dst_unused:UNUSED_PAD src0_sel:DWORD src1_sel:WORD_1
	s_nop 0
	v_addc_co_u32_e32 v5, vcc, 0, v35, vcc
	global_store_dwordx4 v[4:5], v[0:3], off offset:2816
	s_waitcnt lgkmcnt(0)
	s_barrier
	global_load_dwordx2 v[0:1], v[32:33], off offset:456
	v_and_b32_e32 v8, 7, v135
	v_lshlrev_b64 v[2:3], 8, v[92:93]
	v_lshlrev_b64 v[4:5], 8, v[94:95]
	v_lshlrev_b64 v[6:7], 8, v[96:97]
	v_cmp_eq_u32_e64 s[4:5], 0, v8
	v_or_b32_e32 v2, v2, v126
	v_or_b32_e32 v4, v4, v126
	v_or_b32_e32 v6, v6, v126
	v_lshlrev_b64 v[92:93], 4, v[92:93]
	v_lshlrev_b64 v[94:95], 4, v[94:95]
	v_lshlrev_b64 v[96:97], 4, v[96:97]
	v_lshlrev_b64 v[104:105], 1, v[2:3]
	v_lshlrev_b64 v[106:107], 1, v[4:5]
	v_lshlrev_b64 v[108:109], 1, v[6:7]
	s_waitcnt vmcnt(0) lgkmcnt(0)
	v_readfirstlane_b32 s1, v1
	v_readfirstlane_b32 s0, v0
	s_nop 1
	v_lshl_add_u64 v[0:1], s[0:1], 0, v[64:65]
	global_load_dwordx4 v[30:33], v[0:1], off offset:1024
	global_load_dwordx4 v[34:37], v[0:1], off offset:1040
	s_add_u32 s0, s54, 0x2954198
	s_addc_u32 s1, s55, 0
	s_add_u32 s85, s54, 0x1748000
	v_lshlrev_b64 v[0:1], 8, v[90:91]
	s_addc_u32 s86, s55, 0
	v_bfe_u32 v64, v135, 1, 4
	v_or_b32_e32 v0, v0, v126
	s_add_u32 s6, s54, 0x29541a8
	v_lshl_add_u64 v[8:9], s[54:55], 0, v[64:65]
	v_lshlrev_b64 v[90:91], 4, v[90:91]
	s_addc_u32 s7, s55, 0
	v_lshl_add_u64 v[98:99], v[8:9], 0, s[52:53]
	v_lshlrev_b32_e32 v64, 2, v126
	s_waitcnt vmcnt(0) lgkmcnt(0)
	v_mov_b32_e32 v100, v30
	v_mov_b32_e32 v101, v32
	v_mov_b32_e32 v32, v31
	v_mov_b32_e32 v102, v34
	v_mov_b32_e32 v103, v36
	v_mov_b32_e32 v36, v35
	v_lshlrev_b64 v[34:35], 1, v[0:1]
	s_branch .LBB0_1409
